# load segments: the closing s_waitcnt vmcnt(8) and s_waitcnt lgkmcnt(0) merged into one s_waitcnt (32 sites, same condition, one issue slot fewer before the barrier); on top of v64
# speedup vs baseline: 1.0035x; 1.0035x over previous
;     __host__ __device__ __forceinline__ bool next(int i, Unit& u) const { const int vv = vid + (i / 5) * G; if (vv >= 256) return false; u.pm = vv >> 2; u.pn = (vv & 3) + 4 * (i % 5); return true; }
; #define PG8_STAGE(bufoff, gbase, voff) do { _Pragma("unroll") for (int _i = 0; _i < 2; ++_i) \
;         __builtin_amdgcn_global_load_lds((const unsigned*)((const char*)(gbase) + (voff)[_i]), (PG8_LAS unsigned*)(lds + (bufoff) + ldsw + _i * 8192), 16, 0, 0); } while (0)
; #define PG8_LDA(dst, b, h) do { _Pragma("unroll") for (int m = 0; m < 4; ++m) _Pragma("unroll") for (int k = 0; k < 2; ++k) dst[m][k] = *(const PG8_LAS bf16x8*)(lds + PG8_SA(b, h) + aoff + m * 2048 + k * 1024); } while (0)
; #define PG8_LDB(dst, b, h) do { _Pragma("unroll") for (int n = 0; n < 2; ++n) _Pragma("unroll") for (int k = 0; k < 2; ++k) dst[n][k] = *(const PG8_LAS bf16x8*)(lds + PG8_SB(b, h) + boff + n * 2048 + k * 1024); } while (0)
; #define PG8_WAIT_V(n) asm volatile("s_waitcnt vmcnt(" #n ")" ::: "memory")
;     ...
;         const bool has_next = S.next(ui + 1, nxt);
;         const char* nA = has_next ? (const char*)g.A + (size_t)nxt.pm * tstepA + (size_t)nxt.pn * APN + kofA : cA; const char* nB = has_next ? (const char*)g.Bt + (size_t)nxt.pn * tstepB + S.b_off(nxt) + kofB : cB;
;         for (int t = 0; t < nt; t += 2) {
;             const bool last = (t == nt - 2);
;             const char* a1 = cA + (ptrdiff_t)(t + 1) * kstepA;
;             const char* a2 = last ? nA : cA + (ptrdiff_t)(t + 2) * kstepA; const char* b2 = last ? nB : cB + (ptrdiff_t)(t + 2) * kstep;
;             const char* a3 = a2 + kstepA; const char* b3 = b2 + kstep;
;             if (last && has_next) S.a_ready(nxt);
;             if constexpr (SP2) {
;             PG8_LDB(B0, 0, 0); PG8_LDB(B1, 0, 1); PG8_SCHED; PG8_LDA(At, 0, 0); PG8_STAGE(PG8_SA(1, 1), a1 + hstepA, voffA);
;             PG8_WAIT_V(8); PG8_WAIT_L(0); PG8_BAR; PG8_MMA(0, 0, At, B0); PG8_MMA(0, 1, At, B1); PG8_BAR; PG8_SCHED;
;             PG8_LDA(At, 0, 1); PG8_STAGE(PG8_SB(0, 0), b2, voffB); PG8_STAGE(PG8_SB(0, 1), b2 + hstepB, voffB); PG8_STAGE(PG8_SA(0, 0), a2, voffA);
;             PG8_WAIT_V(8); PG8_WAIT_L(0); PG8_BAR; PG8_MMA(1, 0, At, B0); PG8_MMA(1, 1, At, B1); PG8_BAR; PG8_SCHED;
;     __device__ __forceinline__ size_t b_off(const pg8::Unit& u) const { return (size_t)(u.pm >> 3) * 4 * 131072; }
.LBB0_97:
	s_mov_b64 s[30:31], s[6:7]
	s_ashr_i32 s6, s14, 2
	s_and_b32 s6, s6, -8
	s_and_b32 s7, s14, 7
	s_mov_b32 s20, s58
	s_mov_b32 s21, s57
	v_cmp_lt_i64_e64 s[4:5], s[14:15], v[138:139]
	s_bfe_u32 s57, s14, 0x20003
	s_or_b32 s58, s6, s7
	s_and_b64 s[6:7], s[4:5], exec
	s_cselect_b32 s24, s58, s20
	s_cselect_b32 s6, s57, s21
	s_ashr_i32 s25, s24, 31
	s_lshl_b64 s[20:21], s[24:25], 20
	s_add_u32 s20, s2, s20
	s_addc_u32 s21, s3, s21
	s_ashr_i32 s7, s6, 31
	s_lshl_b64 s[6:7], s[6:7], 17
	s_add_u32 s20, s20, s6
	s_addc_u32 s21, s21, s7
	s_and_b64 s[28:29], s[4:5], exec
	ds_read_b128 v[0:3], v141
	ds_read_b128 v[4:7], v141 offset:1024
	ds_read_b128 v[8:11], v141 offset:2048
	ds_read_b128 v[12:15], v141 offset:3072
	ds_read_b128 v[16:19], v142
	ds_read_b128 v[20:23], v142 offset:1024
	ds_read_b128 v[24:27], v142 offset:2048
	ds_read_b128 v[28:31], v142 offset:3072
	s_cselect_b32 s29, s21, s27
	s_cselect_b32 s28, s20, s26
	s_add_u32 s25, s33, s6
	s_addc_u32 s34, s36, s7
	s_ashr_i32 s6, s24, 3
	s_ashr_i32 s7, s6, 31
	s_lshl_b64 s[6:7], s[6:7], 19
	s_add_u32 s6, s25, s6
	s_addc_u32 s7, s34, s7
	s_and_b64 s[24:25], s[4:5], exec
	s_cselect_b32 s25, s7, s31
	s_cselect_b32 s24, s6, s30
	s_add_u32 s60, s26, 0x10000
	s_addc_u32 s61, s27, 0
	s_add_u32 s34, s26, 0x18000
	s_addc_u32 s35, s27, 0
	s_add_u32 s62, s26, 0xc000
	s_addc_u32 s63, s27, 0
	s_mov_b32 m0, s46
	ds_read_b128 v[32:35], v143
	ds_read_b128 v[36:39], v143 offset:1024
	ds_read_b128 v[40:43], v143 offset:2048
	ds_read_b128 v[44:47], v143 offset:3072
	ds_read_b128 v[48:51], v143 offset:4096
	ds_read_b128 v[52:55], v143 offset:5120
	ds_read_b128 v[56:59], v143 offset:6144
	ds_read_b128 v[60:63], v143 offset:7168
	global_load_lds_dwordx4 v134, s[62:63]
	v_lshl_add_u64 v[64:65], s[62:63], 0, v[130:131]
	s_mov_b32 m0, s47
	s_nop 0
	global_load_lds_dwordx4 v[64:65], off
	s_waitcnt vmcnt(8) lgkmcnt(0)
	s_barrier
	s_setprio 1
	v_mfma_f32_16x16x32_bf16 v[64:67], v[0:3], v[32:35], 0
	v_mfma_f32_16x16x32_bf16 v[64:67], v[4:7], v[36:39], v[64:67]
	v_mfma_f32_16x16x32_bf16 v[68:71], v[8:11], v[32:35], 0
	v_mfma_f32_16x16x32_bf16 v[68:71], v[12:15], v[36:39], v[68:71]
	v_mfma_f32_16x16x32_bf16 v[72:75], v[0:3], v[40:43], 0
	v_mfma_f32_16x16x32_bf16 v[72:75], v[4:7], v[44:47], v[72:75]
	v_mfma_f32_16x16x32_bf16 v[76:79], v[8:11], v[40:43], 0
	v_mfma_f32_16x16x32_bf16 v[76:79], v[12:15], v[44:47], v[76:79]
	v_mfma_f32_16x16x32_bf16 v[80:83], v[0:3], v[48:51], 0
	v_mfma_f32_16x16x32_bf16 v[80:83], v[4:7], v[52:55], v[80:83]
	v_mfma_f32_16x16x32_bf16 v[84:87], v[8:11], v[48:51], 0
	v_mfma_f32_16x16x32_bf16 v[84:87], v[12:15], v[52:55], v[84:87]
	v_mfma_f32_16x16x32_bf16 v[88:91], v[0:3], v[56:59], 0
	v_mfma_f32_16x16x32_bf16 v[88:91], v[4:7], v[60:63], v[88:91]
	v_mfma_f32_16x16x32_bf16 v[92:95], v[8:11], v[56:59], 0
	v_mfma_f32_16x16x32_bf16 v[92:95], v[12:15], v[60:63], v[92:95]
	s_setprio 0
	s_setprio 1
	v_mfma_f32_16x16x32_bf16 v[96:99], v[16:19], v[32:35], 0
	v_mfma_f32_16x16x32_bf16 v[96:99], v[20:23], v[36:39], v[96:99]
	v_mfma_f32_16x16x32_bf16 v[32:35], v[24:27], v[32:35], 0
	v_mfma_f32_16x16x32_bf16 v[32:35], v[28:31], v[36:39], v[32:35]
	v_mfma_f32_16x16x32_bf16 v[36:39], v[16:19], v[40:43], 0
	v_mfma_f32_16x16x32_bf16 v[36:39], v[20:23], v[44:47], v[36:39]
	v_mfma_f32_16x16x32_bf16 v[40:43], v[24:27], v[40:43], 0
	v_mfma_f32_16x16x32_bf16 v[40:43], v[28:31], v[44:47], v[40:43]
	v_mfma_f32_16x16x32_bf16 v[44:47], v[16:19], v[48:51], 0
	v_mfma_f32_16x16x32_bf16 v[44:47], v[20:23], v[52:55], v[44:47]
	v_mfma_f32_16x16x32_bf16 v[48:51], v[24:27], v[48:51], 0
	v_mfma_f32_16x16x32_bf16 v[48:51], v[28:31], v[52:55], v[48:51]
	v_mfma_f32_16x16x32_bf16 v[52:55], v[16:19], v[56:59], 0
	v_mfma_f32_16x16x32_bf16 v[52:55], v[20:23], v[60:63], v[52:55]
	v_mfma_f32_16x16x32_bf16 v[56:59], v[24:27], v[56:59], 0
	v_mfma_f32_16x16x32_bf16 v[56:59], v[28:31], v[60:63], v[56:59]
	s_setprio 0
	s_barrier
	v_lshl_add_u64 v[210:211], s[30:31], 0, v[132:133]
	s_mov_b32 m0, s48
	v_lshl_add_u64 v[146:147], v[210:211], 0, s[16:17]
	v_lshl_add_u64 v[212:213], s[30:31], 0, v[128:129]
	s_add_u32 s62, s30, 0x10100
	ds_read_b128 v[60:63], v143 offset:16384
	ds_read_b128 v[100:103], v143 offset:17408
	ds_read_b128 v[104:107], v143 offset:18432
	ds_read_b128 v[108:111], v143 offset:19456
	ds_read_b128 v[112:115], v143 offset:20480
	ds_read_b128 v[116:119], v143 offset:21504
	ds_read_b128 v[120:123], v143 offset:22528
	ds_read_b128 v[124:127], v143 offset:23552
	global_load_lds_dwordx4 v[146:147], off
	v_lshl_add_u64 v[146:147], v[212:213], 0, s[16:17]
	s_mov_b32 m0, s50
	s_addc_u32 s63, s31, 0
	global_load_lds_dwordx4 v[146:147], off
	s_mov_b32 m0, s51
	s_nop 0
	global_load_lds_dwordx4 v132, s[62:63]
	s_mov_b32 m0, s52
	s_nop 0
	global_load_lds_dwordx4 v128, s[62:63]
	s_mov_b32 m0, s23
	s_nop 0
	global_load_lds_dwordx4 v134, s[60:61]
	v_lshl_add_u64 v[146:147], s[60:61], 0, v[130:131]
	s_mov_b32 m0, s37
	s_nop 0
	global_load_lds_dwordx4 v[146:147], off
	s_waitcnt vmcnt(8) lgkmcnt(0)
	s_barrier
; #define PG8_STAGE(bufoff, gbase, voff) do { _Pragma("unroll") for (int _i = 0; _i < 2; ++_i) \
;         __builtin_amdgcn_global_load_lds((const unsigned*)((const char*)(gbase) + (voff)[_i]), (PG8_LAS unsigned*)(lds + (bufoff) + ldsw + _i * 8192), 16, 0, 0); } while (0)
; #define PG8_LDA(dst, b, h) do { _Pragma("unroll") for (int m = 0; m < 4; ++m) _Pragma("unroll") for (int k = 0; k < 2; ++k) dst[m][k] = *(const PG8_LAS bf16x8*)(lds + PG8_SA(b, h) + aoff + m * 2048 + k * 1024); } while (0)
; #define PG8_LDB(dst, b, h) do { _Pragma("unroll") for (int n = 0; n < 2; ++n) _Pragma("unroll") for (int k = 0; k < 2; ++k) dst[n][k] = *(const PG8_LAS bf16x8*)(lds + PG8_SB(b, h) + boff + n * 2048 + k * 1024); } while (0)
; #define PG8_MMA(ai, bj, At, Bt) do { __builtin_amdgcn_s_setprio(1); _Pragma("unroll") for (int m = 0; m < 4; ++m) _Pragma("unroll") for (int n = 0; n < 2; ++n) _Pragma("unroll") for (int k = 0; k < 2; ++k) \
;         acc[ai][bj][m][n] = __builtin_amdgcn_mfma_f32_16x16x32_bf16(Bt[n][k], At[m][k], acc[ai][bj][m][n], 0, 0, 0); __builtin_amdgcn_s_setprio(0); } while (0)
; #define PG8_WAIT_V(n) asm volatile("s_waitcnt vmcnt(" #n ")" ::: "memory")
; #define PG8_WAIT_L(n) asm volatile("s_waitcnt lgkmcnt(" #n ")" ::: "memory")
; #define PG8_BAR __builtin_amdgcn_s_barrier()
; #define PG8_SCHED __builtin_amdgcn_sched_barrier(0)
;     ...
;             PG8_WAIT_V(8); PG8_WAIT_L(0); PG8_BAR; PG8_MMA(0, 0, At, B0); PG8_MMA(0, 1, At, B1); PG8_BAR; PG8_SCHED;
;             PG8_LDA(At, 0, 1); PG8_STAGE(PG8_SB(0, 0), b2, voffB); PG8_STAGE(PG8_SB(0, 1), b2 + hstepB, voffB); PG8_STAGE(PG8_SA(0, 0), a2, voffA);
;             PG8_WAIT_V(8); PG8_WAIT_L(0); PG8_BAR; PG8_MMA(1, 0, At, B0); PG8_MMA(1, 1, At, B1); PG8_BAR; PG8_SCHED;
;             PG8_LDB(B0, 1, 0); PG8_LDB(B1, 1, 1); PG8_SCHED; PG8_LDA(At, 1, 0); PG8_STAGE(PG8_SA(0, 1), a2 + hstepA, voffA);
;             PG8_WAIT_V(8); PG8_WAIT_L(0); PG8_BAR; PG8_MMA(0, 0, At, B0); PG8_MMA(0, 1, At, B1); PG8_BAR; PG8_SCHED;
	s_setprio 1
	v_mfma_f32_16x16x32_bf16 v[146:149], v[0:3], v[60:63], 0
	v_mfma_f32_16x16x32_bf16 v[146:149], v[4:7], v[100:103], v[146:149]
	v_mfma_f32_16x16x32_bf16 v[154:157], v[0:3], v[104:107], 0
	v_mfma_f32_16x16x32_bf16 v[154:157], v[4:7], v[108:111], v[154:157]
	v_mfma_f32_16x16x32_bf16 v[162:165], v[0:3], v[112:115], 0
	v_mfma_f32_16x16x32_bf16 v[162:165], v[4:7], v[116:119], v[162:165]
	v_mfma_f32_16x16x32_bf16 v[0:3], v[0:3], v[120:123], 0
	v_mfma_f32_16x16x32_bf16 v[0:3], v[4:7], v[124:127], v[0:3]
	v_mfma_f32_16x16x32_bf16 v[4:7], v[8:11], v[120:123], 0
	v_mfma_f32_16x16x32_bf16 v[4:7], v[12:15], v[124:127], v[4:7]
	v_mfma_f32_16x16x32_bf16 v[150:153], v[8:11], v[60:63], 0
	v_mfma_f32_16x16x32_bf16 v[150:153], v[12:15], v[100:103], v[150:153]
	v_mfma_f32_16x16x32_bf16 v[158:161], v[8:11], v[104:107], 0
	v_mfma_f32_16x16x32_bf16 v[158:161], v[12:15], v[108:111], v[158:161]
	v_mfma_f32_16x16x32_bf16 v[166:169], v[8:11], v[112:115], 0
	v_mfma_f32_16x16x32_bf16 v[166:169], v[12:15], v[116:119], v[166:169]
	s_setprio 0
	s_setprio 1
	v_mfma_f32_16x16x32_bf16 v[8:11], v[16:19], v[60:63], 0
	v_mfma_f32_16x16x32_bf16 v[8:11], v[20:23], v[100:103], v[8:11]
	v_mfma_f32_16x16x32_bf16 v[12:15], v[24:27], v[60:63], 0
	v_mfma_f32_16x16x32_bf16 v[12:15], v[28:31], v[100:103], v[12:15]
	v_mfma_f32_16x16x32_bf16 v[60:63], v[16:19], v[104:107], 0
	v_mfma_f32_16x16x32_bf16 v[60:63], v[20:23], v[108:111], v[60:63]
	v_mfma_f32_16x16x32_bf16 v[100:103], v[24:27], v[104:107], 0
	v_mfma_f32_16x16x32_bf16 v[100:103], v[28:31], v[108:111], v[100:103]
	v_mfma_f32_16x16x32_bf16 v[104:107], v[16:19], v[112:115], 0
	v_mfma_f32_16x16x32_bf16 v[104:107], v[20:23], v[116:119], v[104:107]
	v_mfma_f32_16x16x32_bf16 v[16:19], v[16:19], v[120:123], 0
	v_mfma_f32_16x16x32_bf16 v[16:19], v[20:23], v[124:127], v[16:19]
	v_mfma_f32_16x16x32_bf16 v[108:111], v[24:27], v[112:115], 0
	v_mfma_f32_16x16x32_bf16 v[108:111], v[28:31], v[116:119], v[108:111]
	v_mfma_f32_16x16x32_bf16 v[20:23], v[24:27], v[120:123], 0
	v_mfma_f32_16x16x32_bf16 v[20:23], v[28:31], v[124:127], v[20:23]
	s_setprio 0
	s_barrier
	ds_read_b128 v[24:27], v144
	ds_read_b128 v[28:31], v144 offset:1024
	ds_read_b128 v[112:115], v144 offset:2048
	ds_read_b128 v[116:119], v144 offset:3072
	ds_read_b128 v[120:123], v145
	ds_read_b128 v[124:127], v145 offset:1024
	ds_read_b128 v[170:173], v145 offset:2048
	ds_read_b128 v[174:177], v145 offset:3072
	s_add_u32 s60, s26, 0x14000
	s_addc_u32 s61, s27, 0
	s_mov_b32 m0, s39
	ds_read_b128 v[178:181], v143 offset:32768
	ds_read_b128 v[182:185], v143 offset:33792
	ds_read_b128 v[186:189], v143 offset:34816
	ds_read_b128 v[190:193], v143 offset:35840
	ds_read_b128 v[194:197], v143 offset:36864
	ds_read_b128 v[198:201], v143 offset:37888
	ds_read_b128 v[202:205], v143 offset:38912
	ds_read_b128 v[206:209], v143 offset:39936
	global_load_lds_dwordx4 v134, s[60:61]
	v_lshl_add_u64 v[214:215], s[60:61], 0, v[130:131]
	s_mov_b32 m0, s40
	s_nop 0
	global_load_lds_dwordx4 v[214:215], off
	s_waitcnt vmcnt(8) lgkmcnt(0)
	s_barrier
	s_setprio 1
	v_mfma_f32_16x16x32_bf16 v[64:67], v[24:27], v[178:181], v[64:67]
	v_mfma_f32_16x16x32_bf16 v[64:67], v[28:31], v[182:185], v[64:67]
	v_mfma_f32_16x16x32_bf16 v[68:71], v[116:119], v[182:185], v[68:71]
	v_mfma_f32_16x16x32_bf16 v[68:71], v[112:115], v[178:181], v[68:71]
	v_mfma_f32_16x16x32_bf16 v[76:79], v[112:115], v[186:189], v[76:79]
	v_mfma_f32_16x16x32_bf16 v[76:79], v[116:119], v[190:193], v[76:79]
	v_mfma_f32_16x16x32_bf16 v[72:75], v[28:31], v[190:193], v[72:75]
	v_mfma_f32_16x16x32_bf16 v[72:75], v[24:27], v[186:189], v[72:75]
	v_mfma_f32_16x16x32_bf16 v[80:83], v[24:27], v[194:197], v[80:83]
	v_mfma_f32_16x16x32_bf16 v[80:83], v[28:31], v[198:201], v[80:83]
	v_mfma_f32_16x16x32_bf16 v[84:87], v[116:119], v[198:201], v[84:87]
	v_mfma_f32_16x16x32_bf16 v[84:87], v[112:115], v[194:197], v[84:87]
	v_mfma_f32_16x16x32_bf16 v[92:95], v[112:115], v[202:205], v[92:95]
	v_mfma_f32_16x16x32_bf16 v[92:95], v[116:119], v[206:209], v[92:95]
	v_mfma_f32_16x16x32_bf16 v[88:91], v[28:31], v[206:209], v[88:91]
	v_mfma_f32_16x16x32_bf16 v[88:91], v[24:27], v[202:205], v[88:91]
	s_setprio 0
	s_setprio 1
	v_mfma_f32_16x16x32_bf16 v[96:99], v[120:123], v[178:181], v[96:99]
	v_mfma_f32_16x16x32_bf16 v[96:99], v[124:127], v[182:185], v[96:99]
	v_mfma_f32_16x16x32_bf16 v[32:35], v[174:177], v[182:185], v[32:35]
	v_mfma_f32_16x16x32_bf16 v[32:35], v[170:173], v[178:181], v[32:35]
	v_mfma_f32_16x16x32_bf16 v[40:43], v[170:173], v[186:189], v[40:43]
	v_mfma_f32_16x16x32_bf16 v[40:43], v[174:177], v[190:193], v[40:43]
	v_mfma_f32_16x16x32_bf16 v[36:39], v[124:127], v[190:193], v[36:39]
	v_mfma_f32_16x16x32_bf16 v[36:39], v[120:123], v[186:189], v[36:39]
	v_mfma_f32_16x16x32_bf16 v[44:47], v[120:123], v[194:197], v[44:47]
	v_mfma_f32_16x16x32_bf16 v[44:47], v[124:127], v[198:201], v[44:47]
	v_mfma_f32_16x16x32_bf16 v[48:51], v[174:177], v[198:201], v[48:51]
	v_mfma_f32_16x16x32_bf16 v[48:51], v[170:173], v[194:197], v[48:51]
	v_mfma_f32_16x16x32_bf16 v[56:59], v[170:173], v[202:205], v[56:59]
	v_mfma_f32_16x16x32_bf16 v[56:59], v[174:177], v[206:209], v[56:59]
	v_mfma_f32_16x16x32_bf16 v[52:55], v[124:127], v[206:209], v[52:55]
	v_mfma_f32_16x16x32_bf16 v[52:55], v[120:123], v[202:205], v[52:55]
	s_setprio 0
	s_barrier
; #define PG8_STAGE(bufoff, gbase, voff) do { _Pragma("unroll") for (int _i = 0; _i < 2; ++_i) \
;         __builtin_amdgcn_global_load_lds((const unsigned*)((const char*)(gbase) + (voff)[_i]), (PG8_LAS unsigned*)(lds + (bufoff) + ldsw + _i * 8192), 16, 0, 0); } while (0)
; #define PG8_LDA(dst, b, h) do { _Pragma("unroll") for (int m = 0; m < 4; ++m) _Pragma("unroll") for (int k = 0; k < 2; ++k) dst[m][k] = *(const PG8_LAS bf16x8*)(lds + PG8_SA(b, h) + aoff + m * 2048 + k * 1024); } while (0)
; #define PG8_LDB(dst, b, h) do { _Pragma("unroll") for (int n = 0; n < 2; ++n) _Pragma("unroll") for (int k = 0; k < 2; ++k) dst[n][k] = *(const PG8_LAS bf16x8*)(lds + PG8_SB(b, h) + boff + n * 2048 + k * 1024); } while (0)
; #define PG8_MMA(ai, bj, At, Bt) do { __builtin_amdgcn_s_setprio(1); _Pragma("unroll") for (int m = 0; m < 4; ++m) _Pragma("unroll") for (int n = 0; n < 2; ++n) _Pragma("unroll") for (int k = 0; k < 2; ++k) \
;         acc[ai][bj][m][n] = __builtin_amdgcn_mfma_f32_16x16x32_bf16(Bt[n][k], At[m][k], acc[ai][bj][m][n], 0, 0, 0); __builtin_amdgcn_s_setprio(0); } while (0)
; #define PG8_WAIT_V(n) asm volatile("s_waitcnt vmcnt(" #n ")" ::: "memory")
; #define PG8_WAIT_L(n) asm volatile("s_waitcnt lgkmcnt(" #n ")" ::: "memory")
; #define PG8_BAR __builtin_amdgcn_s_barrier()
; #define PG8_SCHED __builtin_amdgcn_sched_barrier(0)
;     ...
;             PG8_LDB(B0, 0, 0); PG8_LDB(B1, 0, 1); PG8_SCHED; PG8_LDA(At, 0, 0); PG8_STAGE(PG8_SA(1, 1), a1 + hstepA, voffA);
;             PG8_WAIT_V(8); PG8_WAIT_L(0); PG8_BAR; PG8_MMA(0, 0, At, B0); PG8_MMA(0, 1, At, B1); PG8_BAR; PG8_SCHED;
;     ...
;             PG8_LDA(At, 1, 1); PG8_STAGE(PG8_SB(1, 0), b3, voffB); PG8_STAGE(PG8_SB(1, 1), b3 + hstepB, voffB); PG8_STAGE(PG8_SA(1, 0), a3, voffA);
;             PG8_WAIT_V(8); PG8_WAIT_L(0); PG8_BAR; PG8_MMA(1, 0, At, B0); PG8_MMA(1, 1, At, B1); PG8_BAR; PG8_SCHED;
	s_mov_b32 m0, s53
	v_lshl_add_u64 v[210:211], v[210:211], 0, s[18:19]
	s_add_u32 s30, s30, 0x10180
	ds_read_b128 v[178:181], v143 offset:49152
	ds_read_b128 v[182:185], v143 offset:50176
	ds_read_b128 v[186:189], v143 offset:51200
	ds_read_b128 v[190:193], v143 offset:52224
	ds_read_b128 v[194:197], v143 offset:53248
	ds_read_b128 v[198:201], v143 offset:54272
	ds_read_b128 v[202:205], v143 offset:55296
	ds_read_b128 v[206:209], v143 offset:56320
	global_load_lds_dwordx4 v[210:211], off
	v_lshl_add_u64 v[210:211], v[212:213], 0, s[18:19]
	s_mov_b32 m0, s54
	s_addc_u32 s31, s31, 0
	global_load_lds_dwordx4 v[210:211], off
	s_mov_b32 m0, s55
	s_nop 0
	global_load_lds_dwordx4 v132, s[30:31]
	s_mov_b32 m0, s56
	s_nop 0
	global_load_lds_dwordx4 v128, s[30:31]
	s_mov_b32 m0, s42
	s_nop 0
	global_load_lds_dwordx4 v134, s[34:35]
	s_mov_b32 m0, s43
	s_nop 0
	global_load_lds_dwordx4 v130, s[34:35]
	s_waitcnt vmcnt(8) lgkmcnt(0)
	s_barrier
	s_setprio 1
	v_mfma_f32_16x16x32_bf16 v[0:3], v[24:27], v[202:205], v[0:3]
	v_mfma_f32_16x16x32_bf16 v[0:3], v[28:31], v[206:209], v[0:3]
	v_mfma_f32_16x16x32_bf16 v[4:7], v[116:119], v[206:209], v[4:7]
	v_mfma_f32_16x16x32_bf16 v[4:7], v[112:115], v[202:205], v[4:7]
	v_mfma_f32_16x16x32_bf16 v[150:153], v[112:115], v[178:181], v[150:153]
	v_mfma_f32_16x16x32_bf16 v[150:153], v[116:119], v[182:185], v[150:153]
	v_mfma_f32_16x16x32_bf16 v[146:149], v[28:31], v[182:185], v[146:149]
	v_mfma_f32_16x16x32_bf16 v[146:149], v[24:27], v[178:181], v[146:149]
	v_mfma_f32_16x16x32_bf16 v[154:157], v[24:27], v[186:189], v[154:157]
	v_mfma_f32_16x16x32_bf16 v[154:157], v[28:31], v[190:193], v[154:157]
	v_mfma_f32_16x16x32_bf16 v[158:161], v[116:119], v[190:193], v[158:161]
	v_mfma_f32_16x16x32_bf16 v[158:161], v[112:115], v[186:189], v[158:161]
	v_mfma_f32_16x16x32_bf16 v[166:169], v[112:115], v[194:197], v[166:169]
	v_mfma_f32_16x16x32_bf16 v[166:169], v[116:119], v[198:201], v[166:169]
	v_mfma_f32_16x16x32_bf16 v[162:165], v[28:31], v[198:201], v[162:165]
	v_mfma_f32_16x16x32_bf16 v[162:165], v[24:27], v[194:197], v[162:165]
	s_setprio 0
	s_setprio 1
	v_mfma_f32_16x16x32_bf16 v[8:11], v[120:123], v[178:181], v[8:11]
	v_mfma_f32_16x16x32_bf16 v[8:11], v[124:127], v[182:185], v[8:11]
	v_mfma_f32_16x16x32_bf16 v[12:15], v[170:173], v[178:181], v[12:15]
	v_mfma_f32_16x16x32_bf16 v[12:15], v[174:177], v[182:185], v[12:15]
	v_mfma_f32_16x16x32_bf16 v[24:27], v[120:123], v[186:189], v[60:63]
	v_mfma_f32_16x16x32_bf16 v[24:27], v[124:127], v[190:193], v[24:27]
	v_mfma_f32_16x16x32_bf16 v[28:31], v[170:173], v[186:189], v[100:103]
	v_mfma_f32_16x16x32_bf16 v[28:31], v[174:177], v[190:193], v[28:31]
	v_mfma_f32_16x16x32_bf16 v[60:63], v[120:123], v[194:197], v[104:107]
	v_mfma_f32_16x16x32_bf16 v[60:63], v[124:127], v[198:201], v[60:63]
	v_mfma_f32_16x16x32_bf16 v[100:103], v[170:173], v[194:197], v[108:111]
	v_mfma_f32_16x16x32_bf16 v[100:103], v[174:177], v[198:201], v[100:103]
	v_mfma_f32_16x16x32_bf16 v[16:19], v[120:123], v[202:205], v[16:19]
	v_mfma_f32_16x16x32_bf16 v[16:19], v[124:127], v[206:209], v[16:19]
	v_mfma_f32_16x16x32_bf16 v[20:23], v[170:173], v[202:205], v[20:23]
	v_mfma_f32_16x16x32_bf16 v[20:23], v[174:177], v[206:209], v[20:23]
	s_setprio 0
	s_barrier
	ds_read_b128 v[104:107], v141
	ds_read_b128 v[108:111], v141 offset:1024
	ds_read_b128 v[112:115], v141 offset:2048
	ds_read_b128 v[116:119], v141 offset:3072
	ds_read_b128 v[120:123], v142
	ds_read_b128 v[124:127], v142 offset:1024
	ds_read_b128 v[170:173], v142 offset:2048
	ds_read_b128 v[174:177], v142 offset:3072
	s_add_u32 s30, s28, 0x8000
	s_addc_u32 s31, s29, 0
	s_add_u32 s26, s26, 0x1c000
	s_addc_u32 s27, s27, 0
	s_mov_b32 m0, s46
	ds_read_b128 v[178:181], v143
	ds_read_b128 v[182:185], v143 offset:1024
	ds_read_b128 v[186:189], v143 offset:2048
	ds_read_b128 v[190:193], v143 offset:3072
	ds_read_b128 v[194:197], v143 offset:4096
	ds_read_b128 v[198:201], v143 offset:5120
	ds_read_b128 v[202:205], v143 offset:6144
	ds_read_b128 v[206:209], v143 offset:7168
	global_load_lds_dwordx4 v134, s[26:27]
	v_lshl_add_u64 v[210:211], s[26:27], 0, v[130:131]
	s_mov_b32 m0, s47
	s_nop 0
	global_load_lds_dwordx4 v[210:211], off
	s_waitcnt vmcnt(8) lgkmcnt(0)
	s_barrier
	s_setprio 1
	v_mfma_f32_16x16x32_bf16 v[64:67], v[104:107], v[178:181], v[64:67]
	v_mfma_f32_16x16x32_bf16 v[64:67], v[108:111], v[182:185], v[64:67]
	v_mfma_f32_16x16x32_bf16 v[68:71], v[112:115], v[178:181], v[68:71]
	v_mfma_f32_16x16x32_bf16 v[68:71], v[116:119], v[182:185], v[68:71]
	v_mfma_f32_16x16x32_bf16 v[72:75], v[104:107], v[186:189], v[72:75]
	v_mfma_f32_16x16x32_bf16 v[72:75], v[108:111], v[190:193], v[72:75]
	v_mfma_f32_16x16x32_bf16 v[76:79], v[112:115], v[186:189], v[76:79]
	v_mfma_f32_16x16x32_bf16 v[76:79], v[116:119], v[190:193], v[76:79]
	v_mfma_f32_16x16x32_bf16 v[80:83], v[104:107], v[194:197], v[80:83]
	v_mfma_f32_16x16x32_bf16 v[80:83], v[108:111], v[198:201], v[80:83]
	v_mfma_f32_16x16x32_bf16 v[84:87], v[112:115], v[194:197], v[84:87]
	v_mfma_f32_16x16x32_bf16 v[84:87], v[116:119], v[198:201], v[84:87]
	v_mfma_f32_16x16x32_bf16 v[88:91], v[104:107], v[202:205], v[88:91]
	v_mfma_f32_16x16x32_bf16 v[210:213], v[108:111], v[206:209], v[88:91]
	v_mfma_f32_16x16x32_bf16 v[88:91], v[112:115], v[202:205], v[92:95]
	v_mfma_f32_16x16x32_bf16 v[214:217], v[116:119], v[206:209], v[88:91]
	s_setprio 0
	s_setprio 1
	v_mfma_f32_16x16x32_bf16 v[88:91], v[120:123], v[178:181], v[96:99]
	v_mfma_f32_16x16x32_bf16 v[96:99], v[124:127], v[182:185], v[88:91]
	v_mfma_f32_16x16x32_bf16 v[32:35], v[170:173], v[178:181], v[32:35]
	v_mfma_f32_16x16x32_bf16 v[32:35], v[174:177], v[182:185], v[32:35]
	v_mfma_f32_16x16x32_bf16 v[36:39], v[120:123], v[186:189], v[36:39]
	v_mfma_f32_16x16x32_bf16 v[36:39], v[124:127], v[190:193], v[36:39]
	v_mfma_f32_16x16x32_bf16 v[40:43], v[170:173], v[186:189], v[40:43]
	v_mfma_f32_16x16x32_bf16 v[40:43], v[174:177], v[190:193], v[40:43]
	v_mfma_f32_16x16x32_bf16 v[44:47], v[120:123], v[194:197], v[44:47]
	v_mfma_f32_16x16x32_bf16 v[44:47], v[124:127], v[198:201], v[44:47]
	v_mfma_f32_16x16x32_bf16 v[48:51], v[170:173], v[194:197], v[48:51]
	v_mfma_f32_16x16x32_bf16 v[48:51], v[174:177], v[198:201], v[48:51]
	v_mfma_f32_16x16x32_bf16 v[52:55], v[120:123], v[202:205], v[52:55]
	v_mfma_f32_16x16x32_bf16 v[52:55], v[124:127], v[206:209], v[52:55]
	v_mfma_f32_16x16x32_bf16 v[56:59], v[170:173], v[202:205], v[56:59]
	v_mfma_f32_16x16x32_bf16 v[56:59], v[174:177], v[206:209], v[56:59]
	s_setprio 0
	s_barrier
; #define PG8_STAGE(bufoff, gbase, voff) do { _Pragma("unroll") for (int _i = 0; _i < 2; ++_i) \
;         __builtin_amdgcn_global_load_lds((const unsigned*)((const char*)(gbase) + (voff)[_i]), (PG8_LAS unsigned*)(lds + (bufoff) + ldsw + _i * 8192), 16, 0, 0); } while (0)
; #define PG8_LDA(dst, b, h) do { _Pragma("unroll") for (int m = 0; m < 4; ++m) _Pragma("unroll") for (int k = 0; k < 2; ++k) dst[m][k] = *(const PG8_LAS bf16x8*)(lds + PG8_SA(b, h) + aoff + m * 2048 + k * 1024); } while (0)
; #define PG8_LDB(dst, b, h) do { _Pragma("unroll") for (int n = 0; n < 2; ++n) _Pragma("unroll") for (int k = 0; k < 2; ++k) dst[n][k] = *(const PG8_LAS bf16x8*)(lds + PG8_SB(b, h) + boff + n * 2048 + k * 1024); } while (0)
; #define PG8_MMA(ai, bj, At, Bt) do { __builtin_amdgcn_s_setprio(1); _Pragma("unroll") for (int m = 0; m < 4; ++m) _Pragma("unroll") for (int n = 0; n < 2; ++n) _Pragma("unroll") for (int k = 0; k < 2; ++k) \
;         acc[ai][bj][m][n] = __builtin_amdgcn_mfma_f32_16x16x32_bf16(Bt[n][k], At[m][k], acc[ai][bj][m][n], 0, 0, 0); __builtin_amdgcn_s_setprio(0); } while (0)
; #define PG8_WAIT_V(n) asm volatile("s_waitcnt vmcnt(" #n ")" ::: "memory")
; #define PG8_WAIT_L(n) asm volatile("s_waitcnt lgkmcnt(" #n ")" ::: "memory")
; #define PG8_BAR __builtin_amdgcn_s_barrier()
; #define PG8_SCHED __builtin_amdgcn_sched_barrier(0)
;     ...
;             PG8_LDA(At, 0, 1); PG8_STAGE(PG8_SB(0, 0), b2, voffB); PG8_STAGE(PG8_SB(0, 1), b2 + hstepB, voffB); PG8_STAGE(PG8_SA(0, 0), a2, voffA);
;             PG8_WAIT_V(8); PG8_WAIT_L(0); PG8_BAR; PG8_MMA(1, 0, At, B0); PG8_MMA(1, 1, At, B1); PG8_BAR; PG8_SCHED;
;             PG8_LDB(B0, 1, 0); PG8_LDB(B1, 1, 1); PG8_SCHED; PG8_LDA(At, 1, 0); PG8_STAGE(PG8_SA(0, 1), a2 + hstepA, voffA);
;             PG8_WAIT_V(8); PG8_WAIT_L(0); PG8_BAR; PG8_MMA(0, 0, At, B0); PG8_MMA(0, 1, At, B1); PG8_BAR; PG8_SCHED;
	s_mov_b32 m0, s48
	v_lshl_add_u64 v[246:247], s[24:25], 0, v[132:133]
	s_add_u32 s26, s24, 0x10000
	ds_read_b128 v[88:91], v143 offset:16384
	ds_read_b128 v[92:95], v143 offset:17408
	ds_read_b128 v[178:181], v143 offset:18432
	ds_read_b128 v[182:185], v143 offset:19456
	ds_read_b128 v[186:189], v143 offset:20480
	ds_read_b128 v[190:193], v143 offset:21504
	ds_read_b128 v[194:197], v143 offset:22528
	ds_read_b128 v[198:201], v143 offset:23552
	global_load_lds_dwordx4 v[246:247], off
	v_lshl_add_u64 v[248:249], s[24:25], 0, v[128:129]
	s_mov_b32 m0, s50
	s_addc_u32 s27, s25, 0
	global_load_lds_dwordx4 v[248:249], off
	s_mov_b32 m0, s51
	s_nop 0
	global_load_lds_dwordx4 v132, s[26:27]
	s_mov_b32 m0, s52
	s_nop 0
	global_load_lds_dwordx4 v128, s[26:27]
	s_mov_b32 m0, s23
	s_nop 0
	global_load_lds_dwordx4 v134, s[28:29]
	v_lshl_add_u64 v[202:203], s[28:29], 0, v[130:131]
	s_mov_b32 m0, s37
	s_nop 0
	global_load_lds_dwordx4 v[202:203], off
	s_waitcnt vmcnt(8) lgkmcnt(0)
	s_barrier
	s_setprio 1
	v_mfma_f32_16x16x32_bf16 v[0:3], v[104:107], v[194:197], v[0:3]
	v_mfma_f32_16x16x32_bf16 v[0:3], v[108:111], v[198:201], v[0:3]
	v_mfma_f32_16x16x32_bf16 v[4:7], v[116:119], v[198:201], v[4:7]
	v_mfma_f32_16x16x32_bf16 v[4:7], v[112:115], v[194:197], v[4:7]
	v_mfma_f32_16x16x32_bf16 v[150:153], v[112:115], v[88:91], v[150:153]
	v_mfma_f32_16x16x32_bf16 v[150:153], v[116:119], v[92:95], v[150:153]
	v_mfma_f32_16x16x32_bf16 v[146:149], v[108:111], v[92:95], v[146:149]
	v_mfma_f32_16x16x32_bf16 v[146:149], v[104:107], v[88:91], v[146:149]
	v_mfma_f32_16x16x32_bf16 v[154:157], v[104:107], v[178:181], v[154:157]
	v_mfma_f32_16x16x32_bf16 v[154:157], v[108:111], v[182:185], v[154:157]
	v_mfma_f32_16x16x32_bf16 v[158:161], v[116:119], v[182:185], v[158:161]
	v_mfma_f32_16x16x32_bf16 v[158:161], v[112:115], v[178:181], v[158:161]
	v_mfma_f32_16x16x32_bf16 v[166:169], v[112:115], v[186:189], v[166:169]
	v_mfma_f32_16x16x32_bf16 v[166:169], v[116:119], v[190:193], v[166:169]
	v_mfma_f32_16x16x32_bf16 v[162:165], v[108:111], v[190:193], v[162:165]
	v_mfma_f32_16x16x32_bf16 v[162:165], v[104:107], v[186:189], v[162:165]
	s_setprio 0
	s_setprio 1
	v_mfma_f32_16x16x32_bf16 v[8:11], v[120:123], v[88:91], v[8:11]
	v_mfma_f32_16x16x32_bf16 v[202:205], v[124:127], v[92:95], v[8:11]
	v_mfma_f32_16x16x32_bf16 v[8:11], v[170:173], v[88:91], v[12:15]
	v_mfma_f32_16x16x32_bf16 v[206:209], v[174:177], v[92:95], v[8:11]
	v_mfma_f32_16x16x32_bf16 v[8:11], v[120:123], v[178:181], v[24:27]
	v_mfma_f32_16x16x32_bf16 v[218:221], v[124:127], v[182:185], v[8:11]
	v_mfma_f32_16x16x32_bf16 v[8:11], v[170:173], v[178:181], v[28:31]
	v_mfma_f32_16x16x32_bf16 v[178:181], v[174:177], v[182:185], v[8:11]
	v_mfma_f32_16x16x32_bf16 v[8:11], v[120:123], v[186:189], v[60:63]
	v_mfma_f32_16x16x32_bf16 v[182:185], v[124:127], v[190:193], v[8:11]
	v_mfma_f32_16x16x32_bf16 v[8:11], v[170:173], v[186:189], v[100:103]
	v_mfma_f32_16x16x32_bf16 v[186:189], v[174:177], v[190:193], v[8:11]
	v_mfma_f32_16x16x32_bf16 v[8:11], v[120:123], v[194:197], v[16:19]
	v_mfma_f32_16x16x32_bf16 v[190:193], v[124:127], v[198:201], v[8:11]
	v_mfma_f32_16x16x32_bf16 v[8:11], v[170:173], v[194:197], v[20:23]
	v_mfma_f32_16x16x32_bf16 v[170:173], v[174:177], v[198:201], v[8:11]
	s_setprio 0
	s_barrier
	s_nop 4
	ds_read_b128 v[8:11], v144
	ds_read_b128 v[12:15], v144 offset:1024
	ds_read_b128 v[16:19], v144 offset:2048
	ds_read_b128 v[20:23], v144 offset:3072
	ds_read_b128 v[174:177], v145
	ds_read_b128 v[194:197], v145 offset:1024
	ds_read_b128 v[198:201], v145 offset:2048
	ds_read_b128 v[222:225], v145 offset:3072
	s_add_u32 s26, s28, 0x4000
	s_addc_u32 s27, s29, 0
	s_mov_b32 m0, s39
	ds_read_b128 v[24:27], v143 offset:32768
	ds_read_b128 v[28:31], v143 offset:33792
	ds_read_b128 v[60:63], v143 offset:34816
	ds_read_b128 v[226:229], v143 offset:35840
	ds_read_b128 v[230:233], v143 offset:36864
	ds_read_b128 v[234:237], v143 offset:37888
	ds_read_b128 v[238:241], v143 offset:38912
	ds_read_b128 v[242:245], v143 offset:39936
	global_load_lds_dwordx4 v134, s[26:27]
	v_lshl_add_u64 v[88:89], s[26:27], 0, v[130:131]
	s_mov_b32 m0, s40
	s_nop 0
	global_load_lds_dwordx4 v[88:89], off
	s_waitcnt vmcnt(8) lgkmcnt(0)
	s_barrier
; #define PG8_STAGE(bufoff, gbase, voff) do { _Pragma("unroll") for (int _i = 0; _i < 2; ++_i) \
;         __builtin_amdgcn_global_load_lds((const unsigned*)((const char*)(gbase) + (voff)[_i]), (PG8_LAS unsigned*)(lds + (bufoff) + ldsw + _i * 8192), 16, 0, 0); } while (0)
; #define PG8_LDA(dst, b, h) do { _Pragma("unroll") for (int m = 0; m < 4; ++m) _Pragma("unroll") for (int k = 0; k < 2; ++k) dst[m][k] = *(const PG8_LAS bf16x8*)(lds + PG8_SA(b, h) + aoff + m * 2048 + k * 1024); } while (0)
; #define PG8_LDB(dst, b, h) do { _Pragma("unroll") for (int n = 0; n < 2; ++n) _Pragma("unroll") for (int k = 0; k < 2; ++k) dst[n][k] = *(const PG8_LAS bf16x8*)(lds + PG8_SB(b, h) + boff + n * 2048 + k * 1024); } while (0)
; #define PG8_MMA(ai, bj, At, Bt) do { __builtin_amdgcn_s_setprio(1); _Pragma("unroll") for (int m = 0; m < 4; ++m) _Pragma("unroll") for (int n = 0; n < 2; ++n) _Pragma("unroll") for (int k = 0; k < 2; ++k) \
;         acc[ai][bj][m][n] = __builtin_amdgcn_mfma_f32_16x16x32_bf16(Bt[n][k], At[m][k], acc[ai][bj][m][n], 0, 0, 0); __builtin_amdgcn_s_setprio(0); } while (0)
; #define PG8_WAIT_V(n) asm volatile("s_waitcnt vmcnt(" #n ")" ::: "memory")
; #define PG8_WAIT_L(n) asm volatile("s_waitcnt lgkmcnt(" #n ")" ::: "memory")
; #define PG8_BAR __builtin_amdgcn_s_barrier()
; #define PG8_SCHED __builtin_amdgcn_sched_barrier(0)
;     ...
;             PG8_LDB(B0, 1, 0); PG8_LDB(B1, 1, 1); PG8_SCHED; PG8_LDA(At, 1, 0); PG8_STAGE(PG8_SA(0, 1), a2 + hstepA, voffA);
;             PG8_WAIT_V(8); PG8_WAIT_L(0); PG8_BAR; PG8_MMA(0, 0, At, B0); PG8_MMA(0, 1, At, B1); PG8_BAR; PG8_SCHED;
;             PG8_LDA(At, 1, 1); PG8_STAGE(PG8_SB(1, 0), b3, voffB); PG8_STAGE(PG8_SB(1, 1), b3 + hstepB, voffB); PG8_STAGE(PG8_SA(1, 0), a3, voffA);
;             PG8_WAIT_V(8); PG8_WAIT_L(0); PG8_BAR; PG8_MMA(1, 0, At, B0); PG8_MMA(1, 1, At, B1); PG8_BAR; PG8_SCHED;
;     ...
;         if constexpr (ALIGN_EPI) { if (wr == 0) PG8_BAR; }
	s_setprio 1
	v_mfma_f32_16x16x32_bf16 v[64:67], v[8:11], v[24:27], v[64:67]
	v_mfma_f32_16x16x32_bf16 v[124:127], v[12:15], v[28:31], v[64:67]
	v_mfma_f32_16x16x32_bf16 v[64:67], v[16:19], v[24:27], v[68:71]
	v_mfma_f32_16x16x32_bf16 v[120:123], v[20:23], v[28:31], v[64:67]
	v_mfma_f32_16x16x32_bf16 v[64:67], v[8:11], v[60:63], v[72:75]
	v_mfma_f32_16x16x32_bf16 v[108:111], v[12:15], v[226:229], v[64:67]
	v_mfma_f32_16x16x32_bf16 v[64:67], v[16:19], v[60:63], v[76:79]
	v_mfma_f32_16x16x32_bf16 v[104:107], v[20:23], v[226:229], v[64:67]
	v_mfma_f32_16x16x32_bf16 v[64:67], v[8:11], v[230:233], v[80:83]
	v_mfma_f32_16x16x32_bf16 v[92:95], v[12:15], v[234:237], v[64:67]
	v_mfma_f32_16x16x32_bf16 v[64:67], v[16:19], v[230:233], v[84:87]
	v_mfma_f32_16x16x32_bf16 v[88:91], v[20:23], v[234:237], v[64:67]
	v_mfma_f32_16x16x32_bf16 v[64:67], v[8:11], v[238:241], v[210:213]
	v_mfma_f32_16x16x32_bf16 v[76:79], v[12:15], v[242:245], v[64:67]
	v_mfma_f32_16x16x32_bf16 v[64:67], v[16:19], v[238:241], v[214:217]
	v_mfma_f32_16x16x32_bf16 v[72:75], v[20:23], v[242:245], v[64:67]
	s_setprio 0
	s_setprio 1
	v_mfma_f32_16x16x32_bf16 v[64:67], v[174:177], v[24:27], v[96:99]
	v_mfma_f32_16x16x32_bf16 v[24:27], v[198:201], v[24:27], v[32:35]
	v_mfma_f32_16x16x32_bf16 v[112:115], v[222:225], v[28:31], v[24:27]
	v_mfma_f32_16x16x32_bf16 v[24:27], v[174:177], v[60:63], v[36:39]
	v_mfma_f32_16x16x32_bf16 v[100:103], v[194:197], v[226:229], v[24:27]
	v_mfma_f32_16x16x32_bf16 v[24:27], v[198:201], v[60:63], v[40:43]
	v_mfma_f32_16x16x32_bf16 v[96:99], v[222:225], v[226:229], v[24:27]
	v_mfma_f32_16x16x32_bf16 v[24:27], v[174:177], v[230:233], v[44:47]
	v_mfma_f32_16x16x32_bf16 v[84:87], v[194:197], v[234:237], v[24:27]
	v_mfma_f32_16x16x32_bf16 v[24:27], v[198:201], v[230:233], v[48:51]
	v_mfma_f32_16x16x32_bf16 v[80:83], v[222:225], v[234:237], v[24:27]
	v_mfma_f32_16x16x32_bf16 v[24:27], v[174:177], v[238:241], v[52:55]
	v_mfma_f32_16x16x32_bf16 v[60:63], v[194:197], v[242:245], v[24:27]
	v_mfma_f32_16x16x32_bf16 v[24:27], v[198:201], v[238:241], v[56:59]
	v_mfma_f32_16x16x32_bf16 v[116:119], v[194:197], v[28:31], v[64:67]
	v_mfma_f32_16x16x32_bf16 v[56:59], v[222:225], v[242:245], v[24:27]
	s_setprio 0
	s_barrier
	s_mov_b32 m0, s53
	s_nop 2
	v_lshl_add_u64 v[24:25], v[246:247], 0, s[12:13]
	s_add_u32 s24, s24, 0x10080
	ds_read_b128 v[32:35], v143 offset:49152
	ds_read_b128 v[36:39], v143 offset:50176
	ds_read_b128 v[210:213], v143 offset:51200
	ds_read_b128 v[214:217], v143 offset:52224
	ds_read_b128 v[226:229], v143 offset:53248
	ds_read_b128 v[230:233], v143 offset:54272
	ds_read_b128 v[234:237], v143 offset:55296
	ds_read_b128 v[238:241], v143 offset:56320
	global_load_lds_dwordx4 v[24:25], off
	v_lshl_add_u64 v[24:25], v[248:249], 0, s[12:13]
	s_mov_b32 m0, s54
	s_addc_u32 s25, s25, 0
	global_load_lds_dwordx4 v[24:25], off
	s_mov_b32 m0, s55
	s_nop 0
	global_load_lds_dwordx4 v132, s[24:25]
	s_mov_b32 m0, s56
	s_nop 0
	global_load_lds_dwordx4 v128, s[24:25]
	s_mov_b32 m0, s42
	s_nop 0
	global_load_lds_dwordx4 v134, s[30:31]
	v_lshl_add_u64 v[24:25], s[30:31], 0, v[130:131]
	s_mov_b32 m0, s43
	s_nop 0
	global_load_lds_dwordx4 v[24:25], off
	s_waitcnt vmcnt(8) lgkmcnt(0)
	s_barrier
	s_setprio 1
	v_mfma_f32_16x16x32_bf16 v[24:27], v[8:11], v[32:35], v[146:149]
	v_mfma_f32_16x16x32_bf16 v[68:71], v[12:15], v[36:39], v[24:27]
	v_mfma_f32_16x16x32_bf16 v[24:27], v[16:19], v[32:35], v[150:153]
	v_mfma_f32_16x16x32_bf16 v[64:67], v[20:23], v[36:39], v[24:27]
	v_mfma_f32_16x16x32_bf16 v[24:27], v[8:11], v[210:213], v[154:157]
	v_mfma_f32_16x16x32_bf16 v[44:47], v[12:15], v[214:217], v[24:27]
	v_mfma_f32_16x16x32_bf16 v[24:27], v[16:19], v[210:213], v[158:161]
	v_mfma_f32_16x16x32_bf16 v[40:43], v[20:23], v[214:217], v[24:27]
	v_mfma_f32_16x16x32_bf16 v[24:27], v[8:11], v[226:229], v[162:165]
	v_mfma_f32_16x16x32_bf16 v[28:31], v[12:15], v[230:233], v[24:27]
	v_mfma_f32_16x16x32_bf16 v[0:3], v[8:11], v[234:237], v[0:3]
	v_mfma_f32_16x16x32_bf16 v[12:15], v[12:15], v[238:241], v[0:3]
	v_mfma_f32_16x16x32_bf16 v[24:27], v[16:19], v[226:229], v[166:169]
	v_mfma_f32_16x16x32_bf16 v[24:27], v[20:23], v[230:233], v[24:27]
	v_mfma_f32_16x16x32_bf16 v[0:3], v[16:19], v[234:237], v[4:7]
	v_mfma_f32_16x16x32_bf16 v[8:11], v[20:23], v[238:241], v[0:3]
	s_setprio 0
	s_setprio 1
	v_mfma_f32_16x16x32_bf16 v[0:3], v[174:177], v[32:35], v[202:205]
	v_mfma_f32_16x16x32_bf16 v[52:55], v[194:197], v[36:39], v[0:3]
	v_mfma_f32_16x16x32_bf16 v[0:3], v[198:201], v[32:35], v[206:209]
	v_mfma_f32_16x16x32_bf16 v[48:51], v[222:225], v[36:39], v[0:3]
	v_mfma_f32_16x16x32_bf16 v[0:3], v[174:177], v[210:213], v[218:221]
	v_mfma_f32_16x16x32_bf16 v[36:39], v[194:197], v[214:217], v[0:3]
	v_mfma_f32_16x16x32_bf16 v[0:3], v[198:201], v[210:213], v[178:181]
	v_mfma_f32_16x16x32_bf16 v[32:35], v[222:225], v[214:217], v[0:3]
	v_mfma_f32_16x16x32_bf16 v[0:3], v[174:177], v[226:229], v[182:185]
	v_mfma_f32_16x16x32_bf16 v[20:23], v[194:197], v[230:233], v[0:3]
	v_mfma_f32_16x16x32_bf16 v[0:3], v[198:201], v[226:229], v[186:189]
	v_mfma_f32_16x16x32_bf16 v[16:19], v[222:225], v[230:233], v[0:3]
	v_mfma_f32_16x16x32_bf16 v[0:3], v[174:177], v[234:237], v[190:193]
	v_mfma_f32_16x16x32_bf16 v[4:7], v[194:197], v[238:241], v[0:3]
	v_mfma_f32_16x16x32_bf16 v[0:3], v[198:201], v[234:237], v[170:173]
	v_mfma_f32_16x16x32_bf16 v[0:3], v[222:225], v[238:241], v[0:3]
	s_setprio 0
	s_barrier
	s_and_b64 vcc, exec, s[0:1]
	s_cbranch_vccnz .LBB0_99
	s_barrier

;     __host__ __device__ __forceinline__ bool next(int i, Unit& u) const { const int vv = vid + (i / 5) * G; if (vv >= 256) return false; u.pm = vv >> 2; u.pn = (vv & 3) + 4 * (i % 5); return true; }
; #define PG8_STAGE(bufoff, gbase, voff) do { _Pragma("unroll") for (int _i = 0; _i < 2; ++_i) \
;         __builtin_amdgcn_global_load_lds((const unsigned*)((const char*)(gbase) + (voff)[_i]), (PG8_LAS unsigned*)(lds + (bufoff) + ldsw + _i * 8192), 16, 0, 0); } while (0)
; #define PG8_LDA(dst, b, h) do { _Pragma("unroll") for (int m = 0; m < 4; ++m) _Pragma("unroll") for (int k = 0; k < 2; ++k) dst[m][k] = *(const PG8_LAS bf16x8*)(lds + PG8_SA(b, h) + aoff + m * 2048 + k * 1024); } while (0)
; #define PG8_LDB(dst, b, h) do { _Pragma("unroll") for (int n = 0; n < 2; ++n) _Pragma("unroll") for (int k = 0; k < 2; ++k) dst[n][k] = *(const PG8_LAS bf16x8*)(lds + PG8_SB(b, h) + boff + n * 2048 + k * 1024); } while (0)
; #define PG8_WAIT_V(n) asm volatile("s_waitcnt vmcnt(" #n ")" ::: "memory")
; #define PG8_WAIT_L(n) asm volatile("s_waitcnt lgkmcnt(" #n ")" ::: "memory")
; #define PG8_BAR __builtin_amdgcn_s_barrier()
;     ...
;         const bool has_next = S.next(ui + 1, nxt);
;         const char* nA = has_next ? (const char*)g.A + (size_t)nxt.pm * tstepA + (size_t)nxt.pn * APN + kofA : cA; const char* nB = has_next ? (const char*)g.Bt + (size_t)nxt.pn * tstepB + S.b_off(nxt) + kofB : cB;
;         for (int t = 0; t < nt; t += 2) {
;             const bool last = (t == nt - 2);
;             const char* a1 = cA + (ptrdiff_t)(t + 1) * kstepA;
;             const char* a2 = last ? nA : cA + (ptrdiff_t)(t + 2) * kstepA; const char* b2 = last ? nB : cB + (ptrdiff_t)(t + 2) * kstep;
;             const char* a3 = a2 + kstepA; const char* b3 = b2 + kstep;
;             if (last && has_next) S.a_ready(nxt);
;             if constexpr (SP2) {
;             PG8_LDB(B0, 0, 0); PG8_LDB(B1, 0, 1); PG8_SCHED; PG8_LDA(At, 0, 0); PG8_STAGE(PG8_SA(1, 1), a1 + hstepA, voffA);
;             PG8_WAIT_V(8); PG8_WAIT_L(0); PG8_BAR; PG8_MMA(0, 0, At, B0); PG8_MMA(0, 1, At, B1); PG8_BAR; PG8_SCHED;
;             PG8_LDA(At, 0, 1); PG8_STAGE(PG8_SB(0, 0), b2, voffB); PG8_STAGE(PG8_SB(0, 1), b2 + hstepB, voffB); PG8_STAGE(PG8_SA(0, 0), a2, voffA);
;             PG8_WAIT_V(8); PG8_WAIT_L(0); PG8_BAR; PG8_MMA(1, 0, At, B0); PG8_MMA(1, 1, At, B1); PG8_BAR; PG8_SCHED;
.Lin_nostg:
	s_add_u32 s65, s6, 0x4000
	s_addc_u32 s66, s7, 0
	s_cmp_eq_u32 vcc_lo, 28
	s_cselect_b32 s90, s54, s65
	s_cselect_b32 s91, s29, s66
	s_cselect_b32 s88, s55, s56
	s_cselect_b32 s89, s31, s57
	s_add_u32 s86, s90, 0x8000
	s_addc_u32 s87, s91, 0
	s_add_i32 s65, 0, 0x10000
	s_add_i32 s66, 0, 0x14000
	v_add_u32_e32 v22, s65, v182
	v_add_u32_e32 v54, s66, v182
	ds_read_b128 v[10:13], v22
	ds_read_b128 v[14:17], v22 offset:1024
	ds_read_b128 v[18:21], v22 offset:2048
	ds_read_b128 v[22:25], v22 offset:3072
	ds_read_b128 v[26:29], v54
	ds_read_b128 v[38:41], v54 offset:1024
	ds_read_b128 v[50:53], v54 offset:2048
	ds_read_b128 v[54:57], v54 offset:3072
	s_add_i32 m0, s51, 0xc000
	ds_read_b128 v[172:175], v183
	ds_read_b128 v[176:179], v183 offset:1024
	ds_read_b128 v[184:187], v183 offset:2048
	ds_read_b128 v[188:191], v183 offset:3072
	ds_read_b128 v[192:195], v183 offset:4096
	ds_read_b128 v[196:199], v183 offset:5120
	ds_read_b128 v[200:203], v183 offset:6144
	ds_read_b128 v[204:207], v183 offset:7168
	global_load_lds_dwordx4 v168, s[6:7]
	s_add_i32 m0, s51, 0xe000
	s_nop 0
	global_load_lds_dwordx4 v170, s[6:7]
	s_waitcnt vmcnt(8) lgkmcnt(0)
	s_barrier
	s_setprio 1
	v_mfma_f32_16x16x32_bf16 v[158:161], v[10:13], v[172:175], 0
	v_mfma_f32_16x16x32_bf16 v[158:161], v[14:17], v[176:179], v[158:161]
	v_mfma_f32_16x16x32_bf16 v[154:157], v[22:25], v[176:179], 0
	v_mfma_f32_16x16x32_bf16 v[154:157], v[18:21], v[172:175], v[154:157]
	v_mfma_f32_16x16x32_bf16 v[138:141], v[18:21], v[184:187], 0
	v_mfma_f32_16x16x32_bf16 v[138:141], v[22:25], v[188:191], v[138:141]
	v_mfma_f32_16x16x32_bf16 v[142:145], v[14:17], v[188:191], 0
	v_mfma_f32_16x16x32_bf16 v[142:145], v[10:13], v[184:187], v[142:145]
	v_mfma_f32_16x16x32_bf16 v[126:129], v[10:13], v[192:195], 0
	v_mfma_f32_16x16x32_bf16 v[126:129], v[14:17], v[196:199], v[126:129]
	v_mfma_f32_16x16x32_bf16 v[122:125], v[22:25], v[196:199], 0
	v_mfma_f32_16x16x32_bf16 v[122:125], v[18:21], v[192:195], v[122:125]
	v_mfma_f32_16x16x32_bf16 v[106:109], v[18:21], v[200:203], 0
	v_mfma_f32_16x16x32_bf16 v[106:109], v[22:25], v[204:207], v[106:109]
	v_mfma_f32_16x16x32_bf16 v[110:113], v[14:17], v[204:207], 0
	v_mfma_f32_16x16x32_bf16 v[110:113], v[10:13], v[200:203], v[110:113]
	s_setprio 0
	s_setprio 1
	v_mfma_f32_16x16x32_bf16 v[150:153], v[26:29], v[172:175], 0
	v_mfma_f32_16x16x32_bf16 v[150:153], v[38:41], v[176:179], v[150:153]
	v_mfma_f32_16x16x32_bf16 v[146:149], v[54:57], v[176:179], 0
	v_mfma_f32_16x16x32_bf16 v[146:149], v[50:53], v[172:175], v[146:149]
	v_mfma_f32_16x16x32_bf16 v[130:133], v[50:53], v[184:187], 0
	v_mfma_f32_16x16x32_bf16 v[130:133], v[54:57], v[188:191], v[130:133]
	v_mfma_f32_16x16x32_bf16 v[134:137], v[38:41], v[188:191], 0
	v_mfma_f32_16x16x32_bf16 v[134:137], v[26:29], v[184:187], v[134:137]
	v_mfma_f32_16x16x32_bf16 v[118:121], v[26:29], v[192:195], 0
	v_mfma_f32_16x16x32_bf16 v[118:121], v[38:41], v[196:199], v[118:121]
	v_mfma_f32_16x16x32_bf16 v[114:117], v[54:57], v[196:199], 0
	v_mfma_f32_16x16x32_bf16 v[114:117], v[50:53], v[192:195], v[114:117]
	v_mfma_f32_16x16x32_bf16 v[98:101], v[50:53], v[200:203], 0
	v_mfma_f32_16x16x32_bf16 v[98:101], v[54:57], v[204:207], v[98:101]
	v_mfma_f32_16x16x32_bf16 v[102:105], v[38:41], v[204:207], 0
	v_mfma_f32_16x16x32_bf16 v[102:105], v[26:29], v[200:203], v[102:105]
	s_setprio 0
	s_barrier
	s_add_i32 s65, s65, s2
	s_mov_b32 m0, s65
	ds_read_b128 v[172:175], v183 offset:16384
	ds_read_b128 v[176:179], v183 offset:17408
	ds_read_b128 v[184:187], v183 offset:18432
	ds_read_b128 v[188:191], v183 offset:19456
	ds_read_b128 v[192:195], v183 offset:20480
	ds_read_b128 v[196:199], v183 offset:21504
	ds_read_b128 v[200:203], v183 offset:22528
	ds_read_b128 v[204:207], v183 offset:23552
	global_load_lds_dwordx4 v0, s[88:89]
	s_add_i32 m0, s65, 0x2000
	s_add_u32 s96, s88, 0x4000
	s_addc_u32 s97, s89, 0
	s_add_i32 s65, s66, s2
	global_load_lds_dwordx4 v162, s[88:89]
	s_mov_b32 m0, s65
	s_nop 0
	global_load_lds_dwordx4 v0, s[96:97]
	s_add_i32 m0, s65, 0x2000
	s_nop 0
	global_load_lds_dwordx4 v162, s[96:97]
	s_mov_b32 m0, s51
	s_nop 0
	global_load_lds_dwordx4 v166, s[90:91]
	s_mov_b32 m0, s92
	s_nop 0
	global_load_lds_dwordx4 v164, s[90:91]
	s_waitcnt vmcnt(8) lgkmcnt(0)
	s_barrier
	s_setprio 1
	v_mfma_f32_16x16x32_bf16 v[94:97], v[10:13], v[172:175], 0
	v_mfma_f32_16x16x32_bf16 v[94:97], v[14:17], v[176:179], v[94:97]
	v_mfma_f32_16x16x32_bf16 v[90:93], v[18:21], v[172:175], 0
	v_mfma_f32_16x16x32_bf16 v[90:93], v[22:25], v[176:179], v[90:93]
	v_mfma_f32_16x16x32_bf16 v[78:81], v[10:13], v[184:187], 0
	v_mfma_f32_16x16x32_bf16 v[78:81], v[14:17], v[188:191], v[78:81]
	v_mfma_f32_16x16x32_bf16 v[74:77], v[18:21], v[184:187], 0
	v_mfma_f32_16x16x32_bf16 v[74:77], v[22:25], v[188:191], v[74:77]
	v_mfma_f32_16x16x32_bf16 v[62:65], v[10:13], v[192:195], 0
	v_mfma_f32_16x16x32_bf16 v[62:65], v[14:17], v[196:199], v[62:65]
	v_mfma_f32_16x16x32_bf16 v[58:61], v[18:21], v[192:195], 0
	v_mfma_f32_16x16x32_bf16 v[58:61], v[22:25], v[196:199], v[58:61]
	v_mfma_f32_16x16x32_bf16 v[10:13], v[10:13], v[200:203], 0
	v_mfma_f32_16x16x32_bf16 v[10:13], v[14:17], v[204:207], v[10:13]
	v_mfma_f32_16x16x32_bf16 v[14:17], v[18:21], v[200:203], 0
	v_mfma_f32_16x16x32_bf16 v[14:17], v[22:25], v[204:207], v[14:17]
	s_setprio 0
	s_setprio 1
	v_mfma_f32_16x16x32_bf16 v[30:33], v[26:29], v[184:187], 0
	v_mfma_f32_16x16x32_bf16 v[70:73], v[38:41], v[188:191], v[30:33]
	v_mfma_f32_16x16x32_bf16 v[30:33], v[50:53], v[184:187], 0
	v_mfma_f32_16x16x32_bf16 v[66:69], v[54:57], v[188:191], v[30:33]
	v_mfma_f32_16x16x32_bf16 v[30:33], v[26:29], v[192:195], 0
	v_mfma_f32_16x16x32_bf16 v[46:49], v[38:41], v[196:199], v[30:33]
	v_mfma_f32_16x16x32_bf16 v[30:33], v[50:53], v[192:195], 0
	v_mfma_f32_16x16x32_bf16 v[42:45], v[54:57], v[196:199], v[30:33]
	v_mfma_f32_16x16x32_bf16 v[6:9], v[26:29], v[200:203], 0
	v_mfma_f32_16x16x32_bf16 v[6:9], v[38:41], v[204:207], v[6:9]
	v_mfma_f32_16x16x32_bf16 v[2:5], v[50:53], v[200:203], 0
	v_mfma_f32_16x16x32_bf16 v[2:5], v[54:57], v[204:207], v[2:5]
	v_mfma_f32_16x16x32_bf16 v[18:21], v[26:29], v[172:175], 0
	v_mfma_f32_16x16x32_bf16 v[18:21], v[38:41], v[176:179], v[18:21]
	v_mfma_f32_16x16x32_bf16 v[22:25], v[50:53], v[172:175], 0
	v_mfma_f32_16x16x32_bf16 v[22:25], v[54:57], v[176:179], v[22:25]
	s_setprio 0
	s_barrier
	s_branch .Lin_mid

; #define PG8_STAGE(bufoff, gbase, voff) do { _Pragma("unroll") for (int _i = 0; _i < 2; ++_i) \
;         __builtin_amdgcn_global_load_lds((const unsigned*)((const char*)(gbase) + (voff)[_i]), (PG8_LAS unsigned*)(lds + (bufoff) + ldsw + _i * 8192), 16, 0, 0); } while (0)
; #define PG8_LDA(dst, b, h) do { _Pragma("unroll") for (int m = 0; m < 4; ++m) _Pragma("unroll") for (int k = 0; k < 2; ++k) dst[m][k] = *(const PG8_LAS bf16x8*)(lds + PG8_SA(b, h) + aoff + m * 2048 + k * 1024); } while (0)
; #define PG8_LDB(dst, b, h) do { _Pragma("unroll") for (int n = 0; n < 2; ++n) _Pragma("unroll") for (int k = 0; k < 2; ++k) dst[n][k] = *(const PG8_LAS bf16x8*)(lds + PG8_SB(b, h) + boff + n * 2048 + k * 1024); } while (0)
; #define PG8_MMA(ai, bj, At, Bt) do { __builtin_amdgcn_s_setprio(1); _Pragma("unroll") for (int m = 0; m < 4; ++m) _Pragma("unroll") for (int n = 0; n < 2; ++n) _Pragma("unroll") for (int k = 0; k < 2; ++k) \
;         acc[ai][bj][m][n] = __builtin_amdgcn_mfma_f32_16x16x32_bf16(Bt[n][k], At[m][k], acc[ai][bj][m][n], 0, 0, 0); __builtin_amdgcn_s_setprio(0); } while (0)
; #define PG8_WAIT_V(n) asm volatile("s_waitcnt vmcnt(" #n ")" ::: "memory")
; #define PG8_WAIT_L(n) asm volatile("s_waitcnt lgkmcnt(" #n ")" ::: "memory")
; #define PG8_BAR __builtin_amdgcn_s_barrier()
; #define PG8_SCHED __builtin_amdgcn_sched_barrier(0)
;     ...
;             const bool last = (t == nt - 2);
;             const char* a1 = cA + (ptrdiff_t)(t + 1) * kstepA;
;             const char* a2 = last ? nA : cA + (ptrdiff_t)(t + 2) * kstepA; const char* b2 = last ? nB : cB + (ptrdiff_t)(t + 2) * kstep;
;             const char* a3 = a2 + kstepA; const char* b3 = b2 + kstep;
;             if (last && has_next) S.a_ready(nxt);
;             if constexpr (SP2) {
;             PG8_LDB(B0, 0, 0); PG8_LDB(B1, 0, 1); PG8_SCHED; PG8_LDA(At, 0, 0); PG8_STAGE(PG8_SA(1, 1), a1 + hstepA, voffA);
;             PG8_WAIT_V(8); PG8_WAIT_L(0); PG8_BAR; PG8_MMA(0, 0, At, B0); PG8_MMA(0, 1, At, B1); PG8_BAR; PG8_SCHED;
;             PG8_LDA(At, 0, 1); PG8_STAGE(PG8_SB(0, 0), b2, voffB); PG8_STAGE(PG8_SB(0, 1), b2 + hstepB, voffB); PG8_STAGE(PG8_SA(0, 0), a2, voffA);
;             PG8_WAIT_V(8); PG8_WAIT_L(0); PG8_BAR; PG8_MMA(1, 0, At, B0); PG8_MMA(1, 1, At, B1); PG8_BAR; PG8_SCHED;
.LBB0_328:
	s_add_u32 s65, s6, 0x4000
	s_addc_u32 s66, s7, 0
	s_cmp_eq_u32 vcc_lo, 28
	s_cselect_b32 s90, s54, s65
	s_cselect_b32 s91, s29, s66
	s_cselect_b32 s88, s55, s56
	s_cselect_b32 s89, s31, s57
	s_add_u32 s86, s90, 0x8000
	s_addc_u32 s87, s91, 0
	s_add_i32 s65, 0, 0x10000
	s_add_i32 s66, 0, 0x14000
	v_add_u32_e32 v22, s65, v182
	v_add_u32_e32 v54, s66, v182
	ds_read_b128 v[10:13], v22
	ds_read_b128 v[14:17], v22 offset:1024
	ds_read_b128 v[18:21], v22 offset:2048
	ds_read_b128 v[22:25], v22 offset:3072
	ds_read_b128 v[26:29], v54
	ds_read_b128 v[38:41], v54 offset:1024
	ds_read_b128 v[50:53], v54 offset:2048
	ds_read_b128 v[54:57], v54 offset:3072
	s_add_i32 m0, s51, 0xc000
	ds_read_b128 v[172:175], v183
	ds_read_b128 v[176:179], v183 offset:1024
	ds_read_b128 v[184:187], v183 offset:2048
	ds_read_b128 v[188:191], v183 offset:3072
	ds_read_b128 v[192:195], v183 offset:4096
	ds_read_b128 v[196:199], v183 offset:5120
	ds_read_b128 v[200:203], v183 offset:6144
	ds_read_b128 v[204:207], v183 offset:7168
	global_load_lds_dwordx4 v168, s[6:7]
	s_add_i32 m0, s51, 0xe000
	s_nop 0
	global_load_lds_dwordx4 v170, s[6:7]
	s_waitcnt vmcnt(8) lgkmcnt(0)
	s_barrier
	s_setprio 1
	v_mfma_f32_16x16x32_bf16 v[158:161], v[10:13], v[172:175], v[158:161]
	v_mfma_f32_16x16x32_bf16 v[158:161], v[14:17], v[176:179], v[158:161]
	v_mfma_f32_16x16x32_bf16 v[154:157], v[22:25], v[176:179], v[154:157]
	v_mfma_f32_16x16x32_bf16 v[154:157], v[18:21], v[172:175], v[154:157]
	v_mfma_f32_16x16x32_bf16 v[138:141], v[18:21], v[184:187], v[138:141]
	v_mfma_f32_16x16x32_bf16 v[138:141], v[22:25], v[188:191], v[138:141]
	v_mfma_f32_16x16x32_bf16 v[142:145], v[14:17], v[188:191], v[142:145]
	v_mfma_f32_16x16x32_bf16 v[142:145], v[10:13], v[184:187], v[142:145]
	v_mfma_f32_16x16x32_bf16 v[126:129], v[10:13], v[192:195], v[126:129]
	v_mfma_f32_16x16x32_bf16 v[126:129], v[14:17], v[196:199], v[126:129]
	v_mfma_f32_16x16x32_bf16 v[122:125], v[22:25], v[196:199], v[122:125]
	v_mfma_f32_16x16x32_bf16 v[122:125], v[18:21], v[192:195], v[122:125]
	v_mfma_f32_16x16x32_bf16 v[106:109], v[18:21], v[200:203], v[106:109]
	v_mfma_f32_16x16x32_bf16 v[106:109], v[22:25], v[204:207], v[106:109]
	v_mfma_f32_16x16x32_bf16 v[110:113], v[14:17], v[204:207], v[110:113]
	v_mfma_f32_16x16x32_bf16 v[110:113], v[10:13], v[200:203], v[110:113]
	s_setprio 0
	s_setprio 1
	v_mfma_f32_16x16x32_bf16 v[150:153], v[26:29], v[172:175], v[150:153]
	v_mfma_f32_16x16x32_bf16 v[150:153], v[38:41], v[176:179], v[150:153]
	v_mfma_f32_16x16x32_bf16 v[146:149], v[54:57], v[176:179], v[146:149]
	v_mfma_f32_16x16x32_bf16 v[146:149], v[50:53], v[172:175], v[146:149]
	v_mfma_f32_16x16x32_bf16 v[130:133], v[50:53], v[184:187], v[130:133]
	v_mfma_f32_16x16x32_bf16 v[130:133], v[54:57], v[188:191], v[130:133]
	v_mfma_f32_16x16x32_bf16 v[134:137], v[38:41], v[188:191], v[134:137]
	v_mfma_f32_16x16x32_bf16 v[134:137], v[26:29], v[184:187], v[134:137]
	v_mfma_f32_16x16x32_bf16 v[118:121], v[26:29], v[192:195], v[118:121]
	v_mfma_f32_16x16x32_bf16 v[118:121], v[38:41], v[196:199], v[118:121]
	v_mfma_f32_16x16x32_bf16 v[114:117], v[54:57], v[196:199], v[114:117]
	v_mfma_f32_16x16x32_bf16 v[114:117], v[50:53], v[192:195], v[114:117]
	v_mfma_f32_16x16x32_bf16 v[98:101], v[50:53], v[200:203], v[98:101]
	v_mfma_f32_16x16x32_bf16 v[98:101], v[54:57], v[204:207], v[98:101]
	v_mfma_f32_16x16x32_bf16 v[102:105], v[38:41], v[204:207], v[102:105]
	v_mfma_f32_16x16x32_bf16 v[102:105], v[26:29], v[200:203], v[102:105]
	s_setprio 0
	s_barrier
	s_add_i32 s65, s65, s2
	s_mov_b32 m0, s65
	ds_read_b128 v[172:175], v183 offset:16384
	ds_read_b128 v[176:179], v183 offset:17408
	ds_read_b128 v[184:187], v183 offset:18432
	ds_read_b128 v[188:191], v183 offset:19456
	ds_read_b128 v[192:195], v183 offset:20480
	ds_read_b128 v[196:199], v183 offset:21504
	ds_read_b128 v[200:203], v183 offset:22528
	ds_read_b128 v[204:207], v183 offset:23552
	global_load_lds_dwordx4 v0, s[88:89]
	s_add_i32 m0, s65, 0x2000
	s_add_u32 s96, s88, 0x4000
	s_addc_u32 s97, s89, 0
	s_add_i32 s65, s66, s2
	global_load_lds_dwordx4 v162, s[88:89]
	s_mov_b32 m0, s65
	s_nop 0
	global_load_lds_dwordx4 v0, s[96:97]
	s_add_i32 m0, s65, 0x2000
	s_nop 0
	global_load_lds_dwordx4 v162, s[96:97]
	s_mov_b32 m0, s51
	s_nop 0
	global_load_lds_dwordx4 v166, s[90:91]
	s_mov_b32 m0, s92
	s_nop 0
	global_load_lds_dwordx4 v164, s[90:91]
	s_waitcnt vmcnt(8) lgkmcnt(0)
	s_barrier
	s_setprio 1
	v_mfma_f32_16x16x32_bf16 v[94:97], v[10:13], v[172:175], v[94:97]
	v_mfma_f32_16x16x32_bf16 v[94:97], v[14:17], v[176:179], v[94:97]
	v_mfma_f32_16x16x32_bf16 v[90:93], v[18:21], v[172:175], v[90:93]
	v_mfma_f32_16x16x32_bf16 v[90:93], v[22:25], v[176:179], v[90:93]
	v_mfma_f32_16x16x32_bf16 v[78:81], v[10:13], v[184:187], v[78:81]
	v_mfma_f32_16x16x32_bf16 v[78:81], v[14:17], v[188:191], v[78:81]
	v_mfma_f32_16x16x32_bf16 v[74:77], v[18:21], v[184:187], v[74:77]
	v_mfma_f32_16x16x32_bf16 v[74:77], v[22:25], v[188:191], v[74:77]
	v_mfma_f32_16x16x32_bf16 v[62:65], v[10:13], v[192:195], v[62:65]
	v_mfma_f32_16x16x32_bf16 v[62:65], v[14:17], v[196:199], v[62:65]
	v_mfma_f32_16x16x32_bf16 v[58:61], v[18:21], v[192:195], v[58:61]
	v_mfma_f32_16x16x32_bf16 v[58:61], v[22:25], v[196:199], v[58:61]
	v_mfma_f32_16x16x32_bf16 v[10:13], v[10:13], v[200:203], v[34:37]
	v_mfma_f32_16x16x32_bf16 v[10:13], v[14:17], v[204:207], v[10:13]
	v_mfma_f32_16x16x32_bf16 v[14:17], v[18:21], v[200:203], v[30:33]
	v_mfma_f32_16x16x32_bf16 v[14:17], v[22:25], v[204:207], v[14:17]
	s_setprio 0
	s_setprio 1
	v_mfma_f32_16x16x32_bf16 v[30:33], v[26:29], v[184:187], v[70:73]
	v_mfma_f32_16x16x32_bf16 v[70:73], v[38:41], v[188:191], v[30:33]
	v_mfma_f32_16x16x32_bf16 v[30:33], v[50:53], v[184:187], v[66:69]
	v_mfma_f32_16x16x32_bf16 v[66:69], v[54:57], v[188:191], v[30:33]
	v_mfma_f32_16x16x32_bf16 v[30:33], v[26:29], v[192:195], v[46:49]
	v_mfma_f32_16x16x32_bf16 v[46:49], v[38:41], v[196:199], v[30:33]
	v_mfma_f32_16x16x32_bf16 v[30:33], v[50:53], v[192:195], v[42:45]
	v_mfma_f32_16x16x32_bf16 v[42:45], v[54:57], v[196:199], v[30:33]
	v_mfma_f32_16x16x32_bf16 v[6:9], v[26:29], v[200:203], v[6:9]
	v_mfma_f32_16x16x32_bf16 v[6:9], v[38:41], v[204:207], v[6:9]
	v_mfma_f32_16x16x32_bf16 v[2:5], v[50:53], v[200:203], v[2:5]
	v_mfma_f32_16x16x32_bf16 v[2:5], v[54:57], v[204:207], v[2:5]
	v_mfma_f32_16x16x32_bf16 v[18:21], v[26:29], v[172:175], v[86:89]
	v_mfma_f32_16x16x32_bf16 v[18:21], v[38:41], v[176:179], v[18:21]
	v_mfma_f32_16x16x32_bf16 v[22:25], v[50:53], v[172:175], v[82:85]
	v_mfma_f32_16x16x32_bf16 v[22:25], v[54:57], v[176:179], v[22:25]
	s_setprio 0
	s_barrier
; #define PG8_STAGE(bufoff, gbase, voff) do { _Pragma("unroll") for (int _i = 0; _i < 2; ++_i) \
;         __builtin_amdgcn_global_load_lds((const unsigned*)((const char*)(gbase) + (voff)[_i]), (PG8_LAS unsigned*)(lds + (bufoff) + ldsw + _i * 8192), 16, 0, 0); } while (0)
; #define PG8_LDA(dst, b, h) do { _Pragma("unroll") for (int m = 0; m < 4; ++m) _Pragma("unroll") for (int k = 0; k < 2; ++k) dst[m][k] = *(const PG8_LAS bf16x8*)(lds + PG8_SA(b, h) + aoff + m * 2048 + k * 1024); } while (0)
; #define PG8_LDB(dst, b, h) do { _Pragma("unroll") for (int n = 0; n < 2; ++n) _Pragma("unroll") for (int k = 0; k < 2; ++k) dst[n][k] = *(const PG8_LAS bf16x8*)(lds + PG8_SB(b, h) + boff + n * 2048 + k * 1024); } while (0)
; #define PG8_WAIT_V(n) asm volatile("s_waitcnt vmcnt(" #n ")" ::: "memory")
; #define PG8_WAIT_L(n) asm volatile("s_waitcnt lgkmcnt(" #n ")" ::: "memory")
; #define PG8_BAR __builtin_amdgcn_s_barrier()
; #define PG8_SCHED __builtin_amdgcn_sched_barrier(0)
;     ...
;             const char* a2 = last ? nA : cA + (ptrdiff_t)(t + 2) * kstepA; const char* b2 = last ? nB : cB + (ptrdiff_t)(t + 2) * kstep;
;             const char* a3 = a2 + kstepA; const char* b3 = b2 + kstep;
;             if (last && has_next) S.a_ready(nxt);
;             if constexpr (SP2) {
;             PG8_LDB(B0, 0, 0); PG8_LDB(B1, 0, 1); PG8_SCHED; PG8_LDA(At, 0, 0); PG8_STAGE(PG8_SA(1, 1), a1 + hstepA, voffA);
;             PG8_WAIT_V(8); PG8_WAIT_L(0); PG8_BAR; PG8_MMA(0, 0, At, B0); PG8_MMA(0, 1, At, B1); PG8_BAR; PG8_SCHED;
;             PG8_LDA(At, 0, 1); PG8_STAGE(PG8_SB(0, 0), b2, voffB); PG8_STAGE(PG8_SB(0, 1), b2 + hstepB, voffB); PG8_STAGE(PG8_SA(0, 0), a2, voffA);
;             PG8_WAIT_V(8); PG8_WAIT_L(0); PG8_BAR; PG8_MMA(1, 0, At, B0); PG8_MMA(1, 1, At, B1); PG8_BAR; PG8_SCHED;
;             PG8_LDB(B0, 1, 0); PG8_LDB(B1, 1, 1); PG8_SCHED; PG8_LDA(At, 1, 0); PG8_STAGE(PG8_SA(0, 1), a2 + hstepA, voffA);
;             PG8_WAIT_V(8); PG8_WAIT_L(0); PG8_BAR; PG8_MMA(0, 0, At, B0); PG8_MMA(0, 1, At, B1); PG8_BAR; PG8_SCHED;
;             PG8_LDA(At, 1, 1); PG8_STAGE(PG8_SB(1, 0), b3, voffB); PG8_STAGE(PG8_SB(1, 1), b3 + hstepB, voffB); PG8_STAGE(PG8_SA(1, 0), a3, voffA);
;             PG8_WAIT_V(8); PG8_WAIT_L(0); PG8_BAR; PG8_MMA(1, 0, At, B0); PG8_MMA(1, 1, At, B1); PG8_BAR; PG8_SCHED;
;     ...
;         if constexpr (ALIGN_EPI) { if (wr == 0) PG8_BAR; }
.Lin_mid:
	s_add_i32 s65, 0, 0x18000
	v_add_u32_e32 v34, s65, v182
	s_add_i32 s66, 0, 0x1c000
	ds_read_b128 v[26:29], v34
	ds_read_b128 v[30:33], v34 offset:1024
	ds_read_b128 v[38:41], v34 offset:2048
	ds_read_b128 v[50:53], v34 offset:3072
	v_add_u32_e32 v34, s66, v182
	ds_read_b128 v[54:57], v34
	ds_read_b128 v[172:175], v34 offset:1024
	ds_read_b128 v[176:179], v34 offset:2048
	ds_read_b128 v[184:187], v34 offset:3072
	s_add_u32 s90, s90, 0x4000
	s_addc_u32 s91, s91, 0
	s_mov_b32 m0, s14
	ds_read_b128 v[34:37], v183 offset:32768
	ds_read_b128 v[82:85], v183 offset:33792
	ds_read_b128 v[86:89], v183 offset:34816
	ds_read_b128 v[188:191], v183 offset:35840
	ds_read_b128 v[192:195], v183 offset:36864
	ds_read_b128 v[196:199], v183 offset:37888
	ds_read_b128 v[200:203], v183 offset:38912
	ds_read_b128 v[204:207], v183 offset:39936
	global_load_lds_dwordx4 v166, s[90:91]
	v_lshl_add_u64 v[208:209], s[90:91], 0, v[164:165]
	s_mov_b32 m0, s15
	s_nop 0
	global_load_lds_dwordx4 v[208:209], off
	s_waitcnt vmcnt(8) lgkmcnt(0)
	s_barrier
	s_setprio 1
	v_mfma_f32_16x16x32_bf16 v[158:161], v[26:29], v[34:37], v[158:161]
	v_mfma_f32_16x16x32_bf16 v[158:161], v[30:33], v[82:85], v[158:161]
	v_mfma_f32_16x16x32_bf16 v[154:157], v[50:53], v[82:85], v[154:157]
	v_mfma_f32_16x16x32_bf16 v[154:157], v[38:41], v[34:37], v[154:157]
	v_mfma_f32_16x16x32_bf16 v[138:141], v[38:41], v[86:89], v[138:141]
	v_mfma_f32_16x16x32_bf16 v[138:141], v[50:53], v[188:191], v[138:141]
	v_mfma_f32_16x16x32_bf16 v[142:145], v[30:33], v[188:191], v[142:145]
	v_mfma_f32_16x16x32_bf16 v[142:145], v[26:29], v[86:89], v[142:145]
	v_mfma_f32_16x16x32_bf16 v[126:129], v[26:29], v[192:195], v[126:129]
	v_mfma_f32_16x16x32_bf16 v[126:129], v[30:33], v[196:199], v[126:129]
	v_mfma_f32_16x16x32_bf16 v[122:125], v[50:53], v[196:199], v[122:125]
	v_mfma_f32_16x16x32_bf16 v[122:125], v[38:41], v[192:195], v[122:125]
	v_mfma_f32_16x16x32_bf16 v[106:109], v[38:41], v[200:203], v[106:109]
	v_mfma_f32_16x16x32_bf16 v[106:109], v[50:53], v[204:207], v[106:109]
	v_mfma_f32_16x16x32_bf16 v[110:113], v[30:33], v[204:207], v[110:113]
	v_mfma_f32_16x16x32_bf16 v[110:113], v[26:29], v[200:203], v[110:113]
	s_setprio 0
	s_setprio 1
	v_mfma_f32_16x16x32_bf16 v[150:153], v[54:57], v[34:37], v[150:153]
	v_mfma_f32_16x16x32_bf16 v[150:153], v[172:175], v[82:85], v[150:153]
	v_mfma_f32_16x16x32_bf16 v[34:37], v[176:179], v[34:37], v[146:149]
	v_mfma_f32_16x16x32_bf16 v[146:149], v[184:187], v[82:85], v[34:37]
	v_mfma_f32_16x16x32_bf16 v[34:37], v[54:57], v[86:89], v[134:137]
	v_mfma_f32_16x16x32_bf16 v[134:137], v[172:175], v[188:191], v[34:37]
	v_mfma_f32_16x16x32_bf16 v[34:37], v[176:179], v[86:89], v[130:133]
	v_mfma_f32_16x16x32_bf16 v[130:133], v[184:187], v[188:191], v[34:37]
	v_mfma_f32_16x16x32_bf16 v[34:37], v[54:57], v[192:195], v[118:121]
	v_mfma_f32_16x16x32_bf16 v[118:121], v[172:175], v[196:199], v[34:37]
	v_mfma_f32_16x16x32_bf16 v[34:37], v[176:179], v[192:195], v[114:117]
	v_mfma_f32_16x16x32_bf16 v[114:117], v[184:187], v[196:199], v[34:37]
	v_mfma_f32_16x16x32_bf16 v[34:37], v[54:57], v[200:203], v[102:105]
	v_mfma_f32_16x16x32_bf16 v[102:105], v[172:175], v[204:207], v[34:37]
	v_mfma_f32_16x16x32_bf16 v[34:37], v[176:179], v[200:203], v[98:101]
	v_mfma_f32_16x16x32_bf16 v[98:101], v[184:187], v[204:207], v[34:37]
	s_setprio 0
	s_barrier
	s_add_u32 s90, s88, 0x8000
	s_addc_u32 s91, s89, 0
	s_add_i32 s65, s65, s2
	s_nop 0
	s_mov_b32 m0, s65
	ds_read_b128 v[82:85], v183 offset:49152
	ds_read_b128 v[188:191], v183 offset:50176
	ds_read_b128 v[192:195], v183 offset:51200
	ds_read_b128 v[196:199], v183 offset:52224
	ds_read_b128 v[200:203], v183 offset:53248
	ds_read_b128 v[204:207], v183 offset:54272
	ds_read_b128 v[208:211], v183 offset:55296
	ds_read_b128 v[216:219], v183 offset:56320
	global_load_lds_dwordx4 v0, s[90:91]
	s_add_i32 m0, s65, 0x2000
	s_add_u32 s88, s88, 0xc000
	s_addc_u32 s89, s89, 0
	s_add_i32 s65, s66, s2
	global_load_lds_dwordx4 v162, s[90:91]
	s_mov_b32 m0, s65
	s_nop 0
	global_load_lds_dwordx4 v0, s[88:89]
	s_add_i32 m0, s65, 0x2000
	s_nop 0
	global_load_lds_dwordx4 v162, s[88:89]
	s_mov_b32 m0, s71
	s_nop 0
	global_load_lds_dwordx4 v166, s[86:87]
	v_lshl_add_u64 v[34:35], s[86:87], 0, v[164:165]
	s_mov_b32 m0, s80
	s_nop 0
	global_load_lds_dwordx4 v[34:35], off
	s_waitcnt vmcnt(8) lgkmcnt(0)
	s_barrier
	s_setprio 1
	v_mfma_f32_16x16x32_bf16 v[34:37], v[26:29], v[82:85], v[94:97]
	v_mfma_f32_16x16x32_bf16 v[94:97], v[30:33], v[188:191], v[34:37]
	v_mfma_f32_16x16x32_bf16 v[34:37], v[38:41], v[82:85], v[90:93]
	v_mfma_f32_16x16x32_bf16 v[90:93], v[50:53], v[188:191], v[34:37]
	v_mfma_f32_16x16x32_bf16 v[34:37], v[26:29], v[192:195], v[78:81]
	v_mfma_f32_16x16x32_bf16 v[78:81], v[30:33], v[196:199], v[34:37]
	v_mfma_f32_16x16x32_bf16 v[34:37], v[38:41], v[192:195], v[74:77]
	v_mfma_f32_16x16x32_bf16 v[74:77], v[50:53], v[196:199], v[34:37]
	v_mfma_f32_16x16x32_bf16 v[34:37], v[26:29], v[200:203], v[62:65]
	v_mfma_f32_16x16x32_bf16 v[62:65], v[30:33], v[204:207], v[34:37]
	v_mfma_f32_16x16x32_bf16 v[34:37], v[38:41], v[200:203], v[58:61]
	v_mfma_f32_16x16x32_bf16 v[58:61], v[50:53], v[204:207], v[34:37]
	v_mfma_f32_16x16x32_bf16 v[10:13], v[26:29], v[208:211], v[10:13]
	v_mfma_f32_16x16x32_bf16 v[34:37], v[30:33], v[216:219], v[10:13]
	v_mfma_f32_16x16x32_bf16 v[10:13], v[38:41], v[208:211], v[14:17]
	v_mfma_f32_16x16x32_bf16 v[30:33], v[50:53], v[216:219], v[10:13]
	s_setprio 0
	s_setprio 1
	v_mfma_f32_16x16x32_bf16 v[10:13], v[54:57], v[82:85], v[18:21]
	v_mfma_f32_16x16x32_bf16 v[86:89], v[172:175], v[188:191], v[10:13]
	v_mfma_f32_16x16x32_bf16 v[10:13], v[176:179], v[82:85], v[22:25]
	v_mfma_f32_16x16x32_bf16 v[82:85], v[184:187], v[188:191], v[10:13]
	v_mfma_f32_16x16x32_bf16 v[10:13], v[54:57], v[192:195], v[70:73]
	v_mfma_f32_16x16x32_bf16 v[70:73], v[172:175], v[196:199], v[10:13]
	v_mfma_f32_16x16x32_bf16 v[10:13], v[176:179], v[192:195], v[66:69]
	v_mfma_f32_16x16x32_bf16 v[66:69], v[184:187], v[196:199], v[10:13]
	v_mfma_f32_16x16x32_bf16 v[10:13], v[54:57], v[200:203], v[46:49]
	v_mfma_f32_16x16x32_bf16 v[46:49], v[172:175], v[204:207], v[10:13]
	v_mfma_f32_16x16x32_bf16 v[10:13], v[176:179], v[200:203], v[42:45]
	v_mfma_f32_16x16x32_bf16 v[42:45], v[184:187], v[204:207], v[10:13]
	v_mfma_f32_16x16x32_bf16 v[6:9], v[54:57], v[208:211], v[6:9]
	v_mfma_f32_16x16x32_bf16 v[6:9], v[172:175], v[216:219], v[6:9]
	v_mfma_f32_16x16x32_bf16 v[2:5], v[176:179], v[208:211], v[2:5]
	v_mfma_f32_16x16x32_bf16 v[2:5], v[184:187], v[216:219], v[2:5]
	s_setprio 0
	s_barrier
	s_add_i32 vcc_lo, vcc_lo, 2
	s_add_u32 s6, s6, 0x10000
	s_addc_u32 s7, s7, 0
	s_add_u32 s56, s56, 0x10000
	s_addc_u32 s57, s57, 0
	s_cmp_gt_u32 vcc_lo, 29
	s_cbranch_scc0 .LBB0_328
	s_and_b64 vcc, exec, s[26:27]
	s_cbranch_vccz .LBB0_331
	s_barrier

;     __host__ __device__ __forceinline__ bool next(int i, Unit& u) const { const int vv = vid + (i / 5) * G; if (vv >= 256) return false; u.pm = vv >> 2; u.pn = (vv & 3) + 4 * (i % 5); return true; }
; #define PG8_STAGE(bufoff, gbase, voff) do { _Pragma("unroll") for (int _i = 0; _i < 2; ++_i) \
;         __builtin_amdgcn_global_load_lds((const unsigned*)((const char*)(gbase) + (voff)[_i]), (PG8_LAS unsigned*)(lds + (bufoff) + ldsw + _i * 8192), 16, 0, 0); } while (0)
; #define PG8_LDA(dst, b, h) do { _Pragma("unroll") for (int m = 0; m < 4; ++m) _Pragma("unroll") for (int k = 0; k < 2; ++k) dst[m][k] = *(const PG8_LAS bf16x8*)(lds + PG8_SA(b, h) + aoff + m * 2048 + k * 1024); } while (0)
; #define PG8_LDB(dst, b, h) do { _Pragma("unroll") for (int n = 0; n < 2; ++n) _Pragma("unroll") for (int k = 0; k < 2; ++k) dst[n][k] = *(const PG8_LAS bf16x8*)(lds + PG8_SB(b, h) + boff + n * 2048 + k * 1024); } while (0)
; #define PG8_WAIT_V(n) asm volatile("s_waitcnt vmcnt(" #n ")" ::: "memory")
; #define PG8_WAIT_L(n) asm volatile("s_waitcnt lgkmcnt(" #n ")" ::: "memory")
; #define PG8_BAR __builtin_amdgcn_s_barrier()
;     ...
;         const bool has_next = S.next(ui + 1, nxt);
;         const char* nA = has_next ? (const char*)g.A + (size_t)nxt.pm * tstepA + (size_t)nxt.pn * APN + kofA : cA; const char* nB = has_next ? (const char*)g.Bt + (size_t)nxt.pn * tstepB + S.b_off(nxt) + kofB : cB;
;         for (int t = 0; t < nt; t += 2) {
;             const bool last = (t == nt - 2);
;             const char* a1 = cA + (ptrdiff_t)(t + 1) * kstepA;
;             const char* a2 = last ? nA : cA + (ptrdiff_t)(t + 2) * kstepA; const char* b2 = last ? nB : cB + (ptrdiff_t)(t + 2) * kstep;
;             const char* a3 = a2 + kstepA; const char* b3 = b2 + kstep;
;             if (last && has_next) S.a_ready(nxt);
;             if constexpr (SP2) {
;             PG8_LDB(B0, 0, 0); PG8_LDB(B1, 0, 1); PG8_SCHED; PG8_LDA(At, 0, 0); PG8_STAGE(PG8_SA(1, 1), a1 + hstepA, voffA);
;             PG8_WAIT_V(8); PG8_WAIT_L(0); PG8_BAR; PG8_MMA(0, 0, At, B0); PG8_MMA(0, 1, At, B1); PG8_BAR; PG8_SCHED;
;             PG8_LDA(At, 0, 1); PG8_STAGE(PG8_SB(0, 0), b2, voffB); PG8_STAGE(PG8_SB(0, 1), b2 + hstepB, voffB); PG8_STAGE(PG8_SA(0, 0), a2, voffA);
;             PG8_WAIT_V(8); PG8_WAIT_L(0); PG8_BAR; PG8_MMA(1, 0, At, B0); PG8_MMA(1, 1, At, B1); PG8_BAR; PG8_SCHED;
.Lout_nostg:
	s_add_u32 s36, s34, 0x4000
	s_addc_u32 s37, s35, 0
	s_cmp_eq_u32 s57, 28
	s_cselect_b32 s86, s29, s36
	s_cselect_b32 s87, s23, s37
	s_cselect_b32 s46, s31, s44
	s_cselect_b32 s47, s21, s56
	s_add_u32 s36, s86, 0x8000
	s_addc_u32 s37, s87, 0
	s_add_i32 s65, 0, 0x10000
	v_add_u32_e32 v0, s65, v242
	s_add_i32 s66, 0, 0x14000
	s_waitcnt lgkmcnt(0)
	ds_read_b128 v[130:133], v0
	ds_read_b128 v[134:137], v0 offset:1024
	ds_read_b128 v[138:141], v0 offset:2048
	ds_read_b128 v[142:145], v0 offset:3072
	v_add_u32_e32 v0, s66, v242
	ds_read_b128 v[146:149], v0
	ds_read_b128 v[150:153], v0 offset:1024
	ds_read_b128 v[154:157], v0 offset:2048
	ds_read_b128 v[158:161], v0 offset:3072
	s_add_i32 m0, s51, 0xc000
	ds_read_b128 v[162:165], v243
	ds_read_b128 v[166:169], v243 offset:1024
	ds_read_b128 v[170:173], v243 offset:2048
	ds_read_b128 v[174:177], v243 offset:3072
	ds_read_b128 v[178:181], v243 offset:4096
	ds_read_b128 v[182:185], v243 offset:5120
	ds_read_b128 v[198:201], v243 offset:6144
	ds_read_b128 v[202:205], v243 offset:7168
	global_load_lds_dwordx4 v194, s[34:35]
	s_add_i32 m0, s51, 0xe000
	s_nop 0
	global_load_lds_dwordx4 v196, s[34:35]
	s_waitcnt vmcnt(8) lgkmcnt(0)
	s_barrier
	s_setprio 1
	v_mfma_f32_16x16x32_bf16 v[126:129], v[130:133], v[162:165], 0
	v_mfma_f32_16x16x32_bf16 v[126:129], v[134:137], v[166:169], v[126:129]
	v_mfma_f32_16x16x32_bf16 v[122:125], v[142:145], v[166:169], 0
	v_mfma_f32_16x16x32_bf16 v[122:125], v[138:141], v[162:165], v[122:125]
	v_mfma_f32_16x16x32_bf16 v[106:109], v[138:141], v[170:173], 0
	v_mfma_f32_16x16x32_bf16 v[106:109], v[142:145], v[174:177], v[106:109]
	v_mfma_f32_16x16x32_bf16 v[110:113], v[134:137], v[174:177], 0
	v_mfma_f32_16x16x32_bf16 v[110:113], v[130:133], v[170:173], v[110:113]
	v_mfma_f32_16x16x32_bf16 v[94:97], v[130:133], v[178:181], 0
	v_mfma_f32_16x16x32_bf16 v[94:97], v[134:137], v[182:185], v[94:97]
	v_mfma_f32_16x16x32_bf16 v[90:93], v[142:145], v[182:185], 0
	v_mfma_f32_16x16x32_bf16 v[90:93], v[138:141], v[178:181], v[90:93]
	v_mfma_f32_16x16x32_bf16 v[74:77], v[138:141], v[198:201], 0
	v_mfma_f32_16x16x32_bf16 v[74:77], v[142:145], v[202:205], v[74:77]
	v_mfma_f32_16x16x32_bf16 v[78:81], v[134:137], v[202:205], 0
	v_mfma_f32_16x16x32_bf16 v[78:81], v[130:133], v[198:201], v[78:81]
	s_setprio 0
	s_setprio 1
	v_mfma_f32_16x16x32_bf16 v[118:121], v[146:149], v[162:165], 0
	v_mfma_f32_16x16x32_bf16 v[118:121], v[150:153], v[166:169], v[118:121]
	v_mfma_f32_16x16x32_bf16 v[114:117], v[158:161], v[166:169], 0
	v_mfma_f32_16x16x32_bf16 v[114:117], v[154:157], v[162:165], v[114:117]
	v_mfma_f32_16x16x32_bf16 v[98:101], v[154:157], v[170:173], 0
	v_mfma_f32_16x16x32_bf16 v[98:101], v[158:161], v[174:177], v[98:101]
	v_mfma_f32_16x16x32_bf16 v[102:105], v[150:153], v[174:177], 0
	v_mfma_f32_16x16x32_bf16 v[102:105], v[146:149], v[170:173], v[102:105]
	v_mfma_f32_16x16x32_bf16 v[86:89], v[146:149], v[178:181], 0
	v_mfma_f32_16x16x32_bf16 v[86:89], v[150:153], v[182:185], v[86:89]
	v_mfma_f32_16x16x32_bf16 v[82:85], v[158:161], v[182:185], 0
	v_mfma_f32_16x16x32_bf16 v[82:85], v[154:157], v[178:181], v[82:85]
	v_mfma_f32_16x16x32_bf16 v[66:69], v[154:157], v[198:201], 0
	v_mfma_f32_16x16x32_bf16 v[66:69], v[158:161], v[202:205], v[66:69]
	v_mfma_f32_16x16x32_bf16 v[70:73], v[150:153], v[202:205], 0
	v_mfma_f32_16x16x32_bf16 v[70:73], v[146:149], v[198:201], v[70:73]
	s_setprio 0
	s_barrier
	s_add_i32 s65, s65, s49
	s_mov_b32 m0, s65
	ds_read_b128 v[162:165], v243 offset:16384
	ds_read_b128 v[166:169], v243 offset:17408
	ds_read_b128 v[170:173], v243 offset:18432
	ds_read_b128 v[174:177], v243 offset:19456
	ds_read_b128 v[178:181], v243 offset:20480
	ds_read_b128 v[182:185], v243 offset:21504
	ds_read_b128 v[198:201], v243 offset:22528
	ds_read_b128 v[202:205], v243 offset:23552
	global_load_lds_dwordx4 v188, s[46:47]
	s_add_i32 m0, s65, 0x2000
	s_add_u32 s90, s46, 0x4000
	s_addc_u32 s91, s47, 0
	s_add_i32 s65, s66, s49
	global_load_lds_dwordx4 v192, s[46:47]
	s_mov_b32 m0, s65
	s_nop 0
	global_load_lds_dwordx4 v188, s[90:91]
	s_add_i32 m0, s65, 0x2000
	s_nop 0
	global_load_lds_dwordx4 v192, s[90:91]
	s_mov_b32 m0, s51
	s_nop 0
	global_load_lds_dwordx4 v186, s[86:87]
	s_mov_b32 m0, s54
	s_nop 0
	global_load_lds_dwordx4 v190, s[86:87]
	s_waitcnt vmcnt(8) lgkmcnt(0)
	s_barrier
	s_setprio 1
	v_mfma_f32_16x16x32_bf16 v[62:65], v[130:133], v[162:165], 0
	v_mfma_f32_16x16x32_bf16 v[62:65], v[134:137], v[166:169], v[62:65]
	v_mfma_f32_16x16x32_bf16 v[58:61], v[142:145], v[166:169], 0
	v_mfma_f32_16x16x32_bf16 v[58:61], v[138:141], v[162:165], v[58:61]
	v_mfma_f32_16x16x32_bf16 v[42:45], v[138:141], v[170:173], 0
	v_mfma_f32_16x16x32_bf16 v[42:45], v[142:145], v[174:177], v[42:45]
	v_mfma_f32_16x16x32_bf16 v[46:49], v[134:137], v[174:177], 0
	v_mfma_f32_16x16x32_bf16 v[46:49], v[130:133], v[170:173], v[46:49]
	v_mfma_f32_16x16x32_bf16 v[30:33], v[130:133], v[178:181], 0
	v_mfma_f32_16x16x32_bf16 v[30:33], v[134:137], v[182:185], v[30:33]
	v_mfma_f32_16x16x32_bf16 v[26:29], v[142:145], v[182:185], 0
	v_mfma_f32_16x16x32_bf16 v[26:29], v[138:141], v[178:181], v[26:29]
	v_mfma_f32_16x16x32_bf16 v[10:13], v[138:141], v[198:201], 0
	v_mfma_f32_16x16x32_bf16 v[10:13], v[142:145], v[202:205], v[10:13]
	v_mfma_f32_16x16x32_bf16 v[14:17], v[134:137], v[202:205], 0
	v_mfma_f32_16x16x32_bf16 v[14:17], v[130:133], v[198:201], v[14:17]
	s_setprio 0
	s_setprio 1
	v_mfma_f32_16x16x32_bf16 v[54:57], v[146:149], v[162:165], 0
	v_mfma_f32_16x16x32_bf16 v[54:57], v[150:153], v[166:169], v[54:57]
	v_mfma_f32_16x16x32_bf16 v[50:53], v[158:161], v[166:169], 0
	v_mfma_f32_16x16x32_bf16 v[50:53], v[154:157], v[162:165], v[50:53]
	v_mfma_f32_16x16x32_bf16 v[34:37], v[154:157], v[170:173], 0
	v_mfma_f32_16x16x32_bf16 v[34:37], v[158:161], v[174:177], v[34:37]
	v_mfma_f32_16x16x32_bf16 v[38:41], v[150:153], v[174:177], 0
	v_mfma_f32_16x16x32_bf16 v[38:41], v[146:149], v[170:173], v[38:41]
	v_mfma_f32_16x16x32_bf16 v[22:25], v[146:149], v[178:181], 0
	v_mfma_f32_16x16x32_bf16 v[22:25], v[150:153], v[182:185], v[22:25]
	v_mfma_f32_16x16x32_bf16 v[18:21], v[158:161], v[182:185], 0
	v_mfma_f32_16x16x32_bf16 v[18:21], v[154:157], v[178:181], v[18:21]
	v_mfma_f32_16x16x32_bf16 v[2:5], v[154:157], v[198:201], 0
	v_mfma_f32_16x16x32_bf16 v[2:5], v[158:161], v[202:205], v[2:5]
	v_mfma_f32_16x16x32_bf16 v[6:9], v[150:153], v[202:205], 0
	v_mfma_f32_16x16x32_bf16 v[6:9], v[146:149], v[198:201], v[6:9]
	s_setprio 0
	s_barrier
	s_branch .Lout_mid

; #define PG8_STAGE(bufoff, gbase, voff) do { _Pragma("unroll") for (int _i = 0; _i < 2; ++_i) \
;         __builtin_amdgcn_global_load_lds((const unsigned*)((const char*)(gbase) + (voff)[_i]), (PG8_LAS unsigned*)(lds + (bufoff) + ldsw + _i * 8192), 16, 0, 0); } while (0)
; #define PG8_LDA(dst, b, h) do { _Pragma("unroll") for (int m = 0; m < 4; ++m) _Pragma("unroll") for (int k = 0; k < 2; ++k) dst[m][k] = *(const PG8_LAS bf16x8*)(lds + PG8_SA(b, h) + aoff + m * 2048 + k * 1024); } while (0)
; #define PG8_LDB(dst, b, h) do { _Pragma("unroll") for (int n = 0; n < 2; ++n) _Pragma("unroll") for (int k = 0; k < 2; ++k) dst[n][k] = *(const PG8_LAS bf16x8*)(lds + PG8_SB(b, h) + boff + n * 2048 + k * 1024); } while (0)
; #define PG8_MMA(ai, bj, At, Bt) do { __builtin_amdgcn_s_setprio(1); _Pragma("unroll") for (int m = 0; m < 4; ++m) _Pragma("unroll") for (int n = 0; n < 2; ++n) _Pragma("unroll") for (int k = 0; k < 2; ++k) \
;         acc[ai][bj][m][n] = __builtin_amdgcn_mfma_f32_16x16x32_bf16(Bt[n][k], At[m][k], acc[ai][bj][m][n], 0, 0, 0); __builtin_amdgcn_s_setprio(0); } while (0)
; #define PG8_WAIT_V(n) asm volatile("s_waitcnt vmcnt(" #n ")" ::: "memory")
; #define PG8_WAIT_L(n) asm volatile("s_waitcnt lgkmcnt(" #n ")" ::: "memory")
; #define PG8_BAR __builtin_amdgcn_s_barrier()
; #define PG8_SCHED __builtin_amdgcn_sched_barrier(0)
;     ...
;             const bool last = (t == nt - 2);
;             const char* a1 = cA + (ptrdiff_t)(t + 1) * kstepA;
;             const char* a2 = last ? nA : cA + (ptrdiff_t)(t + 2) * kstepA; const char* b2 = last ? nB : cB + (ptrdiff_t)(t + 2) * kstep;
;             const char* a3 = a2 + kstepA; const char* b3 = b2 + kstep;
;             if (last && has_next) S.a_ready(nxt);
;             if constexpr (SP2) {
;             PG8_LDB(B0, 0, 0); PG8_LDB(B1, 0, 1); PG8_SCHED; PG8_LDA(At, 0, 0); PG8_STAGE(PG8_SA(1, 1), a1 + hstepA, voffA);
;             PG8_WAIT_V(8); PG8_WAIT_L(0); PG8_BAR; PG8_MMA(0, 0, At, B0); PG8_MMA(0, 1, At, B1); PG8_BAR; PG8_SCHED;
;             PG8_LDA(At, 0, 1); PG8_STAGE(PG8_SB(0, 0), b2, voffB); PG8_STAGE(PG8_SB(0, 1), b2 + hstepB, voffB); PG8_STAGE(PG8_SA(0, 0), a2, voffA);
;             PG8_WAIT_V(8); PG8_WAIT_L(0); PG8_BAR; PG8_MMA(1, 0, At, B0); PG8_MMA(1, 1, At, B1); PG8_BAR; PG8_SCHED;
.LBB0_1128:
	s_add_u32 s36, s34, 0x4000
	s_addc_u32 s37, s35, 0
	s_cmp_eq_u32 s57, 28
	s_cselect_b32 s86, s29, s36
	s_cselect_b32 s87, s23, s37
	s_cselect_b32 s46, s31, s44
	s_cselect_b32 s47, s21, s56
	s_add_u32 s36, s86, 0x8000
	s_addc_u32 s37, s87, 0
	s_add_i32 s65, 0, 0x10000
	v_add_u32_e32 v0, s65, v242
	s_add_i32 s66, 0, 0x14000
	s_waitcnt lgkmcnt(0)
	ds_read_b128 v[130:133], v0
	ds_read_b128 v[134:137], v0 offset:1024
	ds_read_b128 v[138:141], v0 offset:2048
	ds_read_b128 v[142:145], v0 offset:3072
	v_add_u32_e32 v0, s66, v242
	ds_read_b128 v[146:149], v0
	ds_read_b128 v[150:153], v0 offset:1024
	ds_read_b128 v[154:157], v0 offset:2048
	ds_read_b128 v[158:161], v0 offset:3072
	s_add_i32 m0, s51, 0xc000
	ds_read_b128 v[162:165], v243
	ds_read_b128 v[166:169], v243 offset:1024
	ds_read_b128 v[170:173], v243 offset:2048
	ds_read_b128 v[174:177], v243 offset:3072
	ds_read_b128 v[178:181], v243 offset:4096
	ds_read_b128 v[182:185], v243 offset:5120
	ds_read_b128 v[198:201], v243 offset:6144
	ds_read_b128 v[202:205], v243 offset:7168
	global_load_lds_dwordx4 v194, s[34:35]
	s_add_i32 m0, s51, 0xe000
	s_nop 0
	global_load_lds_dwordx4 v196, s[34:35]
	s_waitcnt vmcnt(8) lgkmcnt(0)
	s_barrier
	s_setprio 1
	v_mfma_f32_16x16x32_bf16 v[126:129], v[130:133], v[162:165], v[126:129]
	v_mfma_f32_16x16x32_bf16 v[126:129], v[134:137], v[166:169], v[126:129]
	v_mfma_f32_16x16x32_bf16 v[122:125], v[142:145], v[166:169], v[122:125]
	v_mfma_f32_16x16x32_bf16 v[122:125], v[138:141], v[162:165], v[122:125]
	v_mfma_f32_16x16x32_bf16 v[106:109], v[138:141], v[170:173], v[106:109]
	v_mfma_f32_16x16x32_bf16 v[106:109], v[142:145], v[174:177], v[106:109]
	v_mfma_f32_16x16x32_bf16 v[110:113], v[134:137], v[174:177], v[110:113]
	v_mfma_f32_16x16x32_bf16 v[110:113], v[130:133], v[170:173], v[110:113]
	v_mfma_f32_16x16x32_bf16 v[94:97], v[130:133], v[178:181], v[94:97]
	v_mfma_f32_16x16x32_bf16 v[94:97], v[134:137], v[182:185], v[94:97]
	v_mfma_f32_16x16x32_bf16 v[90:93], v[142:145], v[182:185], v[90:93]
	v_mfma_f32_16x16x32_bf16 v[90:93], v[138:141], v[178:181], v[90:93]
	v_mfma_f32_16x16x32_bf16 v[74:77], v[138:141], v[198:201], v[74:77]
	v_mfma_f32_16x16x32_bf16 v[74:77], v[142:145], v[202:205], v[74:77]
	v_mfma_f32_16x16x32_bf16 v[78:81], v[134:137], v[202:205], v[78:81]
	v_mfma_f32_16x16x32_bf16 v[78:81], v[130:133], v[198:201], v[78:81]
	s_setprio 0
	s_setprio 1
	v_mfma_f32_16x16x32_bf16 v[118:121], v[146:149], v[162:165], v[118:121]
	v_mfma_f32_16x16x32_bf16 v[118:121], v[150:153], v[166:169], v[118:121]
	v_mfma_f32_16x16x32_bf16 v[114:117], v[158:161], v[166:169], v[114:117]
	v_mfma_f32_16x16x32_bf16 v[114:117], v[154:157], v[162:165], v[114:117]
	v_mfma_f32_16x16x32_bf16 v[98:101], v[154:157], v[170:173], v[98:101]
	v_mfma_f32_16x16x32_bf16 v[98:101], v[158:161], v[174:177], v[98:101]
	v_mfma_f32_16x16x32_bf16 v[102:105], v[150:153], v[174:177], v[102:105]
	v_mfma_f32_16x16x32_bf16 v[102:105], v[146:149], v[170:173], v[102:105]
	v_mfma_f32_16x16x32_bf16 v[86:89], v[146:149], v[178:181], v[86:89]
	v_mfma_f32_16x16x32_bf16 v[86:89], v[150:153], v[182:185], v[86:89]
	v_mfma_f32_16x16x32_bf16 v[82:85], v[158:161], v[182:185], v[82:85]
	v_mfma_f32_16x16x32_bf16 v[82:85], v[154:157], v[178:181], v[82:85]
	v_mfma_f32_16x16x32_bf16 v[66:69], v[154:157], v[198:201], v[66:69]
	v_mfma_f32_16x16x32_bf16 v[66:69], v[158:161], v[202:205], v[66:69]
	v_mfma_f32_16x16x32_bf16 v[70:73], v[150:153], v[202:205], v[70:73]
	v_mfma_f32_16x16x32_bf16 v[70:73], v[146:149], v[198:201], v[70:73]
	s_setprio 0
	s_barrier
	s_add_i32 s65, s65, s49
	s_mov_b32 m0, s65
	ds_read_b128 v[162:165], v243 offset:16384
	ds_read_b128 v[166:169], v243 offset:17408
	ds_read_b128 v[170:173], v243 offset:18432
	ds_read_b128 v[174:177], v243 offset:19456
	ds_read_b128 v[178:181], v243 offset:20480
	ds_read_b128 v[182:185], v243 offset:21504
	ds_read_b128 v[198:201], v243 offset:22528
	ds_read_b128 v[202:205], v243 offset:23552
	global_load_lds_dwordx4 v188, s[46:47]
	s_add_i32 m0, s65, 0x2000
	s_add_u32 s90, s46, 0x4000
	s_addc_u32 s91, s47, 0
	s_add_i32 s65, s66, s49
	global_load_lds_dwordx4 v192, s[46:47]
	s_mov_b32 m0, s65
	s_nop 0
	global_load_lds_dwordx4 v188, s[90:91]
	s_add_i32 m0, s65, 0x2000
	s_nop 0
	global_load_lds_dwordx4 v192, s[90:91]
	s_mov_b32 m0, s51
	s_nop 0
	global_load_lds_dwordx4 v186, s[86:87]
	s_mov_b32 m0, s54
	s_nop 0
	global_load_lds_dwordx4 v190, s[86:87]
	s_waitcnt vmcnt(8) lgkmcnt(0)
	s_barrier
	s_setprio 1
	v_mfma_f32_16x16x32_bf16 v[62:65], v[130:133], v[162:165], v[62:65]
	v_mfma_f32_16x16x32_bf16 v[62:65], v[134:137], v[166:169], v[62:65]
	v_mfma_f32_16x16x32_bf16 v[58:61], v[142:145], v[166:169], v[58:61]
	v_mfma_f32_16x16x32_bf16 v[58:61], v[138:141], v[162:165], v[58:61]
	v_mfma_f32_16x16x32_bf16 v[42:45], v[138:141], v[170:173], v[42:45]
	v_mfma_f32_16x16x32_bf16 v[42:45], v[142:145], v[174:177], v[42:45]
	v_mfma_f32_16x16x32_bf16 v[46:49], v[134:137], v[174:177], v[46:49]
	v_mfma_f32_16x16x32_bf16 v[46:49], v[130:133], v[170:173], v[46:49]
	v_mfma_f32_16x16x32_bf16 v[30:33], v[130:133], v[178:181], v[30:33]
	v_mfma_f32_16x16x32_bf16 v[30:33], v[134:137], v[182:185], v[30:33]
	v_mfma_f32_16x16x32_bf16 v[26:29], v[142:145], v[182:185], v[26:29]
	v_mfma_f32_16x16x32_bf16 v[26:29], v[138:141], v[178:181], v[26:29]
	v_mfma_f32_16x16x32_bf16 v[10:13], v[138:141], v[198:201], v[10:13]
	v_mfma_f32_16x16x32_bf16 v[10:13], v[142:145], v[202:205], v[10:13]
	v_mfma_f32_16x16x32_bf16 v[14:17], v[134:137], v[202:205], v[14:17]
	v_mfma_f32_16x16x32_bf16 v[14:17], v[130:133], v[198:201], v[14:17]
	s_setprio 0
	s_setprio 1
	v_mfma_f32_16x16x32_bf16 v[54:57], v[146:149], v[162:165], v[54:57]
	v_mfma_f32_16x16x32_bf16 v[54:57], v[150:153], v[166:169], v[54:57]
	v_mfma_f32_16x16x32_bf16 v[50:53], v[158:161], v[166:169], v[50:53]
	v_mfma_f32_16x16x32_bf16 v[50:53], v[154:157], v[162:165], v[50:53]
	v_mfma_f32_16x16x32_bf16 v[34:37], v[154:157], v[170:173], v[34:37]
	v_mfma_f32_16x16x32_bf16 v[34:37], v[158:161], v[174:177], v[34:37]
	v_mfma_f32_16x16x32_bf16 v[38:41], v[150:153], v[174:177], v[38:41]
	v_mfma_f32_16x16x32_bf16 v[38:41], v[146:149], v[170:173], v[38:41]
	v_mfma_f32_16x16x32_bf16 v[22:25], v[146:149], v[178:181], v[22:25]
	v_mfma_f32_16x16x32_bf16 v[22:25], v[150:153], v[182:185], v[22:25]
	v_mfma_f32_16x16x32_bf16 v[18:21], v[158:161], v[182:185], v[18:21]
	v_mfma_f32_16x16x32_bf16 v[18:21], v[154:157], v[178:181], v[18:21]
	v_mfma_f32_16x16x32_bf16 v[2:5], v[154:157], v[198:201], v[2:5]
	v_mfma_f32_16x16x32_bf16 v[2:5], v[158:161], v[202:205], v[2:5]
	v_mfma_f32_16x16x32_bf16 v[6:9], v[150:153], v[202:205], v[6:9]
	v_mfma_f32_16x16x32_bf16 v[6:9], v[146:149], v[198:201], v[6:9]
	s_setprio 0
	s_barrier
; #define PG8_STAGE(bufoff, gbase, voff) do { _Pragma("unroll") for (int _i = 0; _i < 2; ++_i) \
;         __builtin_amdgcn_global_load_lds((const unsigned*)((const char*)(gbase) + (voff)[_i]), (PG8_LAS unsigned*)(lds + (bufoff) + ldsw + _i * 8192), 16, 0, 0); } while (0)
; #define PG8_LDA(dst, b, h) do { _Pragma("unroll") for (int m = 0; m < 4; ++m) _Pragma("unroll") for (int k = 0; k < 2; ++k) dst[m][k] = *(const PG8_LAS bf16x8*)(lds + PG8_SA(b, h) + aoff + m * 2048 + k * 1024); } while (0)
; #define PG8_LDB(dst, b, h) do { _Pragma("unroll") for (int n = 0; n < 2; ++n) _Pragma("unroll") for (int k = 0; k < 2; ++k) dst[n][k] = *(const PG8_LAS bf16x8*)(lds + PG8_SB(b, h) + boff + n * 2048 + k * 1024); } while (0)
; #define PG8_WAIT_V(n) asm volatile("s_waitcnt vmcnt(" #n ")" ::: "memory")
; #define PG8_WAIT_L(n) asm volatile("s_waitcnt lgkmcnt(" #n ")" ::: "memory")
; #define PG8_BAR __builtin_amdgcn_s_barrier()
; #define PG8_SCHED __builtin_amdgcn_sched_barrier(0)
;     ...
;             const char* a2 = last ? nA : cA + (ptrdiff_t)(t + 2) * kstepA; const char* b2 = last ? nB : cB + (ptrdiff_t)(t + 2) * kstep;
;             const char* a3 = a2 + kstepA; const char* b3 = b2 + kstep;
;             if (last && has_next) S.a_ready(nxt);
;             if constexpr (SP2) {
;             PG8_LDB(B0, 0, 0); PG8_LDB(B1, 0, 1); PG8_SCHED; PG8_LDA(At, 0, 0); PG8_STAGE(PG8_SA(1, 1), a1 + hstepA, voffA);
;             PG8_WAIT_V(8); PG8_WAIT_L(0); PG8_BAR; PG8_MMA(0, 0, At, B0); PG8_MMA(0, 1, At, B1); PG8_BAR; PG8_SCHED;
;             PG8_LDA(At, 0, 1); PG8_STAGE(PG8_SB(0, 0), b2, voffB); PG8_STAGE(PG8_SB(0, 1), b2 + hstepB, voffB); PG8_STAGE(PG8_SA(0, 0), a2, voffA);
;             PG8_WAIT_V(8); PG8_WAIT_L(0); PG8_BAR; PG8_MMA(1, 0, At, B0); PG8_MMA(1, 1, At, B1); PG8_BAR; PG8_SCHED;
;             PG8_LDB(B0, 1, 0); PG8_LDB(B1, 1, 1); PG8_SCHED; PG8_LDA(At, 1, 0); PG8_STAGE(PG8_SA(0, 1), a2 + hstepA, voffA);
;             PG8_WAIT_V(8); PG8_WAIT_L(0); PG8_BAR; PG8_MMA(0, 0, At, B0); PG8_MMA(0, 1, At, B1); PG8_BAR; PG8_SCHED;
;             PG8_LDA(At, 1, 1); PG8_STAGE(PG8_SB(1, 0), b3, voffB); PG8_STAGE(PG8_SB(1, 1), b3 + hstepB, voffB); PG8_STAGE(PG8_SA(1, 0), a3, voffA);
;             PG8_WAIT_V(8); PG8_WAIT_L(0); PG8_BAR; PG8_MMA(1, 0, At, B0); PG8_MMA(1, 1, At, B1); PG8_BAR; PG8_SCHED;
;     ...
;         if constexpr (ALIGN_EPI) { if (wr == 0) PG8_BAR; }
.Lout_mid:
	s_add_i32 s65, 0, 0x18000
	v_add_u32_e32 v0, s65, v242
	s_add_i32 s66, 0, 0x1c000
	ds_read_b128 v[130:133], v0
	ds_read_b128 v[134:137], v0 offset:1024
	ds_read_b128 v[138:141], v0 offset:2048
	ds_read_b128 v[142:145], v0 offset:3072
	v_add_u32_e32 v0, s66, v242
	ds_read_b128 v[146:149], v0
	ds_read_b128 v[150:153], v0 offset:1024
	ds_read_b128 v[154:157], v0 offset:2048
	ds_read_b128 v[158:161], v0 offset:3072
	s_add_u32 s86, s86, 0x4000
	s_addc_u32 s87, s87, 0
	s_mov_b32 m0, s55
	ds_read_b128 v[162:165], v243 offset:32768
	ds_read_b128 v[166:169], v243 offset:33792
	ds_read_b128 v[170:173], v243 offset:34816
	ds_read_b128 v[174:177], v243 offset:35840
	ds_read_b128 v[178:181], v243 offset:36864
	ds_read_b128 v[182:185], v243 offset:37888
	ds_read_b128 v[198:201], v243 offset:38912
	ds_read_b128 v[202:205], v243 offset:39936
	global_load_lds_dwordx4 v186, s[86:87]
	s_mov_b32 m0, s61
	s_nop 0
	global_load_lds_dwordx4 v190, s[86:87]
	s_waitcnt vmcnt(8) lgkmcnt(0)
	s_barrier
	s_setprio 1
	v_mfma_f32_16x16x32_bf16 v[126:129], v[130:133], v[162:165], v[126:129]
	v_mfma_f32_16x16x32_bf16 v[126:129], v[134:137], v[166:169], v[126:129]
	v_mfma_f32_16x16x32_bf16 v[122:125], v[142:145], v[166:169], v[122:125]
	v_mfma_f32_16x16x32_bf16 v[122:125], v[138:141], v[162:165], v[122:125]
	v_mfma_f32_16x16x32_bf16 v[106:109], v[138:141], v[170:173], v[106:109]
	v_mfma_f32_16x16x32_bf16 v[106:109], v[142:145], v[174:177], v[106:109]
	v_mfma_f32_16x16x32_bf16 v[110:113], v[134:137], v[174:177], v[110:113]
	v_mfma_f32_16x16x32_bf16 v[110:113], v[130:133], v[170:173], v[110:113]
	v_mfma_f32_16x16x32_bf16 v[94:97], v[130:133], v[178:181], v[94:97]
	v_mfma_f32_16x16x32_bf16 v[94:97], v[134:137], v[182:185], v[94:97]
	v_mfma_f32_16x16x32_bf16 v[90:93], v[142:145], v[182:185], v[90:93]
	v_mfma_f32_16x16x32_bf16 v[90:93], v[138:141], v[178:181], v[90:93]
	v_mfma_f32_16x16x32_bf16 v[74:77], v[138:141], v[198:201], v[74:77]
	v_mfma_f32_16x16x32_bf16 v[74:77], v[142:145], v[202:205], v[74:77]
	v_mfma_f32_16x16x32_bf16 v[78:81], v[134:137], v[202:205], v[78:81]
	v_mfma_f32_16x16x32_bf16 v[78:81], v[130:133], v[198:201], v[78:81]
	s_setprio 0
	s_setprio 1
	v_mfma_f32_16x16x32_bf16 v[118:121], v[146:149], v[162:165], v[118:121]
	v_mfma_f32_16x16x32_bf16 v[118:121], v[150:153], v[166:169], v[118:121]
	v_mfma_f32_16x16x32_bf16 v[114:117], v[158:161], v[166:169], v[114:117]
	v_mfma_f32_16x16x32_bf16 v[114:117], v[154:157], v[162:165], v[114:117]
	v_mfma_f32_16x16x32_bf16 v[98:101], v[154:157], v[170:173], v[98:101]
	v_mfma_f32_16x16x32_bf16 v[98:101], v[158:161], v[174:177], v[98:101]
	v_mfma_f32_16x16x32_bf16 v[102:105], v[150:153], v[174:177], v[102:105]
	v_mfma_f32_16x16x32_bf16 v[102:105], v[146:149], v[170:173], v[102:105]
	v_mfma_f32_16x16x32_bf16 v[86:89], v[146:149], v[178:181], v[86:89]
	v_mfma_f32_16x16x32_bf16 v[86:89], v[150:153], v[182:185], v[86:89]
	v_mfma_f32_16x16x32_bf16 v[82:85], v[158:161], v[182:185], v[82:85]
	v_mfma_f32_16x16x32_bf16 v[82:85], v[154:157], v[178:181], v[82:85]
	v_mfma_f32_16x16x32_bf16 v[66:69], v[154:157], v[198:201], v[66:69]
	v_mfma_f32_16x16x32_bf16 v[66:69], v[158:161], v[202:205], v[66:69]
	v_mfma_f32_16x16x32_bf16 v[70:73], v[150:153], v[202:205], v[70:73]
	v_mfma_f32_16x16x32_bf16 v[70:73], v[146:149], v[198:201], v[70:73]
	s_setprio 0
	s_barrier
	s_add_u32 s86, s46, 0x8000
	s_addc_u32 s87, s47, 0
	s_add_i32 s65, s65, s49
	s_mov_b32 m0, s65
	ds_read_b128 v[162:165], v243 offset:49152
	ds_read_b128 v[166:169], v243 offset:50176
	ds_read_b128 v[170:173], v243 offset:51200
	ds_read_b128 v[174:177], v243 offset:52224
	ds_read_b128 v[178:181], v243 offset:53248
	ds_read_b128 v[182:185], v243 offset:54272
	ds_read_b128 v[198:201], v243 offset:55296
	ds_read_b128 v[202:205], v243 offset:56320
	global_load_lds_dwordx4 v188, s[86:87]
	s_add_i32 m0, s65, 0x2000
	s_add_u32 s46, s46, 0xc000
	s_addc_u32 s47, s47, 0
	s_add_i32 s65, s66, s49
	global_load_lds_dwordx4 v192, s[86:87]
	s_mov_b32 m0, s65
	s_nop 0
	global_load_lds_dwordx4 v188, s[46:47]
	s_add_i32 m0, s65, 0x2000
	s_nop 0
	global_load_lds_dwordx4 v192, s[46:47]
	s_mov_b32 m0, s83
	s_nop 0
	global_load_lds_dwordx4 v186, s[36:37]
	v_lshl_add_u64 v[206:207], s[36:37], 0, v[190:191]
	s_mov_b32 m0, s85
	s_nop 0
	global_load_lds_dwordx4 v[206:207], off
	s_waitcnt vmcnt(8) lgkmcnt(0)
	s_barrier
	s_setprio 1
	v_mfma_f32_16x16x32_bf16 v[62:65], v[130:133], v[162:165], v[62:65]
	v_mfma_f32_16x16x32_bf16 v[62:65], v[134:137], v[166:169], v[62:65]
	v_mfma_f32_16x16x32_bf16 v[58:61], v[142:145], v[166:169], v[58:61]
	v_mfma_f32_16x16x32_bf16 v[58:61], v[138:141], v[162:165], v[58:61]
	v_mfma_f32_16x16x32_bf16 v[42:45], v[138:141], v[170:173], v[42:45]
	v_mfma_f32_16x16x32_bf16 v[42:45], v[142:145], v[174:177], v[42:45]
	v_mfma_f32_16x16x32_bf16 v[46:49], v[134:137], v[174:177], v[46:49]
	v_mfma_f32_16x16x32_bf16 v[46:49], v[130:133], v[170:173], v[46:49]
	v_mfma_f32_16x16x32_bf16 v[30:33], v[130:133], v[178:181], v[30:33]
	v_mfma_f32_16x16x32_bf16 v[30:33], v[134:137], v[182:185], v[30:33]
	v_mfma_f32_16x16x32_bf16 v[26:29], v[142:145], v[182:185], v[26:29]
	v_mfma_f32_16x16x32_bf16 v[26:29], v[138:141], v[178:181], v[26:29]
	v_mfma_f32_16x16x32_bf16 v[10:13], v[138:141], v[198:201], v[10:13]
	v_mfma_f32_16x16x32_bf16 v[10:13], v[142:145], v[202:205], v[10:13]
	v_mfma_f32_16x16x32_bf16 v[14:17], v[134:137], v[202:205], v[14:17]
	v_mfma_f32_16x16x32_bf16 v[14:17], v[130:133], v[198:201], v[14:17]
	s_setprio 0
	s_setprio 1
	v_mfma_f32_16x16x32_bf16 v[54:57], v[146:149], v[162:165], v[54:57]
	v_mfma_f32_16x16x32_bf16 v[54:57], v[150:153], v[166:169], v[54:57]
	v_mfma_f32_16x16x32_bf16 v[50:53], v[158:161], v[166:169], v[50:53]
	v_mfma_f32_16x16x32_bf16 v[50:53], v[154:157], v[162:165], v[50:53]
	v_mfma_f32_16x16x32_bf16 v[34:37], v[154:157], v[170:173], v[34:37]
	v_mfma_f32_16x16x32_bf16 v[34:37], v[158:161], v[174:177], v[34:37]
	v_mfma_f32_16x16x32_bf16 v[38:41], v[150:153], v[174:177], v[38:41]
	v_mfma_f32_16x16x32_bf16 v[38:41], v[146:149], v[170:173], v[38:41]
	v_mfma_f32_16x16x32_bf16 v[22:25], v[146:149], v[178:181], v[22:25]
	v_mfma_f32_16x16x32_bf16 v[22:25], v[150:153], v[182:185], v[22:25]
	v_mfma_f32_16x16x32_bf16 v[18:21], v[158:161], v[182:185], v[18:21]
	v_mfma_f32_16x16x32_bf16 v[18:21], v[154:157], v[178:181], v[18:21]
	v_mfma_f32_16x16x32_bf16 v[2:5], v[154:157], v[198:201], v[2:5]
	v_mfma_f32_16x16x32_bf16 v[2:5], v[158:161], v[202:205], v[2:5]
	v_mfma_f32_16x16x32_bf16 v[6:9], v[150:153], v[202:205], v[6:9]
	v_mfma_f32_16x16x32_bf16 v[6:9], v[146:149], v[198:201], v[6:9]
	s_setprio 0
	s_barrier
	s_add_i32 s57, s57, 2
	s_add_u32 s34, s34, 0x10000
	s_addc_u32 s35, s35, 0
	s_add_u32 s44, s44, 0x10000
	s_addc_u32 s56, s56, 0
	s_cmp_gt_u32 s57, 29
	s_cbranch_scc0 .LBB0_1128
	s_and_b64 vcc, exec, s[92:93]
	s_cbranch_vccz .LBB0_1131
	s_barrier

;     __host__ __device__ __forceinline__ bool next(int i, Unit& u) const { const int vv = vid + (i / 5) * G; if (vv >= 256) return false; u.pm = vv >> 2; u.pn = (vv & 3) + 4 * (i % 5); return true; }
; #define PG8_STAGE(bufoff, gbase, voff) do { _Pragma("unroll") for (int _i = 0; _i < 2; ++_i) \
;         __builtin_amdgcn_global_load_lds((const unsigned*)((const char*)(gbase) + (voff)[_i]), (PG8_LAS unsigned*)(lds + (bufoff) + ldsw + _i * 8192), 16, 0, 0); } while (0)
; #define PG8_LDA(dst, b, h) do { _Pragma("unroll") for (int m = 0; m < 4; ++m) _Pragma("unroll") for (int k = 0; k < 2; ++k) dst[m][k] = *(const PG8_LAS bf16x8*)(lds + PG8_SA(b, h) + aoff + m * 2048 + k * 1024); } while (0)
; #define PG8_LDB(dst, b, h) do { _Pragma("unroll") for (int n = 0; n < 2; ++n) _Pragma("unroll") for (int k = 0; k < 2; ++k) dst[n][k] = *(const PG8_LAS bf16x8*)(lds + PG8_SB(b, h) + boff + n * 2048 + k * 1024); } while (0)
; #define PG8_WAIT_V(n) asm volatile("s_waitcnt vmcnt(" #n ")" ::: "memory")
; #define PG8_WAIT_L(n) asm volatile("s_waitcnt lgkmcnt(" #n ")" ::: "memory")
; #define PG8_BAR __builtin_amdgcn_s_barrier()
;     ...
;         const bool has_next = S.next(ui + 1, nxt);
;         const char* nA = has_next ? (const char*)g.A + (size_t)nxt.pm * tstepA + (size_t)nxt.pn * APN + kofA : cA; const char* nB = has_next ? (const char*)g.Bt + (size_t)nxt.pn * tstepB + S.b_off(nxt) + kofB : cB;
;         for (int t = 0; t < nt; t += 2) {
;             const bool last = (t == nt - 2);
;             const char* a1 = cA + (ptrdiff_t)(t + 1) * kstepA;
;             const char* a2 = last ? nA : cA + (ptrdiff_t)(t + 2) * kstepA; const char* b2 = last ? nB : cB + (ptrdiff_t)(t + 2) * kstep;
;             const char* a3 = a2 + kstepA; const char* b3 = b2 + kstep;
;             if (last && has_next) S.a_ready(nxt);
;             if constexpr (SP2) {
;             PG8_LDB(B0, 0, 0); PG8_LDB(B1, 0, 1); PG8_SCHED; PG8_LDA(At, 0, 0); PG8_STAGE(PG8_SA(1, 1), a1 + hstepA, voffA);
;             PG8_WAIT_V(8); PG8_WAIT_L(0); PG8_BAR; PG8_MMA(0, 0, At, B0); PG8_MMA(0, 1, At, B1); PG8_BAR; PG8_SCHED;
;             PG8_LDA(At, 0, 1); PG8_STAGE(PG8_SB(0, 0), b2, voffB); PG8_STAGE(PG8_SB(0, 1), b2 + hstepB, voffB); PG8_STAGE(PG8_SA(0, 0), a2, voffA);
;             PG8_WAIT_V(8); PG8_WAIT_L(0); PG8_BAR; PG8_MMA(1, 0, At, B0); PG8_MMA(1, 1, At, B1); PG8_BAR; PG8_SCHED;
.Lup_nostg:
	s_add_u32 s36, s34, 0x10000
	s_addc_u32 s37, s35, 0
	s_cmp_eq_u32 s66, 28
	s_cselect_b32 s88, s57, s36
	s_cselect_b32 s89, s27, s37
	s_cselect_b32 s86, vcc_lo, vcc_hi
	s_cselect_b32 s87, s25, s65
	s_add_u32 s46, s88, 0x8000
	s_addc_u32 s47, s89, 0
	s_add_i32 s96, 0, 0x10000
	v_add_u32_e32 v0, s96, v192
	s_add_i32 s97, 0, 0x14000
	ds_read_b128 v[130:133], v0
	ds_read_b128 v[134:137], v0 offset:1024
	ds_read_b128 v[138:141], v0 offset:2048
	ds_read_b128 v[142:145], v0 offset:3072
	v_add_u32_e32 v0, s97, v192
	ds_read_b128 v[146:149], v0
	ds_read_b128 v[150:153], v0 offset:1024
	ds_read_b128 v[154:157], v0 offset:2048
	ds_read_b128 v[170:173], v0 offset:3072
	s_add_i32 m0, s48, 0xc000
	ds_read_b128 v[174:177], v193
	ds_read_b128 v[178:181], v193 offset:1024
	ds_read_b128 v[182:185], v193 offset:2048
	ds_read_b128 v[186:189], v193 offset:3072
	ds_read_b128 v[194:197], v193 offset:4096
	ds_read_b128 v[198:201], v193 offset:5120
	ds_read_b128 v[202:205], v193 offset:6144
	ds_read_b128 v[206:209], v193 offset:7168
	global_load_lds_dwordx4 v166, s[34:35]
	s_add_i32 m0, s48, 0xe000
	s_nop 0
	global_load_lds_dwordx4 v168, s[34:35]
	s_waitcnt vmcnt(8) lgkmcnt(0)
	s_barrier
	s_setprio 1
	v_mfma_f32_16x16x32_bf16 v[126:129], v[130:133], v[174:177], 0
	v_mfma_f32_16x16x32_bf16 v[126:129], v[134:137], v[178:181], v[126:129]
	v_mfma_f32_16x16x32_bf16 v[122:125], v[142:145], v[178:181], 0
	v_mfma_f32_16x16x32_bf16 v[122:125], v[138:141], v[174:177], v[122:125]
	v_mfma_f32_16x16x32_bf16 v[114:117], v[138:141], v[182:185], 0
	v_mfma_f32_16x16x32_bf16 v[114:117], v[142:145], v[186:189], v[114:117]
	v_mfma_f32_16x16x32_bf16 v[118:121], v[134:137], v[186:189], 0
	v_mfma_f32_16x16x32_bf16 v[118:121], v[130:133], v[182:185], v[118:121]
	v_mfma_f32_16x16x32_bf16 v[110:113], v[130:133], v[194:197], 0
	v_mfma_f32_16x16x32_bf16 v[110:113], v[134:137], v[198:201], v[110:113]
	v_mfma_f32_16x16x32_bf16 v[106:109], v[142:145], v[198:201], 0
	v_mfma_f32_16x16x32_bf16 v[106:109], v[138:141], v[194:197], v[106:109]
	v_mfma_f32_16x16x32_bf16 v[98:101], v[138:141], v[202:205], 0
	v_mfma_f32_16x16x32_bf16 v[98:101], v[142:145], v[206:209], v[98:101]
	v_mfma_f32_16x16x32_bf16 v[102:105], v[134:137], v[206:209], 0
	v_mfma_f32_16x16x32_bf16 v[102:105], v[130:133], v[202:205], v[102:105]
	s_setprio 0
	s_setprio 1
	v_mfma_f32_16x16x32_bf16 v[30:33], v[146:149], v[174:177], 0
	v_mfma_f32_16x16x32_bf16 v[30:33], v[150:153], v[178:181], v[30:33]
	v_mfma_f32_16x16x32_bf16 v[46:49], v[170:173], v[178:181], 0
	v_mfma_f32_16x16x32_bf16 v[46:49], v[154:157], v[174:177], v[46:49]
	v_mfma_f32_16x16x32_bf16 v[34:37], v[154:157], v[182:185], 0
	v_mfma_f32_16x16x32_bf16 v[34:37], v[170:173], v[186:189], v[34:37]
	v_mfma_f32_16x16x32_bf16 v[26:29], v[150:153], v[186:189], 0
	v_mfma_f32_16x16x32_bf16 v[26:29], v[146:149], v[182:185], v[26:29]
	v_mfma_f32_16x16x32_bf16 v[94:97], v[146:149], v[194:197], 0
	v_mfma_f32_16x16x32_bf16 v[94:97], v[150:153], v[198:201], v[94:97]
	v_mfma_f32_16x16x32_bf16 v[90:93], v[170:173], v[198:201], 0
	v_mfma_f32_16x16x32_bf16 v[90:93], v[154:157], v[194:197], v[90:93]
	v_mfma_f32_16x16x32_bf16 v[82:85], v[154:157], v[202:205], 0
	v_mfma_f32_16x16x32_bf16 v[82:85], v[170:173], v[206:209], v[82:85]
	v_mfma_f32_16x16x32_bf16 v[86:89], v[150:153], v[206:209], 0
	v_mfma_f32_16x16x32_bf16 v[86:89], v[146:149], v[202:205], v[86:89]
	s_setprio 0
	s_barrier
	s_add_i32 s34, s96, s44
	s_mov_b32 m0, s34
	ds_read_b128 v[174:177], v193 offset:16384
	ds_read_b128 v[178:181], v193 offset:17408
	ds_read_b128 v[182:185], v193 offset:18432
	ds_read_b128 v[186:189], v193 offset:19456
	ds_read_b128 v[194:197], v193 offset:20480
	ds_read_b128 v[198:201], v193 offset:21504
	ds_read_b128 v[202:205], v193 offset:22528
	ds_read_b128 v[206:209], v193 offset:23552
	global_load_lds_dwordx4 v162, s[86:87]
	s_add_i32 m0, s34, 0x2000
	s_add_u32 s34, s86, 0x4000
	s_addc_u32 s35, s87, 0
	s_add_i32 s96, s97, s44
	global_load_lds_dwordx4 v158, s[86:87]
	s_mov_b32 m0, s96
	v_lshl_add_u64 v[210:211], s[88:89], 0, v[160:161]
	global_load_lds_dwordx4 v162, s[34:35]
	s_add_i32 m0, s96, 0x2000
	s_nop 0
	global_load_lds_dwordx4 v158, s[34:35]
	v_lshl_add_u64 v[190:191], s[88:89], 0, v[164:165]
	s_mov_b32 m0, s48
	s_nop 0
	global_load_lds_dwordx4 v[190:191], off
	s_mov_b32 m0, s49
	s_nop 0
	global_load_lds_dwordx4 v[210:211], off
	s_waitcnt vmcnt(8) lgkmcnt(0)
	s_barrier
	s_setprio 1
	v_mfma_f32_16x16x32_bf16 v[78:81], v[130:133], v[174:177], 0
	v_mfma_f32_16x16x32_bf16 v[78:81], v[134:137], v[178:181], v[78:81]
	v_mfma_f32_16x16x32_bf16 v[74:77], v[142:145], v[178:181], 0
	v_mfma_f32_16x16x32_bf16 v[74:77], v[138:141], v[174:177], v[74:77]
	v_mfma_f32_16x16x32_bf16 v[66:69], v[138:141], v[182:185], 0
	v_mfma_f32_16x16x32_bf16 v[66:69], v[142:145], v[186:189], v[66:69]
	v_mfma_f32_16x16x32_bf16 v[70:73], v[134:137], v[186:189], 0
	v_mfma_f32_16x16x32_bf16 v[70:73], v[130:133], v[182:185], v[70:73]
	v_mfma_f32_16x16x32_bf16 v[42:45], v[130:133], v[194:197], 0
	v_mfma_f32_16x16x32_bf16 v[42:45], v[134:137], v[198:201], v[42:45]
	v_mfma_f32_16x16x32_bf16 v[6:9], v[142:145], v[198:201], 0
	v_mfma_f32_16x16x32_bf16 v[6:9], v[138:141], v[194:197], v[6:9]
	v_mfma_f32_16x16x32_bf16 v[2:5], v[138:141], v[202:205], 0
	v_mfma_f32_16x16x32_bf16 v[2:5], v[142:145], v[206:209], v[2:5]
	v_mfma_f32_16x16x32_bf16 v[38:41], v[134:137], v[206:209], 0
	v_mfma_f32_16x16x32_bf16 v[38:41], v[130:133], v[202:205], v[38:41]
	s_setprio 0
	s_setprio 1
	v_mfma_f32_16x16x32_bf16 v[62:65], v[146:149], v[174:177], 0
	v_mfma_f32_16x16x32_bf16 v[62:65], v[150:153], v[178:181], v[62:65]
	v_mfma_f32_16x16x32_bf16 v[58:61], v[170:173], v[178:181], 0
	v_mfma_f32_16x16x32_bf16 v[58:61], v[154:157], v[174:177], v[58:61]
	v_mfma_f32_16x16x32_bf16 v[50:53], v[154:157], v[182:185], 0
	v_mfma_f32_16x16x32_bf16 v[50:53], v[170:173], v[186:189], v[50:53]
	v_mfma_f32_16x16x32_bf16 v[54:57], v[150:153], v[186:189], 0
	v_mfma_f32_16x16x32_bf16 v[54:57], v[146:149], v[182:185], v[54:57]
	v_mfma_f32_16x16x32_bf16 v[22:25], v[146:149], v[194:197], 0
	v_mfma_f32_16x16x32_bf16 v[22:25], v[150:153], v[198:201], v[22:25]
	v_mfma_f32_16x16x32_bf16 v[18:21], v[170:173], v[198:201], 0
	v_mfma_f32_16x16x32_bf16 v[18:21], v[154:157], v[194:197], v[18:21]
	v_mfma_f32_16x16x32_bf16 v[10:13], v[154:157], v[202:205], 0
	v_mfma_f32_16x16x32_bf16 v[10:13], v[170:173], v[206:209], v[10:13]
	v_mfma_f32_16x16x32_bf16 v[14:17], v[150:153], v[206:209], 0
	v_mfma_f32_16x16x32_bf16 v[14:17], v[146:149], v[202:205], v[14:17]
	s_setprio 0
	s_barrier
	s_branch .Lup_mid

; #define PG8_STAGE(bufoff, gbase, voff) do { _Pragma("unroll") for (int _i = 0; _i < 2; ++_i) \
;         __builtin_amdgcn_global_load_lds((const unsigned*)((const char*)(gbase) + (voff)[_i]), (PG8_LAS unsigned*)(lds + (bufoff) + ldsw + _i * 8192), 16, 0, 0); } while (0)
; #define PG8_LDA(dst, b, h) do { _Pragma("unroll") for (int m = 0; m < 4; ++m) _Pragma("unroll") for (int k = 0; k < 2; ++k) dst[m][k] = *(const PG8_LAS bf16x8*)(lds + PG8_SA(b, h) + aoff + m * 2048 + k * 1024); } while (0)
; #define PG8_LDB(dst, b, h) do { _Pragma("unroll") for (int n = 0; n < 2; ++n) _Pragma("unroll") for (int k = 0; k < 2; ++k) dst[n][k] = *(const PG8_LAS bf16x8*)(lds + PG8_SB(b, h) + boff + n * 2048 + k * 1024); } while (0)
; #define PG8_MMA(ai, bj, At, Bt) do { __builtin_amdgcn_s_setprio(1); _Pragma("unroll") for (int m = 0; m < 4; ++m) _Pragma("unroll") for (int n = 0; n < 2; ++n) _Pragma("unroll") for (int k = 0; k < 2; ++k) \
;         acc[ai][bj][m][n] = __builtin_amdgcn_mfma_f32_16x16x32_bf16(Bt[n][k], At[m][k], acc[ai][bj][m][n], 0, 0, 0); __builtin_amdgcn_s_setprio(0); } while (0)
; #define PG8_WAIT_V(n) asm volatile("s_waitcnt vmcnt(" #n ")" ::: "memory")
; #define PG8_WAIT_L(n) asm volatile("s_waitcnt lgkmcnt(" #n ")" ::: "memory")
; #define PG8_BAR __builtin_amdgcn_s_barrier()
; #define PG8_SCHED __builtin_amdgcn_sched_barrier(0)
;     ...
;             const bool last = (t == nt - 2);
;             const char* a1 = cA + (ptrdiff_t)(t + 1) * kstepA;
;             const char* a2 = last ? nA : cA + (ptrdiff_t)(t + 2) * kstepA; const char* b2 = last ? nB : cB + (ptrdiff_t)(t + 2) * kstep;
;             const char* a3 = a2 + kstepA; const char* b3 = b2 + kstep;
;             if (last && has_next) S.a_ready(nxt);
;             if constexpr (SP2) {
;             PG8_LDB(B0, 0, 0); PG8_LDB(B1, 0, 1); PG8_SCHED; PG8_LDA(At, 0, 0); PG8_STAGE(PG8_SA(1, 1), a1 + hstepA, voffA);
;             PG8_WAIT_V(8); PG8_WAIT_L(0); PG8_BAR; PG8_MMA(0, 0, At, B0); PG8_MMA(0, 1, At, B1); PG8_BAR; PG8_SCHED;
;             PG8_LDA(At, 0, 1); PG8_STAGE(PG8_SB(0, 0), b2, voffB); PG8_STAGE(PG8_SB(0, 1), b2 + hstepB, voffB); PG8_STAGE(PG8_SA(0, 0), a2, voffA);
;             PG8_WAIT_V(8); PG8_WAIT_L(0); PG8_BAR; PG8_MMA(1, 0, At, B0); PG8_MMA(1, 1, At, B1); PG8_BAR; PG8_SCHED;
.LBB0_1256:
	s_add_u32 s36, s34, 0x10000
	s_addc_u32 s37, s35, 0
	s_cmp_eq_u32 s66, 28
	s_cselect_b32 s88, s57, s36
	s_cselect_b32 s89, s27, s37
	s_cselect_b32 s86, vcc_lo, vcc_hi
	s_cselect_b32 s87, s25, s65
	s_add_u32 s46, s88, 0x8000
	s_addc_u32 s47, s89, 0
	s_add_i32 s96, 0, 0x10000
	v_add_u32_e32 v0, s96, v192
	s_add_i32 s97, 0, 0x14000
	ds_read_b128 v[130:133], v0
	ds_read_b128 v[134:137], v0 offset:1024
	ds_read_b128 v[138:141], v0 offset:2048
	ds_read_b128 v[142:145], v0 offset:3072
	v_add_u32_e32 v0, s97, v192
	ds_read_b128 v[146:149], v0
	ds_read_b128 v[150:153], v0 offset:1024
	ds_read_b128 v[154:157], v0 offset:2048
	ds_read_b128 v[170:173], v0 offset:3072
	s_add_i32 m0, s48, 0xc000
	ds_read_b128 v[174:177], v193
	ds_read_b128 v[178:181], v193 offset:1024
	ds_read_b128 v[182:185], v193 offset:2048
	ds_read_b128 v[186:189], v193 offset:3072
	ds_read_b128 v[194:197], v193 offset:4096
	ds_read_b128 v[198:201], v193 offset:5120
	ds_read_b128 v[202:205], v193 offset:6144
	ds_read_b128 v[206:209], v193 offset:7168
	global_load_lds_dwordx4 v166, s[34:35]
	s_add_i32 m0, s48, 0xe000
	s_nop 0
	global_load_lds_dwordx4 v168, s[34:35]
	s_waitcnt vmcnt(8) lgkmcnt(0)
	s_barrier
	s_setprio 1
	v_mfma_f32_16x16x32_bf16 v[126:129], v[130:133], v[174:177], v[126:129]
	v_mfma_f32_16x16x32_bf16 v[126:129], v[134:137], v[178:181], v[126:129]
	v_mfma_f32_16x16x32_bf16 v[122:125], v[142:145], v[178:181], v[122:125]
	v_mfma_f32_16x16x32_bf16 v[122:125], v[138:141], v[174:177], v[122:125]
	v_mfma_f32_16x16x32_bf16 v[114:117], v[138:141], v[182:185], v[114:117]
	v_mfma_f32_16x16x32_bf16 v[114:117], v[142:145], v[186:189], v[114:117]
	v_mfma_f32_16x16x32_bf16 v[118:121], v[134:137], v[186:189], v[118:121]
	v_mfma_f32_16x16x32_bf16 v[118:121], v[130:133], v[182:185], v[118:121]
	v_mfma_f32_16x16x32_bf16 v[110:113], v[130:133], v[194:197], v[110:113]
	v_mfma_f32_16x16x32_bf16 v[110:113], v[134:137], v[198:201], v[110:113]
	v_mfma_f32_16x16x32_bf16 v[106:109], v[142:145], v[198:201], v[106:109]
	v_mfma_f32_16x16x32_bf16 v[106:109], v[138:141], v[194:197], v[106:109]
	v_mfma_f32_16x16x32_bf16 v[98:101], v[138:141], v[202:205], v[98:101]
	v_mfma_f32_16x16x32_bf16 v[98:101], v[142:145], v[206:209], v[98:101]
	v_mfma_f32_16x16x32_bf16 v[102:105], v[134:137], v[206:209], v[102:105]
	v_mfma_f32_16x16x32_bf16 v[102:105], v[130:133], v[202:205], v[102:105]
	s_setprio 0
	s_setprio 1
	v_mfma_f32_16x16x32_bf16 v[30:33], v[146:149], v[174:177], v[30:33]
	v_mfma_f32_16x16x32_bf16 v[30:33], v[150:153], v[178:181], v[30:33]
	v_mfma_f32_16x16x32_bf16 v[46:49], v[170:173], v[178:181], v[46:49]
	v_mfma_f32_16x16x32_bf16 v[46:49], v[154:157], v[174:177], v[46:49]
	v_mfma_f32_16x16x32_bf16 v[34:37], v[154:157], v[182:185], v[34:37]
	v_mfma_f32_16x16x32_bf16 v[34:37], v[170:173], v[186:189], v[34:37]
	v_mfma_f32_16x16x32_bf16 v[26:29], v[150:153], v[186:189], v[26:29]
	v_mfma_f32_16x16x32_bf16 v[26:29], v[146:149], v[182:185], v[26:29]
	v_mfma_f32_16x16x32_bf16 v[94:97], v[146:149], v[194:197], v[94:97]
	v_mfma_f32_16x16x32_bf16 v[94:97], v[150:153], v[198:201], v[94:97]
	v_mfma_f32_16x16x32_bf16 v[90:93], v[170:173], v[198:201], v[90:93]
	v_mfma_f32_16x16x32_bf16 v[90:93], v[154:157], v[194:197], v[90:93]
	v_mfma_f32_16x16x32_bf16 v[82:85], v[154:157], v[202:205], v[82:85]
	v_mfma_f32_16x16x32_bf16 v[82:85], v[170:173], v[206:209], v[82:85]
	v_mfma_f32_16x16x32_bf16 v[86:89], v[150:153], v[206:209], v[86:89]
	v_mfma_f32_16x16x32_bf16 v[86:89], v[146:149], v[202:205], v[86:89]
	s_setprio 0
	s_barrier
	s_add_i32 s34, s96, s44
	s_mov_b32 m0, s34
	ds_read_b128 v[174:177], v193 offset:16384
	ds_read_b128 v[178:181], v193 offset:17408
	ds_read_b128 v[182:185], v193 offset:18432
	ds_read_b128 v[186:189], v193 offset:19456
	ds_read_b128 v[194:197], v193 offset:20480
	ds_read_b128 v[198:201], v193 offset:21504
	ds_read_b128 v[202:205], v193 offset:22528
	ds_read_b128 v[206:209], v193 offset:23552
	global_load_lds_dwordx4 v162, s[86:87]
	s_add_i32 m0, s34, 0x2000
	s_add_u32 s34, s86, 0x4000
	s_addc_u32 s35, s87, 0
	s_add_i32 s96, s97, s44
	global_load_lds_dwordx4 v158, s[86:87]
	s_mov_b32 m0, s96
	v_lshl_add_u64 v[210:211], s[88:89], 0, v[160:161]
	global_load_lds_dwordx4 v162, s[34:35]
	s_add_i32 m0, s96, 0x2000
	s_nop 0
	global_load_lds_dwordx4 v158, s[34:35]
	v_lshl_add_u64 v[190:191], s[88:89], 0, v[164:165]
	s_mov_b32 m0, s48
	s_nop 0
	global_load_lds_dwordx4 v[190:191], off
	s_mov_b32 m0, s49
	s_nop 0
	global_load_lds_dwordx4 v[210:211], off
	s_waitcnt vmcnt(8) lgkmcnt(0)
	s_barrier
	s_setprio 1
	v_mfma_f32_16x16x32_bf16 v[78:81], v[130:133], v[174:177], v[78:81]
	v_mfma_f32_16x16x32_bf16 v[78:81], v[134:137], v[178:181], v[78:81]
	v_mfma_f32_16x16x32_bf16 v[74:77], v[142:145], v[178:181], v[74:77]
	v_mfma_f32_16x16x32_bf16 v[74:77], v[138:141], v[174:177], v[74:77]
	v_mfma_f32_16x16x32_bf16 v[66:69], v[138:141], v[182:185], v[66:69]
	v_mfma_f32_16x16x32_bf16 v[66:69], v[142:145], v[186:189], v[66:69]
	v_mfma_f32_16x16x32_bf16 v[70:73], v[134:137], v[186:189], v[70:73]
	v_mfma_f32_16x16x32_bf16 v[70:73], v[130:133], v[182:185], v[70:73]
	v_mfma_f32_16x16x32_bf16 v[42:45], v[130:133], v[194:197], v[42:45]
	v_mfma_f32_16x16x32_bf16 v[42:45], v[134:137], v[198:201], v[42:45]
	v_mfma_f32_16x16x32_bf16 v[6:9], v[142:145], v[198:201], v[6:9]
	v_mfma_f32_16x16x32_bf16 v[6:9], v[138:141], v[194:197], v[6:9]
	v_mfma_f32_16x16x32_bf16 v[2:5], v[138:141], v[202:205], v[2:5]
	v_mfma_f32_16x16x32_bf16 v[2:5], v[142:145], v[206:209], v[2:5]
	v_mfma_f32_16x16x32_bf16 v[38:41], v[134:137], v[206:209], v[38:41]
	v_mfma_f32_16x16x32_bf16 v[38:41], v[130:133], v[202:205], v[38:41]
	s_setprio 0
	s_setprio 1
	v_mfma_f32_16x16x32_bf16 v[62:65], v[146:149], v[174:177], v[62:65]
	v_mfma_f32_16x16x32_bf16 v[62:65], v[150:153], v[178:181], v[62:65]
	v_mfma_f32_16x16x32_bf16 v[58:61], v[170:173], v[178:181], v[58:61]
	v_mfma_f32_16x16x32_bf16 v[58:61], v[154:157], v[174:177], v[58:61]
	v_mfma_f32_16x16x32_bf16 v[50:53], v[154:157], v[182:185], v[50:53]
	v_mfma_f32_16x16x32_bf16 v[50:53], v[170:173], v[186:189], v[50:53]
	v_mfma_f32_16x16x32_bf16 v[54:57], v[150:153], v[186:189], v[54:57]
	v_mfma_f32_16x16x32_bf16 v[54:57], v[146:149], v[182:185], v[54:57]
	v_mfma_f32_16x16x32_bf16 v[22:25], v[146:149], v[194:197], v[22:25]
	v_mfma_f32_16x16x32_bf16 v[22:25], v[150:153], v[198:201], v[22:25]
	v_mfma_f32_16x16x32_bf16 v[18:21], v[170:173], v[198:201], v[18:21]
	v_mfma_f32_16x16x32_bf16 v[18:21], v[154:157], v[194:197], v[18:21]
	v_mfma_f32_16x16x32_bf16 v[10:13], v[154:157], v[202:205], v[10:13]
	v_mfma_f32_16x16x32_bf16 v[10:13], v[170:173], v[206:209], v[10:13]
	v_mfma_f32_16x16x32_bf16 v[14:17], v[150:153], v[206:209], v[14:17]
	v_mfma_f32_16x16x32_bf16 v[14:17], v[146:149], v[202:205], v[14:17]
	s_setprio 0
	s_barrier
; #define PG8_STAGE(bufoff, gbase, voff) do { _Pragma("unroll") for (int _i = 0; _i < 2; ++_i) \
;         __builtin_amdgcn_global_load_lds((const unsigned*)((const char*)(gbase) + (voff)[_i]), (PG8_LAS unsigned*)(lds + (bufoff) + ldsw + _i * 8192), 16, 0, 0); } while (0)
; #define PG8_LDA(dst, b, h) do { _Pragma("unroll") for (int m = 0; m < 4; ++m) _Pragma("unroll") for (int k = 0; k < 2; ++k) dst[m][k] = *(const PG8_LAS bf16x8*)(lds + PG8_SA(b, h) + aoff + m * 2048 + k * 1024); } while (0)
; #define PG8_LDB(dst, b, h) do { _Pragma("unroll") for (int n = 0; n < 2; ++n) _Pragma("unroll") for (int k = 0; k < 2; ++k) dst[n][k] = *(const PG8_LAS bf16x8*)(lds + PG8_SB(b, h) + boff + n * 2048 + k * 1024); } while (0)
; #define PG8_WAIT_V(n) asm volatile("s_waitcnt vmcnt(" #n ")" ::: "memory")
; #define PG8_WAIT_L(n) asm volatile("s_waitcnt lgkmcnt(" #n ")" ::: "memory")
; #define PG8_BAR __builtin_amdgcn_s_barrier()
; #define PG8_SCHED __builtin_amdgcn_sched_barrier(0)
;     ...
;             const char* a2 = last ? nA : cA + (ptrdiff_t)(t + 2) * kstepA; const char* b2 = last ? nB : cB + (ptrdiff_t)(t + 2) * kstep;
;             const char* a3 = a2 + kstepA; const char* b3 = b2 + kstep;
;             if (last && has_next) S.a_ready(nxt);
;             if constexpr (SP2) {
;             PG8_LDB(B0, 0, 0); PG8_LDB(B1, 0, 1); PG8_SCHED; PG8_LDA(At, 0, 0); PG8_STAGE(PG8_SA(1, 1), a1 + hstepA, voffA);
;             PG8_WAIT_V(8); PG8_WAIT_L(0); PG8_BAR; PG8_MMA(0, 0, At, B0); PG8_MMA(0, 1, At, B1); PG8_BAR; PG8_SCHED;
;             PG8_LDA(At, 0, 1); PG8_STAGE(PG8_SB(0, 0), b2, voffB); PG8_STAGE(PG8_SB(0, 1), b2 + hstepB, voffB); PG8_STAGE(PG8_SA(0, 0), a2, voffA);
;             PG8_WAIT_V(8); PG8_WAIT_L(0); PG8_BAR; PG8_MMA(1, 0, At, B0); PG8_MMA(1, 1, At, B1); PG8_BAR; PG8_SCHED;
;             PG8_LDB(B0, 1, 0); PG8_LDB(B1, 1, 1); PG8_SCHED; PG8_LDA(At, 1, 0); PG8_STAGE(PG8_SA(0, 1), a2 + hstepA, voffA);
;             PG8_WAIT_V(8); PG8_WAIT_L(0); PG8_BAR; PG8_MMA(0, 0, At, B0); PG8_MMA(0, 1, At, B1); PG8_BAR; PG8_SCHED;
;             PG8_LDA(At, 1, 1); PG8_STAGE(PG8_SB(1, 0), b3, voffB); PG8_STAGE(PG8_SB(1, 1), b3 + hstepB, voffB); PG8_STAGE(PG8_SA(1, 0), a3, voffA);
;             PG8_WAIT_V(8); PG8_WAIT_L(0); PG8_BAR; PG8_MMA(1, 0, At, B0); PG8_MMA(1, 1, At, B1); PG8_BAR; PG8_SCHED;
;     ...
;         if constexpr (ALIGN_EPI) { if (wr == 0) PG8_BAR; }
.Lup_mid:
	s_add_i32 s88, 0, 0x18000
	v_add_u32_e32 v0, s88, v192
	s_add_i32 s89, 0, 0x1c000
	ds_read_b128 v[130:133], v0
	ds_read_b128 v[134:137], v0 offset:1024
	ds_read_b128 v[138:141], v0 offset:2048
	ds_read_b128 v[142:145], v0 offset:3072
	v_add_u32_e32 v0, s89, v192
	ds_read_b128 v[146:149], v0
	ds_read_b128 v[150:153], v0 offset:1024
	ds_read_b128 v[154:157], v0 offset:2048
	ds_read_b128 v[170:173], v0 offset:3072
	s_mov_b32 m0, s51
	v_lshl_add_u64 v[190:191], v[190:191], 0, s[58:59]
	ds_read_b128 v[174:177], v193 offset:32768
	ds_read_b128 v[178:181], v193 offset:33792
	ds_read_b128 v[182:185], v193 offset:34816
	ds_read_b128 v[186:189], v193 offset:35840
	ds_read_b128 v[194:197], v193 offset:36864
	ds_read_b128 v[198:201], v193 offset:37888
	ds_read_b128 v[202:205], v193 offset:38912
	ds_read_b128 v[206:209], v193 offset:39936
	global_load_lds_dwordx4 v[190:191], off
	v_lshl_add_u64 v[190:191], v[210:211], 0, s[58:59]
	s_mov_b32 m0, s54
	s_nop 0
	global_load_lds_dwordx4 v[190:191], off
	s_waitcnt vmcnt(8) lgkmcnt(0)
	s_barrier
	s_setprio 1
	v_mfma_f32_16x16x32_bf16 v[126:129], v[130:133], v[174:177], v[126:129]
	v_mfma_f32_16x16x32_bf16 v[126:129], v[134:137], v[178:181], v[126:129]
	v_mfma_f32_16x16x32_bf16 v[122:125], v[142:145], v[178:181], v[122:125]
	v_mfma_f32_16x16x32_bf16 v[122:125], v[138:141], v[174:177], v[122:125]
	v_mfma_f32_16x16x32_bf16 v[114:117], v[138:141], v[182:185], v[114:117]
	v_mfma_f32_16x16x32_bf16 v[114:117], v[142:145], v[186:189], v[114:117]
	v_mfma_f32_16x16x32_bf16 v[118:121], v[134:137], v[186:189], v[118:121]
	v_mfma_f32_16x16x32_bf16 v[118:121], v[130:133], v[182:185], v[118:121]
	v_mfma_f32_16x16x32_bf16 v[110:113], v[130:133], v[194:197], v[110:113]
	v_mfma_f32_16x16x32_bf16 v[110:113], v[134:137], v[198:201], v[110:113]
	v_mfma_f32_16x16x32_bf16 v[106:109], v[142:145], v[198:201], v[106:109]
	v_mfma_f32_16x16x32_bf16 v[106:109], v[138:141], v[194:197], v[106:109]
	v_mfma_f32_16x16x32_bf16 v[98:101], v[138:141], v[202:205], v[98:101]
	v_mfma_f32_16x16x32_bf16 v[98:101], v[142:145], v[206:209], v[98:101]
	v_mfma_f32_16x16x32_bf16 v[102:105], v[134:137], v[206:209], v[102:105]
	v_mfma_f32_16x16x32_bf16 v[102:105], v[130:133], v[202:205], v[102:105]
	s_setprio 0
	s_setprio 1
	v_mfma_f32_16x16x32_bf16 v[30:33], v[146:149], v[174:177], v[30:33]
	v_mfma_f32_16x16x32_bf16 v[30:33], v[150:153], v[178:181], v[30:33]
	v_mfma_f32_16x16x32_bf16 v[46:49], v[170:173], v[178:181], v[46:49]
	v_mfma_f32_16x16x32_bf16 v[46:49], v[154:157], v[174:177], v[46:49]
	v_mfma_f32_16x16x32_bf16 v[34:37], v[154:157], v[182:185], v[34:37]
	v_mfma_f32_16x16x32_bf16 v[34:37], v[170:173], v[186:189], v[34:37]
	v_mfma_f32_16x16x32_bf16 v[26:29], v[150:153], v[186:189], v[26:29]
	v_mfma_f32_16x16x32_bf16 v[26:29], v[146:149], v[182:185], v[26:29]
	v_mfma_f32_16x16x32_bf16 v[94:97], v[146:149], v[194:197], v[94:97]
	v_mfma_f32_16x16x32_bf16 v[94:97], v[150:153], v[198:201], v[94:97]
	v_mfma_f32_16x16x32_bf16 v[90:93], v[170:173], v[198:201], v[90:93]
	v_mfma_f32_16x16x32_bf16 v[90:93], v[154:157], v[194:197], v[90:93]
	v_mfma_f32_16x16x32_bf16 v[82:85], v[154:157], v[202:205], v[82:85]
	v_mfma_f32_16x16x32_bf16 v[82:85], v[170:173], v[206:209], v[82:85]
	v_mfma_f32_16x16x32_bf16 v[86:89], v[150:153], v[206:209], v[86:89]
	v_mfma_f32_16x16x32_bf16 v[86:89], v[146:149], v[202:205], v[86:89]
	s_setprio 0
	s_barrier
	s_add_u32 s34, s86, 0x8000
	s_addc_u32 s35, s87, 0
	s_add_i32 s88, s88, s44
	s_mov_b32 m0, s88
	ds_read_b128 v[174:177], v193 offset:49152
	ds_read_b128 v[178:181], v193 offset:50176
	ds_read_b128 v[182:185], v193 offset:51200
	ds_read_b128 v[186:189], v193 offset:52224
	ds_read_b128 v[194:197], v193 offset:53248
	ds_read_b128 v[198:201], v193 offset:54272
	ds_read_b128 v[202:205], v193 offset:55296
	ds_read_b128 v[206:209], v193 offset:56320
	global_load_lds_dwordx4 v162, s[34:35]
	s_add_i32 m0, s88, 0x2000
	v_lshl_add_u64 v[190:191], s[34:35], 0, v[158:159]
	s_add_u32 s34, s86, 0xc000
	s_addc_u32 s35, s87, 0
	s_add_i32 s86, s89, s44
	global_load_lds_dwordx4 v[190:191], off
	s_mov_b32 m0, s86
	s_nop 0
	global_load_lds_dwordx4 v162, s[34:35]
	s_add_i32 m0, s86, 0x2000
	s_nop 0
	global_load_lds_dwordx4 v158, s[34:35]
	s_mov_b32 m0, s85
	s_nop 0
	global_load_lds_dwordx4 v164, s[46:47]
	v_lshl_add_u64 v[190:191], s[46:47], 0, v[160:161]
	s_mov_b32 m0, s90
	s_nop 0
	global_load_lds_dwordx4 v[190:191], off
	s_waitcnt vmcnt(8) lgkmcnt(0)
	s_barrier
	s_setprio 1
	v_mfma_f32_16x16x32_bf16 v[78:81], v[130:133], v[174:177], v[78:81]
	v_mfma_f32_16x16x32_bf16 v[78:81], v[134:137], v[178:181], v[78:81]
	v_mfma_f32_16x16x32_bf16 v[74:77], v[142:145], v[178:181], v[74:77]
	v_mfma_f32_16x16x32_bf16 v[74:77], v[138:141], v[174:177], v[74:77]
	v_mfma_f32_16x16x32_bf16 v[66:69], v[138:141], v[182:185], v[66:69]
	v_mfma_f32_16x16x32_bf16 v[66:69], v[142:145], v[186:189], v[66:69]
	v_mfma_f32_16x16x32_bf16 v[70:73], v[134:137], v[186:189], v[70:73]
	v_mfma_f32_16x16x32_bf16 v[70:73], v[130:133], v[182:185], v[70:73]
	v_mfma_f32_16x16x32_bf16 v[42:45], v[130:133], v[194:197], v[42:45]
	v_mfma_f32_16x16x32_bf16 v[42:45], v[134:137], v[198:201], v[42:45]
	v_mfma_f32_16x16x32_bf16 v[6:9], v[142:145], v[198:201], v[6:9]
	v_mfma_f32_16x16x32_bf16 v[6:9], v[138:141], v[194:197], v[6:9]
	v_mfma_f32_16x16x32_bf16 v[2:5], v[138:141], v[202:205], v[2:5]
	v_mfma_f32_16x16x32_bf16 v[2:5], v[142:145], v[206:209], v[2:5]
	v_mfma_f32_16x16x32_bf16 v[38:41], v[134:137], v[206:209], v[38:41]
	v_mfma_f32_16x16x32_bf16 v[38:41], v[130:133], v[202:205], v[38:41]
	s_setprio 0
	s_setprio 1
	v_mfma_f32_16x16x32_bf16 v[62:65], v[146:149], v[174:177], v[62:65]
	v_mfma_f32_16x16x32_bf16 v[62:65], v[150:153], v[178:181], v[62:65]
	v_mfma_f32_16x16x32_bf16 v[58:61], v[170:173], v[178:181], v[58:61]
	v_mfma_f32_16x16x32_bf16 v[58:61], v[154:157], v[174:177], v[58:61]
	v_mfma_f32_16x16x32_bf16 v[50:53], v[154:157], v[182:185], v[50:53]
	v_mfma_f32_16x16x32_bf16 v[50:53], v[170:173], v[186:189], v[50:53]
	v_mfma_f32_16x16x32_bf16 v[54:57], v[150:153], v[186:189], v[54:57]
	v_mfma_f32_16x16x32_bf16 v[54:57], v[146:149], v[182:185], v[54:57]
	v_mfma_f32_16x16x32_bf16 v[22:25], v[146:149], v[194:197], v[22:25]
	v_mfma_f32_16x16x32_bf16 v[22:25], v[150:153], v[198:201], v[22:25]
	v_mfma_f32_16x16x32_bf16 v[18:21], v[170:173], v[198:201], v[18:21]
	v_mfma_f32_16x16x32_bf16 v[18:21], v[154:157], v[194:197], v[18:21]
	v_mfma_f32_16x16x32_bf16 v[10:13], v[154:157], v[202:205], v[10:13]
	v_mfma_f32_16x16x32_bf16 v[10:13], v[170:173], v[206:209], v[10:13]
	v_mfma_f32_16x16x32_bf16 v[14:17], v[150:153], v[206:209], v[14:17]
	v_mfma_f32_16x16x32_bf16 v[14:17], v[146:149], v[202:205], v[14:17]
	s_setprio 0
	s_barrier
	s_add_i32 s66, s66, 2
	s_add_u32 vcc_hi, vcc_hi, 0x10000
	s_addc_u32 s65, s65, 0
	s_cmp_gt_u32 s66, 29
	s_mov_b64 s[34:35], s[36:37]
	s_cbranch_scc0 .LBB0_1256
	s_and_b64 vcc, exec, s[18:19]
	s_cbranch_vccz .LBB0_1259
	s_barrier

;     __host__ __device__ __forceinline__ bool next(int i, Unit& u) const { const int vv = vid + (i / 5) * G; if (vv >= 256) return false; u.pm = vv >> 2; u.pn = (vv & 3) + 4 * (i % 5); return true; }
; #define PG8_STAGE(bufoff, gbase, voff) do { _Pragma("unroll") for (int _i = 0; _i < 2; ++_i) \
;         __builtin_amdgcn_global_load_lds((const unsigned*)((const char*)(gbase) + (voff)[_i]), (PG8_LAS unsigned*)(lds + (bufoff) + ldsw + _i * 8192), 16, 0, 0); } while (0)
; #define PG8_LDA(dst, b, h) do { _Pragma("unroll") for (int m = 0; m < 4; ++m) _Pragma("unroll") for (int k = 0; k < 2; ++k) dst[m][k] = *(const PG8_LAS bf16x8*)(lds + PG8_SA(b, h) + aoff + m * 2048 + k * 1024); } while (0)
; #define PG8_LDB(dst, b, h) do { _Pragma("unroll") for (int n = 0; n < 2; ++n) _Pragma("unroll") for (int k = 0; k < 2; ++k) dst[n][k] = *(const PG8_LAS bf16x8*)(lds + PG8_SB(b, h) + boff + n * 2048 + k * 1024); } while (0)
; #define PG8_WAIT_V(n) asm volatile("s_waitcnt vmcnt(" #n ")" ::: "memory")
; #define PG8_WAIT_L(n) asm volatile("s_waitcnt lgkmcnt(" #n ")" ::: "memory")
; #define PG8_BAR __builtin_amdgcn_s_barrier()
;     ...
;         const bool has_next = S.next(ui + 1, nxt);
;         const char* nA = has_next ? (const char*)g.A + (size_t)nxt.pm * tstepA + (size_t)nxt.pn * APN + kofA : cA; const char* nB = has_next ? (const char*)g.Bt + (size_t)nxt.pn * tstepB + S.b_off(nxt) + kofB : cB;
;         for (int t = 0; t < nt; t += 2) {
;             const bool last = (t == nt - 2);
;             const char* a1 = cA + (ptrdiff_t)(t + 1) * kstepA;
;             const char* a2 = last ? nA : cA + (ptrdiff_t)(t + 2) * kstepA; const char* b2 = last ? nB : cB + (ptrdiff_t)(t + 2) * kstep;
;             const char* a3 = a2 + kstepA; const char* b3 = b2 + kstep;
;             if (last && has_next) S.a_ready(nxt);
;             if constexpr (SP2) {
;             PG8_LDB(B0, 0, 0); PG8_LDB(B1, 0, 1); PG8_SCHED; PG8_LDA(At, 0, 0); PG8_STAGE(PG8_SA(1, 1), a1 + hstepA, voffA);
;             PG8_WAIT_V(8); PG8_WAIT_L(0); PG8_BAR; PG8_MMA(0, 0, At, B0); PG8_MMA(0, 1, At, B1); PG8_BAR; PG8_SCHED;
;             PG8_LDA(At, 0, 1); PG8_STAGE(PG8_SB(0, 0), b2, voffB); PG8_STAGE(PG8_SB(0, 1), b2 + hstepB, voffB); PG8_STAGE(PG8_SA(0, 0), a2, voffA);
;             PG8_WAIT_V(8); PG8_WAIT_L(0); PG8_BAR; PG8_MMA(1, 0, At, B0); PG8_MMA(1, 1, At, B1); PG8_BAR; PG8_SCHED;
.Ldn_nostg:
	s_or_b32 s44, s56, 1
	s_lshl_b64 s[34:35], s[44:45], 15
	s_sub_u32 s34, 0, s34
	s_subb_u32 s35, 0, s35
	s_add_u32 s44, s28, s34
	s_addc_u32 s65, s29, s35
	s_add_u32 s34, s30, 0xffff8000
	s_addc_u32 s35, s31, -1
	s_add_i32 s66, 0, 0x10000
	v_add_u32_e32 v0, s66, v230
	s_add_i32 s90, 0, 0x14000
	s_waitcnt lgkmcnt(0)
	ds_read_b128 v[130:133], v0
	ds_read_b128 v[134:137], v0 offset:1024
	ds_read_b128 v[138:141], v0 offset:2048
	ds_read_b128 v[142:145], v0 offset:3072
	v_add_u32_e32 v0, s90, v230
	ds_read_b128 v[146:149], v0
	ds_read_b128 v[150:153], v0 offset:1024
	ds_read_b128 v[154:157], v0 offset:2048
	ds_read_b128 v[158:161], v0 offset:3072
	s_add_u32 s88, s44, 0x4000
	s_addc_u32 s89, s65, 0
	s_add_i32 m0, s46, 0xc000
	ds_read_b128 v[162:165], v231
	ds_read_b128 v[166:169], v231 offset:1024
	ds_read_b128 v[170:173], v231 offset:2048
	ds_read_b128 v[174:177], v231 offset:3072
	ds_read_b128 v[178:181], v231 offset:4096
	ds_read_b128 v[182:185], v231 offset:5120
	ds_read_b128 v[186:189], v231 offset:6144
	ds_read_b128 v[190:193], v231 offset:7168
	global_load_lds_dwordx4 v194, s[88:89]
	s_add_i32 m0, s46, 0xe000
	s_nop 0
	global_load_lds_dwordx4 v198, s[88:89]
	s_waitcnt vmcnt(8) lgkmcnt(0)
	s_barrier
	s_setprio 1
	v_mfma_f32_16x16x32_bf16 v[126:129], v[130:133], v[162:165], 0
	v_mfma_f32_16x16x32_bf16 v[126:129], v[134:137], v[166:169], v[126:129]
	v_mfma_f32_16x16x32_bf16 v[122:125], v[142:145], v[166:169], 0
	v_mfma_f32_16x16x32_bf16 v[122:125], v[138:141], v[162:165], v[122:125]
	v_mfma_f32_16x16x32_bf16 v[106:109], v[138:141], v[170:173], 0
	v_mfma_f32_16x16x32_bf16 v[106:109], v[142:145], v[174:177], v[106:109]
	v_mfma_f32_16x16x32_bf16 v[110:113], v[134:137], v[174:177], 0
	v_mfma_f32_16x16x32_bf16 v[110:113], v[130:133], v[170:173], v[110:113]
	v_mfma_f32_16x16x32_bf16 v[94:97], v[130:133], v[178:181], 0
	v_mfma_f32_16x16x32_bf16 v[94:97], v[134:137], v[182:185], v[94:97]
	v_mfma_f32_16x16x32_bf16 v[90:93], v[142:145], v[182:185], 0
	v_mfma_f32_16x16x32_bf16 v[90:93], v[138:141], v[178:181], v[90:93]
	v_mfma_f32_16x16x32_bf16 v[74:77], v[138:141], v[186:189], 0
	v_mfma_f32_16x16x32_bf16 v[74:77], v[142:145], v[190:193], v[74:77]
	v_mfma_f32_16x16x32_bf16 v[78:81], v[134:137], v[190:193], 0
	v_mfma_f32_16x16x32_bf16 v[78:81], v[130:133], v[186:189], v[78:81]
	s_setprio 0
	s_setprio 1
	v_mfma_f32_16x16x32_bf16 v[118:121], v[146:149], v[162:165], 0
	v_mfma_f32_16x16x32_bf16 v[118:121], v[150:153], v[166:169], v[118:121]
	v_mfma_f32_16x16x32_bf16 v[114:117], v[158:161], v[166:169], 0
	v_mfma_f32_16x16x32_bf16 v[114:117], v[154:157], v[162:165], v[114:117]
	v_mfma_f32_16x16x32_bf16 v[98:101], v[154:157], v[170:173], 0
	v_mfma_f32_16x16x32_bf16 v[98:101], v[158:161], v[174:177], v[98:101]
	v_mfma_f32_16x16x32_bf16 v[102:105], v[150:153], v[174:177], 0
	v_mfma_f32_16x16x32_bf16 v[102:105], v[146:149], v[170:173], v[102:105]
	v_mfma_f32_16x16x32_bf16 v[86:89], v[146:149], v[178:181], 0
	v_mfma_f32_16x16x32_bf16 v[86:89], v[150:153], v[182:185], v[86:89]
	v_mfma_f32_16x16x32_bf16 v[82:85], v[158:161], v[182:185], 0
	v_mfma_f32_16x16x32_bf16 v[82:85], v[154:157], v[178:181], v[82:85]
	v_mfma_f32_16x16x32_bf16 v[66:69], v[154:157], v[186:189], 0
	v_mfma_f32_16x16x32_bf16 v[66:69], v[158:161], v[190:193], v[66:69]
	v_mfma_f32_16x16x32_bf16 v[70:73], v[150:153], v[190:193], 0
	v_mfma_f32_16x16x32_bf16 v[70:73], v[146:149], v[186:189], v[70:73]
	s_setprio 0
	s_barrier
	s_add_i32 s44, s66, s41
	s_mov_b32 m0, s44
	ds_read_b128 v[162:165], v231 offset:16384
	ds_read_b128 v[166:169], v231 offset:17408
	ds_read_b128 v[170:173], v231 offset:18432
	ds_read_b128 v[174:177], v231 offset:19456
	ds_read_b128 v[178:181], v231 offset:20480
	ds_read_b128 v[182:185], v231 offset:21504
	ds_read_b128 v[186:189], v231 offset:22528
	ds_read_b128 v[190:193], v231 offset:23552
	global_load_lds_dwordx4 v196, s[8:9]
	s_add_i32 m0, s44, 0x2000
	s_add_u32 s88, s8, 0x4000
	s_addc_u32 s89, s9, 0
	s_add_i32 s44, s90, s41
	global_load_lds_dwordx4 v200, s[8:9]
	s_mov_b32 m0, s44
	s_nop 0
	global_load_lds_dwordx4 v196, s[88:89]
	s_add_i32 m0, s44, 0x2000
	s_nop 0
	global_load_lds_dwordx4 v200, s[88:89]
	s_mov_b32 m0, s46
	s_nop 0
	global_load_lds_dwordx4 v194, s[30:31]
	s_mov_b32 m0, s47
	s_nop 0
	global_load_lds_dwordx4 v198, s[30:31]
	s_waitcnt vmcnt(8) lgkmcnt(0)
	s_barrier
	s_setprio 1
	v_mfma_f32_16x16x32_bf16 v[62:65], v[130:133], v[162:165], 0
	v_mfma_f32_16x16x32_bf16 v[62:65], v[134:137], v[166:169], v[62:65]
	v_mfma_f32_16x16x32_bf16 v[58:61], v[142:145], v[166:169], 0
	v_mfma_f32_16x16x32_bf16 v[58:61], v[138:141], v[162:165], v[58:61]
	v_mfma_f32_16x16x32_bf16 v[42:45], v[138:141], v[170:173], 0
	v_mfma_f32_16x16x32_bf16 v[42:45], v[142:145], v[174:177], v[42:45]
	v_mfma_f32_16x16x32_bf16 v[46:49], v[134:137], v[174:177], 0
	v_mfma_f32_16x16x32_bf16 v[46:49], v[130:133], v[170:173], v[46:49]
	v_mfma_f32_16x16x32_bf16 v[30:33], v[130:133], v[178:181], 0
	v_mfma_f32_16x16x32_bf16 v[30:33], v[134:137], v[182:185], v[30:33]
	v_mfma_f32_16x16x32_bf16 v[26:29], v[142:145], v[182:185], 0
	v_mfma_f32_16x16x32_bf16 v[26:29], v[138:141], v[178:181], v[26:29]
	v_mfma_f32_16x16x32_bf16 v[10:13], v[138:141], v[186:189], 0
	v_mfma_f32_16x16x32_bf16 v[10:13], v[142:145], v[190:193], v[10:13]
	v_mfma_f32_16x16x32_bf16 v[14:17], v[134:137], v[190:193], 0
	v_mfma_f32_16x16x32_bf16 v[14:17], v[130:133], v[186:189], v[14:17]
	s_setprio 0
	s_setprio 1
	v_mfma_f32_16x16x32_bf16 v[54:57], v[146:149], v[162:165], 0
	v_mfma_f32_16x16x32_bf16 v[54:57], v[150:153], v[166:169], v[54:57]
	v_mfma_f32_16x16x32_bf16 v[50:53], v[158:161], v[166:169], 0
	v_mfma_f32_16x16x32_bf16 v[50:53], v[154:157], v[162:165], v[50:53]
	v_mfma_f32_16x16x32_bf16 v[34:37], v[154:157], v[170:173], 0
	v_mfma_f32_16x16x32_bf16 v[34:37], v[158:161], v[174:177], v[34:37]
	v_mfma_f32_16x16x32_bf16 v[38:41], v[150:153], v[174:177], 0
	v_mfma_f32_16x16x32_bf16 v[38:41], v[146:149], v[170:173], v[38:41]
	v_mfma_f32_16x16x32_bf16 v[22:25], v[146:149], v[178:181], 0
	v_mfma_f32_16x16x32_bf16 v[22:25], v[150:153], v[182:185], v[22:25]
	v_mfma_f32_16x16x32_bf16 v[18:21], v[158:161], v[182:185], 0
	v_mfma_f32_16x16x32_bf16 v[18:21], v[154:157], v[178:181], v[18:21]
	v_mfma_f32_16x16x32_bf16 v[2:5], v[154:157], v[186:189], 0
	v_mfma_f32_16x16x32_bf16 v[2:5], v[158:161], v[190:193], v[2:5]
	v_mfma_f32_16x16x32_bf16 v[6:9], v[150:153], v[190:193], 0
	v_mfma_f32_16x16x32_bf16 v[6:9], v[146:149], v[186:189], v[6:9]
	s_setprio 0
	s_barrier
	s_branch .Ldn_mid

; #define PG8_STAGE(bufoff, gbase, voff) do { _Pragma("unroll") for (int _i = 0; _i < 2; ++_i) \
;         __builtin_amdgcn_global_load_lds((const unsigned*)((const char*)(gbase) + (voff)[_i]), (PG8_LAS unsigned*)(lds + (bufoff) + ldsw + _i * 8192), 16, 0, 0); } while (0)
; #define PG8_LDA(dst, b, h) do { _Pragma("unroll") for (int m = 0; m < 4; ++m) _Pragma("unroll") for (int k = 0; k < 2; ++k) dst[m][k] = *(const PG8_LAS bf16x8*)(lds + PG8_SA(b, h) + aoff + m * 2048 + k * 1024); } while (0)
; #define PG8_LDB(dst, b, h) do { _Pragma("unroll") for (int n = 0; n < 2; ++n) _Pragma("unroll") for (int k = 0; k < 2; ++k) dst[n][k] = *(const PG8_LAS bf16x8*)(lds + PG8_SB(b, h) + boff + n * 2048 + k * 1024); } while (0)
; #define PG8_MMA(ai, bj, At, Bt) do { __builtin_amdgcn_s_setprio(1); _Pragma("unroll") for (int m = 0; m < 4; ++m) _Pragma("unroll") for (int n = 0; n < 2; ++n) _Pragma("unroll") for (int k = 0; k < 2; ++k) \
;         acc[ai][bj][m][n] = __builtin_amdgcn_mfma_f32_16x16x32_bf16(Bt[n][k], At[m][k], acc[ai][bj][m][n], 0, 0, 0); __builtin_amdgcn_s_setprio(0); } while (0)
; #define PG8_WAIT_V(n) asm volatile("s_waitcnt vmcnt(" #n ")" ::: "memory")
; #define PG8_WAIT_L(n) asm volatile("s_waitcnt lgkmcnt(" #n ")" ::: "memory")
; #define PG8_BAR __builtin_amdgcn_s_barrier()
; #define PG8_SCHED __builtin_amdgcn_sched_barrier(0)
;     ...
;             const bool last = (t == nt - 2);
;             const char* a1 = cA + (ptrdiff_t)(t + 1) * kstepA;
;             const char* a2 = last ? nA : cA + (ptrdiff_t)(t + 2) * kstepA; const char* b2 = last ? nB : cB + (ptrdiff_t)(t + 2) * kstep;
;             const char* a3 = a2 + kstepA; const char* b3 = b2 + kstep;
;             if (last && has_next) S.a_ready(nxt);
;             if constexpr (SP2) {
;             PG8_LDB(B0, 0, 0); PG8_LDB(B1, 0, 1); PG8_SCHED; PG8_LDA(At, 0, 0); PG8_STAGE(PG8_SA(1, 1), a1 + hstepA, voffA);
;             PG8_WAIT_V(8); PG8_WAIT_L(0); PG8_BAR; PG8_MMA(0, 0, At, B0); PG8_MMA(0, 1, At, B1); PG8_BAR; PG8_SCHED;
;             PG8_LDA(At, 0, 1); PG8_STAGE(PG8_SB(0, 0), b2, voffB); PG8_STAGE(PG8_SB(0, 1), b2 + hstepB, voffB); PG8_STAGE(PG8_SA(0, 0), a2, voffA);
;             PG8_WAIT_V(8); PG8_WAIT_L(0); PG8_BAR; PG8_MMA(1, 0, At, B0); PG8_MMA(1, 1, At, B1); PG8_BAR; PG8_SCHED;
.LBB0_1444:
	s_or_b32 s44, s56, 1
	s_lshl_b64 s[34:35], s[44:45], 15
	s_sub_u32 s34, 0, s34
	s_subb_u32 s35, 0, s35
	s_add_u32 s44, s28, s34
	s_addc_u32 s65, s29, s35
	s_add_u32 s34, s30, 0xffff8000
	s_addc_u32 s35, s31, -1
	s_add_i32 s66, 0, 0x10000
	v_add_u32_e32 v0, s66, v230
	s_add_i32 s90, 0, 0x14000
	s_waitcnt lgkmcnt(0)
	ds_read_b128 v[130:133], v0
	ds_read_b128 v[134:137], v0 offset:1024
	ds_read_b128 v[138:141], v0 offset:2048
	ds_read_b128 v[142:145], v0 offset:3072
	v_add_u32_e32 v0, s90, v230
	ds_read_b128 v[146:149], v0
	ds_read_b128 v[150:153], v0 offset:1024
	ds_read_b128 v[154:157], v0 offset:2048
	ds_read_b128 v[158:161], v0 offset:3072
	s_add_u32 s88, s44, 0x4000
	s_addc_u32 s89, s65, 0
	s_add_i32 m0, s46, 0xc000
	ds_read_b128 v[162:165], v231
	ds_read_b128 v[166:169], v231 offset:1024
	ds_read_b128 v[170:173], v231 offset:2048
	ds_read_b128 v[174:177], v231 offset:3072
	ds_read_b128 v[178:181], v231 offset:4096
	ds_read_b128 v[182:185], v231 offset:5120
	ds_read_b128 v[186:189], v231 offset:6144
	ds_read_b128 v[190:193], v231 offset:7168
	global_load_lds_dwordx4 v194, s[88:89]
	s_add_i32 m0, s46, 0xe000
	s_nop 0
	global_load_lds_dwordx4 v198, s[88:89]
	s_waitcnt vmcnt(8) lgkmcnt(0)
	s_barrier
	s_setprio 1
	v_mfma_f32_16x16x32_bf16 v[126:129], v[130:133], v[162:165], v[126:129]
	v_mfma_f32_16x16x32_bf16 v[126:129], v[134:137], v[166:169], v[126:129]
	v_mfma_f32_16x16x32_bf16 v[122:125], v[142:145], v[166:169], v[122:125]
	v_mfma_f32_16x16x32_bf16 v[122:125], v[138:141], v[162:165], v[122:125]
	v_mfma_f32_16x16x32_bf16 v[106:109], v[138:141], v[170:173], v[106:109]
	v_mfma_f32_16x16x32_bf16 v[106:109], v[142:145], v[174:177], v[106:109]
	v_mfma_f32_16x16x32_bf16 v[110:113], v[134:137], v[174:177], v[110:113]
	v_mfma_f32_16x16x32_bf16 v[110:113], v[130:133], v[170:173], v[110:113]
	v_mfma_f32_16x16x32_bf16 v[94:97], v[130:133], v[178:181], v[94:97]
	v_mfma_f32_16x16x32_bf16 v[94:97], v[134:137], v[182:185], v[94:97]
	v_mfma_f32_16x16x32_bf16 v[90:93], v[142:145], v[182:185], v[90:93]
	v_mfma_f32_16x16x32_bf16 v[90:93], v[138:141], v[178:181], v[90:93]
	v_mfma_f32_16x16x32_bf16 v[74:77], v[138:141], v[186:189], v[74:77]
	v_mfma_f32_16x16x32_bf16 v[74:77], v[142:145], v[190:193], v[74:77]
	v_mfma_f32_16x16x32_bf16 v[78:81], v[134:137], v[190:193], v[78:81]
	v_mfma_f32_16x16x32_bf16 v[78:81], v[130:133], v[186:189], v[78:81]
	s_setprio 0
	s_setprio 1
	v_mfma_f32_16x16x32_bf16 v[118:121], v[146:149], v[162:165], v[118:121]
	v_mfma_f32_16x16x32_bf16 v[118:121], v[150:153], v[166:169], v[118:121]
	v_mfma_f32_16x16x32_bf16 v[114:117], v[158:161], v[166:169], v[114:117]
	v_mfma_f32_16x16x32_bf16 v[114:117], v[154:157], v[162:165], v[114:117]
	v_mfma_f32_16x16x32_bf16 v[98:101], v[154:157], v[170:173], v[98:101]
	v_mfma_f32_16x16x32_bf16 v[98:101], v[158:161], v[174:177], v[98:101]
	v_mfma_f32_16x16x32_bf16 v[102:105], v[150:153], v[174:177], v[102:105]
	v_mfma_f32_16x16x32_bf16 v[102:105], v[146:149], v[170:173], v[102:105]
	v_mfma_f32_16x16x32_bf16 v[86:89], v[146:149], v[178:181], v[86:89]
	v_mfma_f32_16x16x32_bf16 v[86:89], v[150:153], v[182:185], v[86:89]
	v_mfma_f32_16x16x32_bf16 v[82:85], v[158:161], v[182:185], v[82:85]
	v_mfma_f32_16x16x32_bf16 v[82:85], v[154:157], v[178:181], v[82:85]
	v_mfma_f32_16x16x32_bf16 v[66:69], v[154:157], v[186:189], v[66:69]
	v_mfma_f32_16x16x32_bf16 v[66:69], v[158:161], v[190:193], v[66:69]
	v_mfma_f32_16x16x32_bf16 v[70:73], v[150:153], v[190:193], v[70:73]
	v_mfma_f32_16x16x32_bf16 v[70:73], v[146:149], v[186:189], v[70:73]
	s_setprio 0
	s_barrier
	s_add_i32 s44, s66, s41
	s_mov_b32 m0, s44
	ds_read_b128 v[162:165], v231 offset:16384
	ds_read_b128 v[166:169], v231 offset:17408
	ds_read_b128 v[170:173], v231 offset:18432
	ds_read_b128 v[174:177], v231 offset:19456
	ds_read_b128 v[178:181], v231 offset:20480
	ds_read_b128 v[182:185], v231 offset:21504
	ds_read_b128 v[186:189], v231 offset:22528
	ds_read_b128 v[190:193], v231 offset:23552
	global_load_lds_dwordx4 v196, s[8:9]
	s_add_i32 m0, s44, 0x2000
	s_add_u32 s88, s8, 0x4000
	s_addc_u32 s89, s9, 0
	s_add_i32 s44, s90, s41
	global_load_lds_dwordx4 v200, s[8:9]
	s_mov_b32 m0, s44
	s_nop 0
	global_load_lds_dwordx4 v196, s[88:89]
	s_add_i32 m0, s44, 0x2000
	s_nop 0
	global_load_lds_dwordx4 v200, s[88:89]
	s_mov_b32 m0, s46
	s_nop 0
	global_load_lds_dwordx4 v194, s[30:31]
	s_mov_b32 m0, s47
	s_nop 0
	global_load_lds_dwordx4 v198, s[30:31]
	s_waitcnt vmcnt(8) lgkmcnt(0)
	s_barrier
	s_setprio 1
	v_mfma_f32_16x16x32_bf16 v[62:65], v[130:133], v[162:165], v[62:65]
	v_mfma_f32_16x16x32_bf16 v[62:65], v[134:137], v[166:169], v[62:65]
	v_mfma_f32_16x16x32_bf16 v[58:61], v[142:145], v[166:169], v[58:61]
	v_mfma_f32_16x16x32_bf16 v[58:61], v[138:141], v[162:165], v[58:61]
	v_mfma_f32_16x16x32_bf16 v[42:45], v[138:141], v[170:173], v[42:45]
	v_mfma_f32_16x16x32_bf16 v[42:45], v[142:145], v[174:177], v[42:45]
	v_mfma_f32_16x16x32_bf16 v[46:49], v[134:137], v[174:177], v[46:49]
	v_mfma_f32_16x16x32_bf16 v[46:49], v[130:133], v[170:173], v[46:49]
	v_mfma_f32_16x16x32_bf16 v[30:33], v[130:133], v[178:181], v[30:33]
	v_mfma_f32_16x16x32_bf16 v[30:33], v[134:137], v[182:185], v[30:33]
	v_mfma_f32_16x16x32_bf16 v[26:29], v[142:145], v[182:185], v[26:29]
	v_mfma_f32_16x16x32_bf16 v[26:29], v[138:141], v[178:181], v[26:29]
	v_mfma_f32_16x16x32_bf16 v[10:13], v[138:141], v[186:189], v[10:13]
	v_mfma_f32_16x16x32_bf16 v[10:13], v[142:145], v[190:193], v[10:13]
	v_mfma_f32_16x16x32_bf16 v[14:17], v[134:137], v[190:193], v[14:17]
	v_mfma_f32_16x16x32_bf16 v[14:17], v[130:133], v[186:189], v[14:17]
	s_setprio 0
	s_setprio 1
	v_mfma_f32_16x16x32_bf16 v[54:57], v[146:149], v[162:165], v[54:57]
	v_mfma_f32_16x16x32_bf16 v[54:57], v[150:153], v[166:169], v[54:57]
	v_mfma_f32_16x16x32_bf16 v[50:53], v[158:161], v[166:169], v[50:53]
	v_mfma_f32_16x16x32_bf16 v[50:53], v[154:157], v[162:165], v[50:53]
	v_mfma_f32_16x16x32_bf16 v[34:37], v[154:157], v[170:173], v[34:37]
	v_mfma_f32_16x16x32_bf16 v[34:37], v[158:161], v[174:177], v[34:37]
	v_mfma_f32_16x16x32_bf16 v[38:41], v[150:153], v[174:177], v[38:41]
	v_mfma_f32_16x16x32_bf16 v[38:41], v[146:149], v[170:173], v[38:41]
	v_mfma_f32_16x16x32_bf16 v[22:25], v[146:149], v[178:181], v[22:25]
	v_mfma_f32_16x16x32_bf16 v[22:25], v[150:153], v[182:185], v[22:25]
	v_mfma_f32_16x16x32_bf16 v[18:21], v[158:161], v[182:185], v[18:21]
	v_mfma_f32_16x16x32_bf16 v[18:21], v[154:157], v[178:181], v[18:21]
	v_mfma_f32_16x16x32_bf16 v[2:5], v[154:157], v[186:189], v[2:5]
	v_mfma_f32_16x16x32_bf16 v[2:5], v[158:161], v[190:193], v[2:5]
	v_mfma_f32_16x16x32_bf16 v[6:9], v[150:153], v[190:193], v[6:9]
	v_mfma_f32_16x16x32_bf16 v[6:9], v[146:149], v[186:189], v[6:9]
	s_setprio 0
	s_barrier
; #define PG8_STAGE(bufoff, gbase, voff) do { _Pragma("unroll") for (int _i = 0; _i < 2; ++_i) \
;         __builtin_amdgcn_global_load_lds((const unsigned*)((const char*)(gbase) + (voff)[_i]), (PG8_LAS unsigned*)(lds + (bufoff) + ldsw + _i * 8192), 16, 0, 0); } while (0)
; #define PG8_LDA(dst, b, h) do { _Pragma("unroll") for (int m = 0; m < 4; ++m) _Pragma("unroll") for (int k = 0; k < 2; ++k) dst[m][k] = *(const PG8_LAS bf16x8*)(lds + PG8_SA(b, h) + aoff + m * 2048 + k * 1024); } while (0)
; #define PG8_LDB(dst, b, h) do { _Pragma("unroll") for (int n = 0; n < 2; ++n) _Pragma("unroll") for (int k = 0; k < 2; ++k) dst[n][k] = *(const PG8_LAS bf16x8*)(lds + PG8_SB(b, h) + boff + n * 2048 + k * 1024); } while (0)
; #define PG8_MMA(ai, bj, At, Bt) do { __builtin_amdgcn_s_setprio(1); _Pragma("unroll") for (int m = 0; m < 4; ++m) _Pragma("unroll") for (int n = 0; n < 2; ++n) _Pragma("unroll") for (int k = 0; k < 2; ++k) \
;         acc[ai][bj][m][n] = __builtin_amdgcn_mfma_f32_16x16x32_bf16(Bt[n][k], At[m][k], acc[ai][bj][m][n], 0, 0, 0); __builtin_amdgcn_s_setprio(0); } while (0)
; #define PG8_WAIT_V(n) asm volatile("s_waitcnt vmcnt(" #n ")" ::: "memory")
; #define PG8_WAIT_L(n) asm volatile("s_waitcnt lgkmcnt(" #n ")" ::: "memory")
; #define PG8_BAR __builtin_amdgcn_s_barrier()
; #define PG8_SCHED __builtin_amdgcn_sched_barrier(0)
;     ...
;             PG8_LDB(B0, 1, 0); PG8_LDB(B1, 1, 1); PG8_SCHED; PG8_LDA(At, 1, 0); PG8_STAGE(PG8_SA(0, 1), a2 + hstepA, voffA);
;             PG8_WAIT_V(8); PG8_WAIT_L(0); PG8_BAR; PG8_MMA(0, 0, At, B0); PG8_MMA(0, 1, At, B1); PG8_BAR; PG8_SCHED;
;             PG8_LDA(At, 1, 1); PG8_STAGE(PG8_SB(1, 0), b3, voffB); PG8_STAGE(PG8_SB(1, 1), b3 + hstepB, voffB); PG8_STAGE(PG8_SA(1, 0), a3, voffA);
;             PG8_WAIT_V(8); PG8_WAIT_L(0); PG8_BAR; PG8_MMA(1, 0, At, B0); PG8_MMA(1, 1, At, B1); PG8_BAR; PG8_SCHED;
.Ldn_mid:
	s_add_i32 s44, 0, 0x18000
	v_add_u32_e32 v0, s44, v230
	s_add_i32 s65, 0, 0x1c000
	ds_read_b128 v[130:133], v0
	ds_read_b128 v[134:137], v0 offset:1024
	ds_read_b128 v[138:141], v0 offset:2048
	ds_read_b128 v[142:145], v0 offset:3072
	v_add_u32_e32 v0, s65, v230
	ds_read_b128 v[146:149], v0
	ds_read_b128 v[150:153], v0 offset:1024
	ds_read_b128 v[154:157], v0 offset:2048
	ds_read_b128 v[158:161], v0 offset:3072
	s_add_u32 s30, s30, 0x4000
	s_addc_u32 s31, s31, 0
	s_mov_b32 m0, s48
	ds_read_b128 v[162:165], v231 offset:32768
	ds_read_b128 v[166:169], v231 offset:33792
	ds_read_b128 v[170:173], v231 offset:34816
	ds_read_b128 v[174:177], v231 offset:35840
	ds_read_b128 v[178:181], v231 offset:36864
	ds_read_b128 v[182:185], v231 offset:37888
	ds_read_b128 v[186:189], v231 offset:38912
	ds_read_b128 v[190:193], v231 offset:39936
	global_load_lds_dwordx4 v194, s[30:31]
	s_mov_b32 m0, s49
	s_nop 0
	global_load_lds_dwordx4 v198, s[30:31]
	s_waitcnt vmcnt(8) lgkmcnt(0)
	s_barrier
	s_setprio 1
	v_mfma_f32_16x16x32_bf16 v[126:129], v[130:133], v[162:165], v[126:129]
	v_mfma_f32_16x16x32_bf16 v[126:129], v[134:137], v[166:169], v[126:129]
	v_mfma_f32_16x16x32_bf16 v[122:125], v[142:145], v[166:169], v[122:125]
	v_mfma_f32_16x16x32_bf16 v[122:125], v[138:141], v[162:165], v[122:125]
	v_mfma_f32_16x16x32_bf16 v[106:109], v[138:141], v[170:173], v[106:109]
	v_mfma_f32_16x16x32_bf16 v[106:109], v[142:145], v[174:177], v[106:109]
	v_mfma_f32_16x16x32_bf16 v[110:113], v[134:137], v[174:177], v[110:113]
	v_mfma_f32_16x16x32_bf16 v[110:113], v[130:133], v[170:173], v[110:113]
	v_mfma_f32_16x16x32_bf16 v[94:97], v[130:133], v[178:181], v[94:97]
	v_mfma_f32_16x16x32_bf16 v[94:97], v[134:137], v[182:185], v[94:97]
	v_mfma_f32_16x16x32_bf16 v[90:93], v[142:145], v[182:185], v[90:93]
	v_mfma_f32_16x16x32_bf16 v[90:93], v[138:141], v[178:181], v[90:93]
	v_mfma_f32_16x16x32_bf16 v[74:77], v[138:141], v[186:189], v[74:77]
	v_mfma_f32_16x16x32_bf16 v[74:77], v[142:145], v[190:193], v[74:77]
	v_mfma_f32_16x16x32_bf16 v[78:81], v[134:137], v[190:193], v[78:81]
	v_mfma_f32_16x16x32_bf16 v[78:81], v[130:133], v[186:189], v[78:81]
	s_setprio 0
	s_setprio 1
	v_mfma_f32_16x16x32_bf16 v[118:121], v[146:149], v[162:165], v[118:121]
	v_mfma_f32_16x16x32_bf16 v[118:121], v[150:153], v[166:169], v[118:121]
	v_mfma_f32_16x16x32_bf16 v[114:117], v[158:161], v[166:169], v[114:117]
	v_mfma_f32_16x16x32_bf16 v[114:117], v[154:157], v[162:165], v[114:117]
	v_mfma_f32_16x16x32_bf16 v[98:101], v[154:157], v[170:173], v[98:101]
	v_mfma_f32_16x16x32_bf16 v[98:101], v[158:161], v[174:177], v[98:101]
	v_mfma_f32_16x16x32_bf16 v[102:105], v[150:153], v[174:177], v[102:105]
	v_mfma_f32_16x16x32_bf16 v[102:105], v[146:149], v[170:173], v[102:105]
	v_mfma_f32_16x16x32_bf16 v[86:89], v[146:149], v[178:181], v[86:89]
	v_mfma_f32_16x16x32_bf16 v[86:89], v[150:153], v[182:185], v[86:89]
	v_mfma_f32_16x16x32_bf16 v[82:85], v[158:161], v[182:185], v[82:85]
	v_mfma_f32_16x16x32_bf16 v[82:85], v[154:157], v[178:181], v[82:85]
	v_mfma_f32_16x16x32_bf16 v[66:69], v[154:157], v[186:189], v[66:69]
	v_mfma_f32_16x16x32_bf16 v[66:69], v[158:161], v[190:193], v[66:69]
	v_mfma_f32_16x16x32_bf16 v[70:73], v[150:153], v[190:193], v[70:73]
	v_mfma_f32_16x16x32_bf16 v[70:73], v[146:149], v[186:189], v[70:73]
	s_setprio 0
	s_barrier
	s_add_u32 s30, s8, 0xffff8000
	s_addc_u32 s31, s9, -1
	s_add_i32 s44, s44, s41
	s_mov_b32 m0, s44
	ds_read_b128 v[162:165], v231 offset:49152
	ds_read_b128 v[166:169], v231 offset:50176
	ds_read_b128 v[170:173], v231 offset:51200
	ds_read_b128 v[174:177], v231 offset:52224
	ds_read_b128 v[178:181], v231 offset:53248
	ds_read_b128 v[182:185], v231 offset:54272
	ds_read_b128 v[186:189], v231 offset:55296
	ds_read_b128 v[190:193], v231 offset:56320
	global_load_lds_dwordx4 v196, s[30:31]
	s_add_i32 m0, s44, 0x2000
	s_add_u32 s8, s8, 0xffffc000
	v_lshl_add_u64 v[202:203], s[30:31], 0, v[200:201]
	s_addc_u32 s9, s9, -1
	s_add_i32 s30, s65, s41
	global_load_lds_dwordx4 v[202:203], off
	s_mov_b32 m0, s30
	s_nop 0
	global_load_lds_dwordx4 v196, s[8:9]
	s_add_i32 m0, s30, 0x2000
	s_nop 0
	global_load_lds_dwordx4 v200, s[8:9]
	s_mov_b32 m0, s71
	s_nop 0
	global_load_lds_dwordx4 v194, s[34:35]
	v_lshl_add_u64 v[202:203], s[34:35], 0, v[198:199]
	s_mov_b32 m0, s80
	s_nop 0
	global_load_lds_dwordx4 v[202:203], off
	s_waitcnt vmcnt(8) lgkmcnt(0)
	s_barrier
	s_setprio 1
	v_mfma_f32_16x16x32_bf16 v[62:65], v[130:133], v[162:165], v[62:65]
	v_mfma_f32_16x16x32_bf16 v[62:65], v[134:137], v[166:169], v[62:65]
	v_mfma_f32_16x16x32_bf16 v[58:61], v[142:145], v[166:169], v[58:61]
	v_mfma_f32_16x16x32_bf16 v[58:61], v[138:141], v[162:165], v[58:61]
	v_mfma_f32_16x16x32_bf16 v[42:45], v[138:141], v[170:173], v[42:45]
	v_mfma_f32_16x16x32_bf16 v[42:45], v[142:145], v[174:177], v[42:45]
	v_mfma_f32_16x16x32_bf16 v[46:49], v[134:137], v[174:177], v[46:49]
	v_mfma_f32_16x16x32_bf16 v[46:49], v[130:133], v[170:173], v[46:49]
	v_mfma_f32_16x16x32_bf16 v[30:33], v[130:133], v[178:181], v[30:33]
	v_mfma_f32_16x16x32_bf16 v[30:33], v[134:137], v[182:185], v[30:33]
	v_mfma_f32_16x16x32_bf16 v[26:29], v[142:145], v[182:185], v[26:29]
	v_mfma_f32_16x16x32_bf16 v[26:29], v[138:141], v[178:181], v[26:29]
	v_mfma_f32_16x16x32_bf16 v[10:13], v[138:141], v[186:189], v[10:13]
	v_mfma_f32_16x16x32_bf16 v[10:13], v[142:145], v[190:193], v[10:13]
	v_mfma_f32_16x16x32_bf16 v[14:17], v[134:137], v[190:193], v[14:17]
	v_mfma_f32_16x16x32_bf16 v[14:17], v[130:133], v[186:189], v[14:17]
	s_setprio 0
	s_setprio 1
	v_mfma_f32_16x16x32_bf16 v[54:57], v[146:149], v[162:165], v[54:57]
	v_mfma_f32_16x16x32_bf16 v[54:57], v[150:153], v[166:169], v[54:57]
	v_mfma_f32_16x16x32_bf16 v[50:53], v[158:161], v[166:169], v[50:53]
	v_mfma_f32_16x16x32_bf16 v[50:53], v[154:157], v[162:165], v[50:53]
	v_mfma_f32_16x16x32_bf16 v[34:37], v[154:157], v[170:173], v[34:37]
	v_mfma_f32_16x16x32_bf16 v[34:37], v[158:161], v[174:177], v[34:37]
	v_mfma_f32_16x16x32_bf16 v[38:41], v[150:153], v[174:177], v[38:41]
	v_mfma_f32_16x16x32_bf16 v[38:41], v[146:149], v[170:173], v[38:41]
	v_mfma_f32_16x16x32_bf16 v[22:25], v[146:149], v[178:181], v[22:25]
	v_mfma_f32_16x16x32_bf16 v[22:25], v[150:153], v[182:185], v[22:25]
	v_mfma_f32_16x16x32_bf16 v[18:21], v[158:161], v[182:185], v[18:21]
	v_mfma_f32_16x16x32_bf16 v[18:21], v[154:157], v[178:181], v[18:21]
	v_mfma_f32_16x16x32_bf16 v[2:5], v[154:157], v[186:189], v[2:5]
	v_mfma_f32_16x16x32_bf16 v[2:5], v[158:161], v[190:193], v[2:5]
	v_mfma_f32_16x16x32_bf16 v[6:9], v[150:153], v[190:193], v[6:9]
	v_mfma_f32_16x16x32_bf16 v[6:9], v[146:149], v[186:189], v[6:9]
	s_setprio 0
	s_barrier
	s_cmpk_gt_u32 s56, 0x55
	s_mov_b32 s56, s57
	s_cbranch_scc1 .LBB0_1449
